# k37: nt hint also on scan loader LDS-DMA, final-output stores, and the once-read conversion/transposition loads of P0 and the P3 GEMM half
# baseline (speedup 1.0000x reference)
.LBB0_10:
	s_cmpk_gt_i32 s3, 0x7ff
	s_mov_b64 s[0:1], -1
	s_cbranch_scc0 .LBB0_44
	s_cmpk_gt_u32 s3, 0x81f
	s_cbranch_scc0 .LBB0_41
	s_cmpk_gt_u32 s3, 0x83f
	s_cbranch_scc0 .LBB0_38
	s_cmpk_gt_u32 s3, 0x85f
	s_cbranch_scc0 .LBB0_35
	s_cmpk_gt_u32 s3, 0x87f
	s_cbranch_scc0 .LBB0_32
	s_cmpk_gt_u32 s3, 0x89f
	s_cbranch_scc0 .LBB0_29
	s_cmpk_gt_u32 s3, 0x8bf
	s_cbranch_scc0 .LBB0_26
	s_cmpk_gt_u32 s3, 0xabf
	s_cbranch_scc0 .LBB0_23
	s_and_b32 s14, s21, 0x3e0
	s_cmpk_gt_u32 s3, 0xb3f
	v_or_b32_e32 v115, s14, v79
	v_or_b32_e32 v114, s14, v108
	v_or_b32_e32 v113, s14, v109
	v_or_b32_e32 v112, s14, v110
	s_cbranch_scc0 .LBB0_20
	s_and_b32 s0, s19, 0x1ffc0
	s_lshl_b32 s10, s14, 2
	v_or_b32_e32 v116, s0, v3
	v_lshl_add_u64 v[100:101], v[6:7], 0, s[10:11]
	v_lshlrev_b32_e32 v116, 12, v116
	v_mov_b32_e32 v117, v5
	v_lshl_add_u64 v[116:117], v[100:101], 0, v[116:117]
	global_load_dword v125, v[116:117], off nt
	v_or_b32_e32 v116, s0, v39
	v_lshlrev_b32_e32 v116, 12, v116
	v_mov_b32_e32 v117, v5
	v_lshl_add_u64 v[116:117], v[100:101], 0, v[116:117]
	global_load_dword v128, v[116:117], off nt
	v_mov_b32_e32 v117, v5
	v_or_b32_e32 v116, s0, v41
	v_lshlrev_b32_e32 v116, 12, v116
	v_lshl_add_u64 v[116:117], v[100:101], 0, v[116:117]
	global_load_dword v130, v[116:117], off nt
	v_or_b32_e32 v116, s0, v43
	v_lshlrev_b32_e32 v116, 12, v116
	v_mov_b32_e32 v117, v5
	v_lshl_add_u64 v[116:117], v[100:101], 0, v[116:117]
	global_load_dword v131, v[116:117], off nt
	v_mov_b32_e32 v117, v5
	v_or_b32_e32 v116, s0, v45
	v_lshlrev_b32_e32 v116, 12, v116
	v_lshl_add_u64 v[116:117], v[100:101], 0, v[116:117]
	global_load_dword v132, v[116:117], off nt
	v_or_b32_e32 v116, s0, v47
	v_lshlrev_b32_e32 v116, 12, v116
	v_mov_b32_e32 v117, v5
	v_lshl_add_u64 v[116:117], v[100:101], 0, v[116:117]
	global_load_dword v133, v[116:117], off nt
	v_or_b32_e32 v116, s0, v49
	v_lshlrev_b32_e32 v116, 12, v116
	v_mov_b32_e32 v117, v5
	v_lshl_add_u64 v[116:117], v[100:101], 0, v[116:117]
	global_load_dword v134, v[116:117], off nt
	v_or_b32_e32 v116, s0, v53
	v_lshlrev_b32_e32 v116, 12, v116
	v_mov_b32_e32 v117, v5
	v_lshl_add_u64 v[116:117], v[100:101], 0, v[116:117]
	global_load_dword v135, v[116:117], off nt
	v_mov_b32_e32 v117, v5
	v_or_b32_e32 v116, s0, v55
	v_lshlrev_b32_e32 v116, 12, v116
	v_lshl_add_u64 v[116:117], v[100:101], 0, v[116:117]
	global_load_dword v136, v[116:117], off nt
	v_or_b32_e32 v116, s0, v57
	v_lshlrev_b32_e32 v116, 12, v116
	v_mov_b32_e32 v117, v5
	v_lshl_add_u64 v[116:117], v[100:101], 0, v[116:117]
	global_load_dword v137, v[116:117], off nt
	v_mov_b32_e32 v117, v5
	v_or_b32_e32 v116, s0, v59
	v_lshlrev_b32_e32 v116, 12, v116
	v_lshl_add_u64 v[116:117], v[100:101], 0, v[116:117]
	global_load_dword v138, v[116:117], off nt
	v_or_b32_e32 v116, s0, v61
	v_lshlrev_b32_e32 v116, 12, v116
	v_mov_b32_e32 v117, v5
	v_lshl_add_u64 v[116:117], v[100:101], 0, v[116:117]
	global_load_dword v139, v[116:117], off nt
	v_or_b32_e32 v116, s0, v63
	v_lshlrev_b32_e32 v116, 12, v116
	v_mov_b32_e32 v117, v5
	v_lshl_add_u64 v[116:117], v[100:101], 0, v[116:117]
	global_load_dword v140, v[116:117], off nt
	v_or_b32_e32 v116, s0, v67
	v_lshlrev_b32_e32 v116, 12, v116
	v_mov_b32_e32 v117, v5
	v_lshl_add_u64 v[116:117], v[100:101], 0, v[116:117]
	global_load_dword v141, v[116:117], off nt
	v_mov_b32_e32 v117, v5
	v_or_b32_e32 v116, s0, v69
	v_lshlrev_b32_e32 v116, 12, v116
	v_lshl_add_u64 v[116:117], v[100:101], 0, v[116:117]
	global_load_dword v142, v[116:117], off nt
	v_or_b32_e32 v116, s0, v71
	v_lshlrev_b32_e32 v116, 12, v116
	v_mov_b32_e32 v117, v5
	v_lshl_add_u64 v[116:117], v[100:101], 0, v[116:117]
	global_load_dword v143, v[116:117], off nt
	v_mov_b32_e32 v117, v5
	v_or_b32_e32 v116, s0, v73
	v_lshlrev_b32_e32 v116, 12, v116
	v_lshl_add_u64 v[116:117], v[100:101], 0, v[116:117]
	global_load_dword v144, v[116:117], off nt
	v_or_b32_e32 v116, s0, v83
	v_lshlrev_b32_e32 v116, 12, v116
	v_mov_b32_e32 v117, v5
	v_lshl_add_u64 v[116:117], v[100:101], 0, v[116:117]
	global_load_dword v145, v[116:117], off nt
	v_or_b32_e32 v116, s0, v85
	v_lshlrev_b32_e32 v116, 12, v116
	v_mov_b32_e32 v117, v5
	v_lshl_add_u64 v[116:117], v[100:101], 0, v[116:117]
	global_load_dword v146, v[116:117], off nt
	v_or_b32_e32 v116, s0, v87
	v_lshlrev_b32_e32 v116, 12, v116
	v_mov_b32_e32 v117, v5
	v_lshl_add_u64 v[116:117], v[100:101], 0, v[116:117]
	global_load_dword v148, v[116:117], off nt
	v_mov_b32_e32 v117, v5
	v_or_b32_e32 v116, s0, v89
	v_lshlrev_b32_e32 v116, 12, v116
	v_lshl_add_u64 v[116:117], v[100:101], 0, v[116:117]
	global_load_dword v150, v[116:117], off nt
	v_or_b32_e32 v116, s0, v91
	v_lshlrev_b32_e32 v116, 12, v116
	v_mov_b32_e32 v117, v5
	v_lshl_add_u64 v[116:117], v[100:101], 0, v[116:117]
	global_load_dword v151, v[116:117], off nt
	v_mov_b32_e32 v117, v5
	v_or_b32_e32 v116, s0, v93
	v_lshlrev_b32_e32 v116, 12, v116
	v_lshl_add_u64 v[116:117], v[100:101], 0, v[116:117]
	global_load_dword v152, v[116:117], off nt
	v_or_b32_e32 v116, s0, v95
	v_lshlrev_b32_e32 v116, 12, v116
	v_mov_b32_e32 v117, v5
	v_lshl_add_u64 v[116:117], v[100:101], 0, v[116:117]
	global_load_dword v153, v[116:117], off nt
	v_or_b32_e32 v116, s0, v97
	v_lshlrev_b32_e32 v116, 12, v116
	v_mov_b32_e32 v117, v5
	v_lshl_add_u64 v[116:117], v[100:101], 0, v[116:117]
	global_load_dword v154, v[116:117], off nt
	v_or_b32_e32 v116, s0, v99
	v_lshlrev_b32_e32 v116, 12, v116
	v_mov_b32_e32 v117, v5
	v_lshl_add_u64 v[116:117], v[100:101], 0, v[116:117]
	global_load_dword v155, v[116:117], off nt
	v_mov_b32_e32 v117, v5
	v_or_b32_e32 v116, s0, v102
	v_lshlrev_b32_e32 v116, 12, v116
	v_lshl_add_u64 v[116:117], v[100:101], 0, v[116:117]
	global_load_dword v156, v[116:117], off nt
	v_or_b32_e32 v116, s0, v103
	v_lshlrev_b32_e32 v116, 12, v116
	v_mov_b32_e32 v117, v5
	v_lshl_add_u64 v[116:117], v[100:101], 0, v[116:117]
	global_load_dword v157, v[116:117], off nt
	v_mov_b32_e32 v117, v5
	v_or_b32_e32 v116, s0, v104
	v_lshlrev_b32_e32 v116, 12, v116
	v_lshl_add_u64 v[116:117], v[100:101], 0, v[116:117]
	global_load_dword v158, v[116:117], off nt
	v_or_b32_e32 v116, s0, v105
	v_lshlrev_b32_e32 v116, 12, v116
	v_mov_b32_e32 v117, v5
	v_lshl_add_u64 v[116:117], v[100:101], 0, v[116:117]
	global_load_dword v159, v[116:117], off nt
	v_mov_b32_e32 v117, v5
	v_or_b32_e32 v116, s0, v106
	v_lshlrev_b32_e32 v116, 12, v116
	v_lshl_add_u64 v[116:117], v[100:101], 0, v[116:117]
	global_load_dword v160, v[116:117], off nt
	v_or_b32_e32 v116, s0, v107
	v_lshlrev_b32_e32 v116, 12, v116
	v_mov_b32_e32 v117, v5
	v_lshl_add_u64 v[100:101], v[100:101], 0, v[116:117]
	global_load_dword v161, v[100:101], off nt
	s_waitcnt vmcnt(0)
	v_add_u32_e32 v119, v19, v37
	s_lshl_b32 s10, s0, 1
	ds_write2_b32 v119, v125, v128 offset1:66
	ds_write2_b32 v119, v130, v131 offset0:132 offset1:198
	v_add_u32_e32 v117, 0x400, v119
	v_add_u32_e32 v119, v19, v51
	ds_write2_b32 v117, v132, v133 offset0:8 offset1:74
	ds_write2_b32 v119, v134, v135 offset1:66
	ds_write2_b32 v119, v136, v137 offset0:132 offset1:198
	v_add_u32_e32 v117, 0x400, v119
	v_add_u32_e32 v119, v19, v65
	ds_write2_b32 v117, v138, v139 offset0:8 offset1:74
	ds_write2_b32 v119, v140, v141 offset1:66
	ds_write2_b32 v119, v142, v143 offset0:132 offset1:198
	v_add_u32_e32 v117, 0x400, v119
	v_add_u32_e32 v119, v19, v75
	ds_write2_b32 v117, v144, v145 offset0:8 offset1:74
	ds_write2_b32 v119, v146, v148 offset1:66
	ds_write2_b32 v119, v150, v151 offset0:132 offset1:198
	v_add_u32_e32 v117, 0x400, v119
	v_add_u32_e32 v119, v19, v77
	ds_write2_b32 v117, v152, v153 offset0:8 offset1:74
	ds_write2_b32 v119, v154, v155 offset1:66
	ds_write2_b32 v119, v156, v157 offset0:132 offset1:198
	v_add_u32_e32 v119, 0x400, v119
	ds_write2_b32 v119, v158, v159 offset0:8 offset1:74
	s_mov_b64 s[0:1], 0
	ds_write2_b32 v119, v160, v161 offset0:140 offset1:206
	s_waitcnt lgkmcnt(0)
	ds_read2_b32 v[116:117], v81 offset1:33
	s_waitcnt lgkmcnt(0)
	v_cvt_pk_bf16_f32 v116, v116, v117
	ds_read2_b32 v[118:119], v81 offset0:66 offset1:99
	s_waitcnt lgkmcnt(0)
	v_cvt_pk_bf16_f32 v117, v118, v119
	ds_read2_b32 v[118:119], v81 offset0:132 offset1:165
	s_waitcnt lgkmcnt(0)
	v_cvt_pk_bf16_f32 v118, v118, v119
	ds_read2_b32 v[120:121], v81 offset0:198 offset1:231
	v_lshl_add_u64 v[100:101], v[8:9], 0, s[10:11]
	s_waitcnt lgkmcnt(0)
	v_cvt_pk_bf16_f32 v119, v120, v121
	v_lshlrev_b32_e32 v120, 11, v115
	v_mov_b32_e32 v121, v5
	v_lshl_add_u64 v[120:121], v[100:101], 0, v[120:121]
	global_store_dwordx4 v[120:121], v[116:119], off
	ds_read2_b32 v[116:117], v81 offset0:8 offset1:41
	s_waitcnt lgkmcnt(0)
	v_cvt_pk_bf16_f32 v116, v116, v117
	ds_read2_b32 v[118:119], v81 offset0:74 offset1:107
	s_waitcnt lgkmcnt(0)
	v_cvt_pk_bf16_f32 v117, v118, v119
	ds_read2_b32 v[118:119], v81 offset0:140 offset1:173
	s_waitcnt lgkmcnt(0)
	v_cvt_pk_bf16_f32 v118, v118, v119
	ds_read2_b32 v[120:121], v81 offset0:206 offset1:239
	s_waitcnt lgkmcnt(0)
	v_cvt_pk_bf16_f32 v119, v120, v121
	v_lshlrev_b32_e32 v120, 11, v114
	v_mov_b32_e32 v121, v5
	v_lshl_add_u64 v[120:121], v[100:101], 0, v[120:121]
	global_store_dwordx4 v[120:121], v[116:119], off
	ds_read2_b32 v[116:117], v81 offset0:16 offset1:49
	s_waitcnt lgkmcnt(0)
	v_cvt_pk_bf16_f32 v116, v116, v117
	ds_read2_b32 v[118:119], v81 offset0:82 offset1:115
	s_waitcnt lgkmcnt(0)
	v_cvt_pk_bf16_f32 v117, v118, v119
	ds_read2_b32 v[118:119], v81 offset0:148 offset1:181
	s_waitcnt lgkmcnt(0)
	v_cvt_pk_bf16_f32 v118, v118, v119
	ds_read2_b32 v[120:121], v81 offset0:214 offset1:247
	s_waitcnt lgkmcnt(0)
	v_cvt_pk_bf16_f32 v119, v120, v121
	v_lshlrev_b32_e32 v120, 11, v113
	v_mov_b32_e32 v121, v5
	v_lshl_add_u64 v[120:121], v[100:101], 0, v[120:121]
	global_store_dwordx4 v[120:121], v[116:119], off
	ds_read2_b32 v[116:117], v81 offset0:24 offset1:57
	s_waitcnt lgkmcnt(0)
	v_cvt_pk_bf16_f32 v116, v116, v117
	ds_read2_b32 v[118:119], v81 offset0:90 offset1:123
	s_waitcnt lgkmcnt(0)
	v_cvt_pk_bf16_f32 v117, v118, v119
	ds_read2_b32 v[118:119], v81 offset0:156 offset1:189
	s_waitcnt lgkmcnt(0)
	v_cvt_pk_bf16_f32 v118, v118, v119
	ds_read2_b32 v[120:121], v81 offset0:222 offset1:255
	s_waitcnt lgkmcnt(0)
	v_cvt_pk_bf16_f32 v119, v120, v121
	v_lshlrev_b32_e32 v120, 11, v112
	v_mov_b32_e32 v121, v5
	v_lshl_add_u64 v[100:101], v[100:101], 0, v[120:121]
	global_store_dwordx4 v[100:101], v[116:119], off
	s_waitcnt lgkmcnt(0)
.LBB0_20:
	s_andn2_b64 vcc, exec, s[0:1]
	s_cbranch_vccnz .LBB0_22
	s_add_i32 s0, s19, 0xfffe1700
	s_and_b32 s0, s0, 0x1c0
	s_lshl_b32 s10, s14, 2
	v_or_b32_e32 v116, s0, v3
	v_lshl_add_u64 v[100:101], v[10:11], 0, s[10:11]
	v_lshlrev_b32_e32 v116, 12, v116
	v_mov_b32_e32 v117, v5
	v_lshl_add_u64 v[116:117], v[100:101], 0, v[116:117]
	global_load_dword v125, v[116:117], off nt
	v_or_b32_e32 v116, s0, v39
	v_lshlrev_b32_e32 v116, 12, v116
	v_mov_b32_e32 v117, v5
	v_lshl_add_u64 v[116:117], v[100:101], 0, v[116:117]
	global_load_dword v128, v[116:117], off nt
	v_mov_b32_e32 v117, v5
	v_or_b32_e32 v116, s0, v41
	v_lshlrev_b32_e32 v116, 12, v116
	v_lshl_add_u64 v[116:117], v[100:101], 0, v[116:117]
	global_load_dword v130, v[116:117], off nt
	v_or_b32_e32 v116, s0, v43
	v_lshlrev_b32_e32 v116, 12, v116
	v_mov_b32_e32 v117, v5
	v_lshl_add_u64 v[116:117], v[100:101], 0, v[116:117]
	global_load_dword v131, v[116:117], off nt
	v_mov_b32_e32 v117, v5
	v_or_b32_e32 v116, s0, v45
	v_lshlrev_b32_e32 v116, 12, v116
	v_lshl_add_u64 v[116:117], v[100:101], 0, v[116:117]
	global_load_dword v132, v[116:117], off nt
	v_or_b32_e32 v116, s0, v47
	v_lshlrev_b32_e32 v116, 12, v116
	v_mov_b32_e32 v117, v5
	v_lshl_add_u64 v[116:117], v[100:101], 0, v[116:117]
	global_load_dword v133, v[116:117], off nt
	v_or_b32_e32 v116, s0, v49
	v_lshlrev_b32_e32 v116, 12, v116
	v_mov_b32_e32 v117, v5
	v_lshl_add_u64 v[116:117], v[100:101], 0, v[116:117]
	global_load_dword v134, v[116:117], off nt
	v_or_b32_e32 v116, s0, v53
	v_lshlrev_b32_e32 v116, 12, v116
	v_mov_b32_e32 v117, v5
	v_lshl_add_u64 v[116:117], v[100:101], 0, v[116:117]
	global_load_dword v135, v[116:117], off nt
	v_mov_b32_e32 v117, v5
	v_or_b32_e32 v116, s0, v55
	v_lshlrev_b32_e32 v116, 12, v116
	v_lshl_add_u64 v[116:117], v[100:101], 0, v[116:117]
	global_load_dword v136, v[116:117], off nt
	v_or_b32_e32 v116, s0, v57
	v_lshlrev_b32_e32 v116, 12, v116
	v_mov_b32_e32 v117, v5
	v_lshl_add_u64 v[116:117], v[100:101], 0, v[116:117]
	global_load_dword v137, v[116:117], off nt
	v_mov_b32_e32 v117, v5
	v_or_b32_e32 v116, s0, v59
	v_lshlrev_b32_e32 v116, 12, v116
	v_lshl_add_u64 v[116:117], v[100:101], 0, v[116:117]
	global_load_dword v138, v[116:117], off nt
	v_or_b32_e32 v116, s0, v61
	v_lshlrev_b32_e32 v116, 12, v116
	v_mov_b32_e32 v117, v5
	v_lshl_add_u64 v[116:117], v[100:101], 0, v[116:117]
	global_load_dword v139, v[116:117], off nt
	v_or_b32_e32 v116, s0, v63
	v_lshlrev_b32_e32 v116, 12, v116
	v_mov_b32_e32 v117, v5
	v_lshl_add_u64 v[116:117], v[100:101], 0, v[116:117]
	global_load_dword v140, v[116:117], off nt
	v_or_b32_e32 v116, s0, v67
	v_lshlrev_b32_e32 v116, 12, v116
	v_mov_b32_e32 v117, v5
	v_lshl_add_u64 v[116:117], v[100:101], 0, v[116:117]
	global_load_dword v141, v[116:117], off nt
	v_mov_b32_e32 v117, v5
	v_or_b32_e32 v116, s0, v69
	v_lshlrev_b32_e32 v116, 12, v116
	v_lshl_add_u64 v[116:117], v[100:101], 0, v[116:117]
	global_load_dword v142, v[116:117], off nt
	v_or_b32_e32 v116, s0, v71
	v_lshlrev_b32_e32 v116, 12, v116
	v_mov_b32_e32 v117, v5
	v_lshl_add_u64 v[116:117], v[100:101], 0, v[116:117]
	global_load_dword v143, v[116:117], off nt
	v_mov_b32_e32 v117, v5
	v_or_b32_e32 v116, s0, v73
	v_lshlrev_b32_e32 v116, 12, v116
	v_lshl_add_u64 v[116:117], v[100:101], 0, v[116:117]
	global_load_dword v144, v[116:117], off nt
	v_or_b32_e32 v116, s0, v83
	v_lshlrev_b32_e32 v116, 12, v116
	v_mov_b32_e32 v117, v5
	v_lshl_add_u64 v[116:117], v[100:101], 0, v[116:117]
	global_load_dword v145, v[116:117], off nt
	v_or_b32_e32 v116, s0, v85
	v_lshlrev_b32_e32 v116, 12, v116
	v_mov_b32_e32 v117, v5
	v_lshl_add_u64 v[116:117], v[100:101], 0, v[116:117]
	global_load_dword v146, v[116:117], off nt
	v_or_b32_e32 v116, s0, v87
	v_lshlrev_b32_e32 v116, 12, v116
	v_mov_b32_e32 v117, v5
	v_lshl_add_u64 v[116:117], v[100:101], 0, v[116:117]
	global_load_dword v148, v[116:117], off nt
	v_mov_b32_e32 v117, v5
	v_or_b32_e32 v116, s0, v89
	v_lshlrev_b32_e32 v116, 12, v116
	v_lshl_add_u64 v[116:117], v[100:101], 0, v[116:117]
	global_load_dword v150, v[116:117], off nt
	v_or_b32_e32 v116, s0, v91
	v_lshlrev_b32_e32 v116, 12, v116
	v_mov_b32_e32 v117, v5
	v_lshl_add_u64 v[116:117], v[100:101], 0, v[116:117]
	global_load_dword v151, v[116:117], off nt
	v_mov_b32_e32 v117, v5
	v_or_b32_e32 v116, s0, v93
	v_lshlrev_b32_e32 v116, 12, v116
	v_lshl_add_u64 v[116:117], v[100:101], 0, v[116:117]
	global_load_dword v152, v[116:117], off nt
	v_or_b32_e32 v116, s0, v95
	v_lshlrev_b32_e32 v116, 12, v116
	v_mov_b32_e32 v117, v5
	v_lshl_add_u64 v[116:117], v[100:101], 0, v[116:117]
	global_load_dword v153, v[116:117], off nt
	v_or_b32_e32 v116, s0, v97
	v_lshlrev_b32_e32 v116, 12, v116
	v_mov_b32_e32 v117, v5
	v_lshl_add_u64 v[116:117], v[100:101], 0, v[116:117]
	global_load_dword v154, v[116:117], off nt
	v_or_b32_e32 v116, s0, v99
	v_lshlrev_b32_e32 v116, 12, v116
	v_mov_b32_e32 v117, v5
	v_lshl_add_u64 v[116:117], v[100:101], 0, v[116:117]
	global_load_dword v155, v[116:117], off nt
	v_mov_b32_e32 v117, v5
	v_or_b32_e32 v116, s0, v102
	v_lshlrev_b32_e32 v116, 12, v116
	v_lshl_add_u64 v[116:117], v[100:101], 0, v[116:117]
	global_load_dword v156, v[116:117], off nt
	v_or_b32_e32 v116, s0, v103
	v_lshlrev_b32_e32 v116, 12, v116
	v_mov_b32_e32 v117, v5
	v_lshl_add_u64 v[116:117], v[100:101], 0, v[116:117]
	global_load_dword v157, v[116:117], off nt
	v_mov_b32_e32 v117, v5
	v_or_b32_e32 v116, s0, v104
	v_lshlrev_b32_e32 v116, 12, v116
	v_lshl_add_u64 v[116:117], v[100:101], 0, v[116:117]
	global_load_dword v158, v[116:117], off nt
	v_or_b32_e32 v116, s0, v105
	v_lshlrev_b32_e32 v116, 12, v116
	v_mov_b32_e32 v117, v5
	v_lshl_add_u64 v[116:117], v[100:101], 0, v[116:117]
	global_load_dword v159, v[116:117], off nt
	v_mov_b32_e32 v117, v5
	v_or_b32_e32 v116, s0, v106
	v_lshlrev_b32_e32 v116, 12, v116
	v_lshl_add_u64 v[116:117], v[100:101], 0, v[116:117]
	global_load_dword v160, v[116:117], off nt
	v_or_b32_e32 v116, s0, v107
	v_lshlrev_b32_e32 v116, 12, v116
	v_mov_b32_e32 v117, v5
	v_lshl_add_u64 v[100:101], v[100:101], 0, v[116:117]
	global_load_dword v161, v[100:101], off nt
	s_waitcnt vmcnt(0)
	v_add_u32_e32 v119, v19, v37
	s_lshl_b32 s10, s0, 1
	v_lshlrev_b32_e32 v114, 9, v114
	v_lshlrev_b32_e32 v112, 9, v112
	ds_write2_b32 v119, v125, v128 offset1:66
	ds_write2_b32 v119, v130, v131 offset0:132 offset1:198
	v_add_u32_e32 v117, 0x400, v119
	v_add_u32_e32 v119, v19, v51
	ds_write2_b32 v117, v132, v133 offset0:8 offset1:74
	ds_write2_b32 v119, v134, v135 offset1:66
	ds_write2_b32 v119, v136, v137 offset0:132 offset1:198
	v_add_u32_e32 v117, 0x400, v119
	v_add_u32_e32 v119, v19, v65
	ds_write2_b32 v117, v138, v139 offset0:8 offset1:74
	ds_write2_b32 v119, v140, v141 offset1:66
	ds_write2_b32 v119, v142, v143 offset0:132 offset1:198
	v_add_u32_e32 v117, 0x400, v119
	v_add_u32_e32 v119, v19, v75
	ds_write2_b32 v117, v144, v145 offset0:8 offset1:74
	ds_write2_b32 v119, v146, v148 offset1:66
	ds_write2_b32 v119, v150, v151 offset0:132 offset1:198
	v_add_u32_e32 v117, 0x400, v119
	v_add_u32_e32 v119, v19, v77
	ds_write2_b32 v117, v152, v153 offset0:8 offset1:74
	ds_write2_b32 v119, v154, v155 offset1:66
	ds_write2_b32 v119, v156, v157 offset0:132 offset1:198
	v_add_u32_e32 v119, 0x400, v119
	ds_write2_b32 v119, v158, v159 offset0:8 offset1:74
	ds_write2_b32 v119, v160, v161 offset0:140 offset1:206
	s_waitcnt lgkmcnt(0)
	ds_read2_b32 v[116:117], v81 offset1:33
	s_waitcnt lgkmcnt(0)
	v_cvt_pk_bf16_f32 v116, v116, v117
	ds_read2_b32 v[118:119], v81 offset0:66 offset1:99
	s_waitcnt lgkmcnt(0)
	v_cvt_pk_bf16_f32 v117, v118, v119
	ds_read2_b32 v[118:119], v81 offset0:132 offset1:165
	s_waitcnt lgkmcnt(0)
	v_cvt_pk_bf16_f32 v118, v118, v119
	ds_read2_b32 v[120:121], v81 offset0:198 offset1:231
	v_lshl_add_u64 v[100:101], v[12:13], 0, s[10:11]
	s_waitcnt lgkmcnt(0)
	v_cvt_pk_bf16_f32 v119, v120, v121
	v_lshlrev_b32_e32 v120, 9, v115
	v_mov_b32_e32 v121, v5
	v_lshl_add_u64 v[120:121], v[100:101], 0, v[120:121]
	global_store_dwordx4 v[120:121], v[116:119], off
	ds_read2_b32 v[116:117], v81 offset0:8 offset1:41
	v_mov_b32_e32 v115, v5
	s_waitcnt lgkmcnt(0)
	v_cvt_pk_bf16_f32 v116, v116, v117
	ds_read2_b32 v[118:119], v81 offset0:74 offset1:107
	s_waitcnt lgkmcnt(0)
	v_cvt_pk_bf16_f32 v117, v118, v119
	ds_read2_b32 v[118:119], v81 offset0:140 offset1:173
	v_lshl_add_u64 v[114:115], v[100:101], 0, v[114:115]
	s_waitcnt lgkmcnt(0)
	v_cvt_pk_bf16_f32 v118, v118, v119
	ds_read2_b32 v[120:121], v81 offset0:206 offset1:239
	s_waitcnt lgkmcnt(0)
	v_cvt_pk_bf16_f32 v119, v120, v121
	global_store_dwordx4 v[114:115], v[116:119], off
	ds_read2_b32 v[114:115], v81 offset0:16 offset1:49
	s_waitcnt lgkmcnt(0)
	v_cvt_pk_bf16_f32 v114, v114, v115
	ds_read2_b32 v[116:117], v81 offset0:82 offset1:115
	s_waitcnt lgkmcnt(0)
	v_cvt_pk_bf16_f32 v115, v116, v117
	ds_read2_b32 v[116:117], v81 offset0:148 offset1:181
	s_waitcnt lgkmcnt(0)
	v_cvt_pk_bf16_f32 v116, v116, v117
	ds_read2_b32 v[118:119], v81 offset0:214 offset1:247
	s_waitcnt lgkmcnt(0)
	v_cvt_pk_bf16_f32 v117, v118, v119
	v_lshlrev_b32_e32 v118, 9, v113
	v_mov_b32_e32 v119, v5
	v_lshl_add_u64 v[118:119], v[100:101], 0, v[118:119]
	global_store_dwordx4 v[118:119], v[114:117], off
	ds_read2_b32 v[114:115], v81 offset0:24 offset1:57
	v_mov_b32_e32 v113, v5
	s_waitcnt lgkmcnt(0)
	v_cvt_pk_bf16_f32 v114, v114, v115
	ds_read2_b32 v[116:117], v81 offset0:90 offset1:123
	s_waitcnt lgkmcnt(0)
	v_cvt_pk_bf16_f32 v115, v116, v117
	ds_read2_b32 v[116:117], v81 offset0:156 offset1:189
	v_lshl_add_u64 v[100:101], v[100:101], 0, v[112:113]
	s_waitcnt lgkmcnt(0)
	v_cvt_pk_bf16_f32 v116, v116, v117
	ds_read2_b32 v[118:119], v81 offset0:222 offset1:255
	s_waitcnt lgkmcnt(0)
	v_cvt_pk_bf16_f32 v117, v118, v119
	global_store_dwordx4 v[100:101], v[114:117], off
	s_waitcnt lgkmcnt(0)

.LBB0_23:
	s_andn2_b64 vcc, exec, s[0:1]
	s_cbranch_vccnz .LBB0_25
	s_add_i32 s0, s19, 0x500
	s_and_b32 s1, s0, 0x1ffc0
	s_and_b32 s0, s21, 0x3e0
	s_lshl_b32 s10, s0, 2
	v_or_b32_e32 v112, s1, v3
	v_lshl_add_u64 v[100:101], v[14:15], 0, s[10:11]
	v_lshlrev_b32_e32 v112, 12, v112
	v_mov_b32_e32 v113, v5
	v_lshl_add_u64 v[112:113], v[100:101], 0, v[112:113]
	global_load_dword v125, v[112:113], off nt
	v_or_b32_e32 v112, s1, v39
	v_lshlrev_b32_e32 v112, 12, v112
	v_mov_b32_e32 v113, v5
	v_lshl_add_u64 v[112:113], v[100:101], 0, v[112:113]
	global_load_dword v128, v[112:113], off nt
	v_mov_b32_e32 v113, v5
	v_or_b32_e32 v112, s1, v41
	v_lshlrev_b32_e32 v112, 12, v112
	v_lshl_add_u64 v[112:113], v[100:101], 0, v[112:113]
	global_load_dword v130, v[112:113], off nt
	v_or_b32_e32 v112, s1, v43
	v_lshlrev_b32_e32 v112, 12, v112
	v_mov_b32_e32 v113, v5
	v_lshl_add_u64 v[112:113], v[100:101], 0, v[112:113]
	global_load_dword v131, v[112:113], off nt
	v_mov_b32_e32 v113, v5
	v_or_b32_e32 v112, s1, v45
	v_lshlrev_b32_e32 v112, 12, v112
	v_lshl_add_u64 v[112:113], v[100:101], 0, v[112:113]
	global_load_dword v132, v[112:113], off nt
	v_or_b32_e32 v112, s1, v47
	v_lshlrev_b32_e32 v112, 12, v112
	v_mov_b32_e32 v113, v5
	v_lshl_add_u64 v[112:113], v[100:101], 0, v[112:113]
	global_load_dword v133, v[112:113], off nt
	v_or_b32_e32 v112, s1, v49
	v_lshlrev_b32_e32 v112, 12, v112
	v_mov_b32_e32 v113, v5
	v_lshl_add_u64 v[112:113], v[100:101], 0, v[112:113]
	global_load_dword v134, v[112:113], off nt
	v_or_b32_e32 v112, s1, v53
	v_lshlrev_b32_e32 v112, 12, v112
	v_mov_b32_e32 v113, v5
	v_lshl_add_u64 v[112:113], v[100:101], 0, v[112:113]
	global_load_dword v135, v[112:113], off nt
	v_mov_b32_e32 v113, v5
	v_or_b32_e32 v112, s1, v55
	v_lshlrev_b32_e32 v112, 12, v112
	v_lshl_add_u64 v[112:113], v[100:101], 0, v[112:113]
	global_load_dword v136, v[112:113], off nt
	v_or_b32_e32 v112, s1, v57
	v_lshlrev_b32_e32 v112, 12, v112
	v_mov_b32_e32 v113, v5
	v_lshl_add_u64 v[112:113], v[100:101], 0, v[112:113]
	global_load_dword v137, v[112:113], off nt
	v_mov_b32_e32 v113, v5
	v_or_b32_e32 v112, s1, v59
	v_lshlrev_b32_e32 v112, 12, v112
	v_lshl_add_u64 v[112:113], v[100:101], 0, v[112:113]
	global_load_dword v138, v[112:113], off nt
	v_or_b32_e32 v112, s1, v61
	v_lshlrev_b32_e32 v112, 12, v112
	v_mov_b32_e32 v113, v5
	v_lshl_add_u64 v[112:113], v[100:101], 0, v[112:113]
	global_load_dword v139, v[112:113], off nt
	v_or_b32_e32 v112, s1, v63
	v_lshlrev_b32_e32 v112, 12, v112
	v_mov_b32_e32 v113, v5
	v_lshl_add_u64 v[112:113], v[100:101], 0, v[112:113]
	global_load_dword v140, v[112:113], off nt
	v_or_b32_e32 v112, s1, v67
	v_lshlrev_b32_e32 v112, 12, v112
	v_mov_b32_e32 v113, v5
	v_lshl_add_u64 v[112:113], v[100:101], 0, v[112:113]
	global_load_dword v141, v[112:113], off nt
	v_mov_b32_e32 v113, v5
	v_or_b32_e32 v112, s1, v69
	v_lshlrev_b32_e32 v112, 12, v112
	v_lshl_add_u64 v[112:113], v[100:101], 0, v[112:113]
	global_load_dword v142, v[112:113], off nt
	v_or_b32_e32 v112, s1, v71
	v_lshlrev_b32_e32 v112, 12, v112
	v_mov_b32_e32 v113, v5
	v_lshl_add_u64 v[112:113], v[100:101], 0, v[112:113]
	global_load_dword v143, v[112:113], off nt
	v_mov_b32_e32 v113, v5
	v_or_b32_e32 v112, s1, v73
	v_lshlrev_b32_e32 v112, 12, v112
	v_lshl_add_u64 v[112:113], v[100:101], 0, v[112:113]
	global_load_dword v144, v[112:113], off nt
	v_or_b32_e32 v112, s1, v83
	v_lshlrev_b32_e32 v112, 12, v112
	v_mov_b32_e32 v113, v5
	v_lshl_add_u64 v[112:113], v[100:101], 0, v[112:113]
	global_load_dword v145, v[112:113], off nt
	v_or_b32_e32 v112, s1, v85
	v_lshlrev_b32_e32 v112, 12, v112
	v_mov_b32_e32 v113, v5
	v_lshl_add_u64 v[112:113], v[100:101], 0, v[112:113]
	global_load_dword v146, v[112:113], off nt
	v_or_b32_e32 v112, s1, v87
	v_lshlrev_b32_e32 v112, 12, v112
	v_mov_b32_e32 v113, v5
	v_lshl_add_u64 v[112:113], v[100:101], 0, v[112:113]
	global_load_dword v148, v[112:113], off nt
	v_mov_b32_e32 v113, v5
	v_or_b32_e32 v112, s1, v89
	v_lshlrev_b32_e32 v112, 12, v112
	v_lshl_add_u64 v[112:113], v[100:101], 0, v[112:113]
	global_load_dword v150, v[112:113], off nt
	v_or_b32_e32 v112, s1, v91
	v_lshlrev_b32_e32 v112, 12, v112
	v_mov_b32_e32 v113, v5
	v_lshl_add_u64 v[112:113], v[100:101], 0, v[112:113]
	global_load_dword v151, v[112:113], off nt
	v_mov_b32_e32 v113, v5
	v_or_b32_e32 v112, s1, v93
	v_lshlrev_b32_e32 v112, 12, v112
	v_lshl_add_u64 v[112:113], v[100:101], 0, v[112:113]
	global_load_dword v152, v[112:113], off nt
	v_or_b32_e32 v112, s1, v95
	v_lshlrev_b32_e32 v112, 12, v112
	v_mov_b32_e32 v113, v5
	v_lshl_add_u64 v[112:113], v[100:101], 0, v[112:113]
	global_load_dword v153, v[112:113], off nt
	v_or_b32_e32 v112, s1, v97
	v_lshlrev_b32_e32 v112, 12, v112
	v_mov_b32_e32 v113, v5
	v_lshl_add_u64 v[112:113], v[100:101], 0, v[112:113]
	global_load_dword v154, v[112:113], off nt
	v_or_b32_e32 v112, s1, v99
	v_lshlrev_b32_e32 v112, 12, v112
	v_mov_b32_e32 v113, v5
	v_lshl_add_u64 v[112:113], v[100:101], 0, v[112:113]
	global_load_dword v155, v[112:113], off nt
	v_mov_b32_e32 v113, v5
	v_or_b32_e32 v112, s1, v102
	v_lshlrev_b32_e32 v112, 12, v112
	v_lshl_add_u64 v[112:113], v[100:101], 0, v[112:113]
	global_load_dword v156, v[112:113], off nt
	v_or_b32_e32 v112, s1, v103
	v_lshlrev_b32_e32 v112, 12, v112
	v_mov_b32_e32 v113, v5
	v_lshl_add_u64 v[112:113], v[100:101], 0, v[112:113]
	global_load_dword v157, v[112:113], off nt
	v_mov_b32_e32 v113, v5
	v_or_b32_e32 v112, s1, v104
	v_lshlrev_b32_e32 v112, 12, v112
	v_lshl_add_u64 v[112:113], v[100:101], 0, v[112:113]
	global_load_dword v158, v[112:113], off nt
	v_or_b32_e32 v112, s1, v105
	v_lshlrev_b32_e32 v112, 12, v112
	v_mov_b32_e32 v113, v5
	v_lshl_add_u64 v[112:113], v[100:101], 0, v[112:113]
	global_load_dword v159, v[112:113], off nt
	v_mov_b32_e32 v113, v5
	v_or_b32_e32 v112, s1, v106
	v_lshlrev_b32_e32 v112, 12, v112
	v_lshl_add_u64 v[112:113], v[100:101], 0, v[112:113]
	global_load_dword v160, v[112:113], off nt
	v_or_b32_e32 v112, s1, v107
	v_lshlrev_b32_e32 v112, 12, v112
	v_mov_b32_e32 v113, v5
	v_lshl_add_u64 v[100:101], v[100:101], 0, v[112:113]
	global_load_dword v161, v[100:101], off nt
	s_waitcnt vmcnt(0)
	v_add_u32_e32 v115, v19, v37
	s_lshl_b32 s10, s1, 1
	ds_write2_b32 v115, v125, v128 offset1:66
	ds_write2_b32 v115, v130, v131 offset0:132 offset1:198
	v_add_u32_e32 v113, 0x400, v115
	v_add_u32_e32 v115, v19, v51
	ds_write2_b32 v113, v132, v133 offset0:8 offset1:74
	ds_write2_b32 v115, v134, v135 offset1:66
	ds_write2_b32 v115, v136, v137 offset0:132 offset1:198
	v_add_u32_e32 v113, 0x400, v115
	v_add_u32_e32 v115, v19, v65
	ds_write2_b32 v113, v138, v139 offset0:8 offset1:74
	ds_write2_b32 v115, v140, v141 offset1:66
	ds_write2_b32 v115, v142, v143 offset0:132 offset1:198
	v_add_u32_e32 v113, 0x400, v115
	v_add_u32_e32 v115, v19, v75
	ds_write2_b32 v113, v144, v145 offset0:8 offset1:74
	ds_write2_b32 v115, v146, v148 offset1:66
	ds_write2_b32 v115, v150, v151 offset0:132 offset1:198
	v_add_u32_e32 v113, 0x400, v115
	v_add_u32_e32 v115, v19, v77
	ds_write2_b32 v113, v152, v153 offset0:8 offset1:74
	ds_write2_b32 v115, v154, v155 offset1:66
	ds_write2_b32 v115, v156, v157 offset0:132 offset1:198
	v_add_u32_e32 v115, 0x400, v115
	ds_write2_b32 v115, v158, v159 offset0:8 offset1:74
	ds_write2_b32 v115, v160, v161 offset0:140 offset1:206
	s_waitcnt lgkmcnt(0)
	ds_read2_b32 v[112:113], v81 offset1:33
	s_waitcnt lgkmcnt(0)
	v_cvt_pk_bf16_f32 v112, v112, v113
	ds_read2_b32 v[114:115], v81 offset0:66 offset1:99
	s_waitcnt lgkmcnt(0)
	v_cvt_pk_bf16_f32 v113, v114, v115
	ds_read2_b32 v[114:115], v81 offset0:132 offset1:165
	s_waitcnt lgkmcnt(0)
	v_cvt_pk_bf16_f32 v114, v114, v115
	ds_read2_b32 v[116:117], v81 offset0:198 offset1:231
	s_waitcnt lgkmcnt(0)
	v_cvt_pk_bf16_f32 v115, v116, v117
	v_or_b32_e32 v116, s0, v79
	v_lshl_add_u64 v[100:101], v[16:17], 0, s[10:11]
	v_lshlrev_b32_e32 v116, 11, v116
	v_mov_b32_e32 v117, v5
	v_lshl_add_u64 v[116:117], v[100:101], 0, v[116:117]
	global_store_dwordx4 v[116:117], v[112:115], off
	ds_read2_b32 v[112:113], v81 offset0:8 offset1:41
	s_waitcnt lgkmcnt(0)
	v_cvt_pk_bf16_f32 v112, v112, v113
	ds_read2_b32 v[114:115], v81 offset0:74 offset1:107
	s_waitcnt lgkmcnt(0)
	v_cvt_pk_bf16_f32 v113, v114, v115
	ds_read2_b32 v[114:115], v81 offset0:140 offset1:173
	s_waitcnt lgkmcnt(0)
	v_cvt_pk_bf16_f32 v114, v114, v115
	ds_read2_b32 v[116:117], v81 offset0:206 offset1:239
	s_waitcnt lgkmcnt(0)
	v_cvt_pk_bf16_f32 v115, v116, v117
	v_or_b32_e32 v116, s0, v108
	v_lshlrev_b32_e32 v116, 11, v116
	v_mov_b32_e32 v117, v5
	v_lshl_add_u64 v[116:117], v[100:101], 0, v[116:117]
	global_store_dwordx4 v[116:117], v[112:115], off
	ds_read2_b32 v[112:113], v81 offset0:16 offset1:49
	s_waitcnt lgkmcnt(0)
	v_cvt_pk_bf16_f32 v112, v112, v113
	ds_read2_b32 v[114:115], v81 offset0:82 offset1:115
	s_waitcnt lgkmcnt(0)
	v_cvt_pk_bf16_f32 v113, v114, v115
	ds_read2_b32 v[114:115], v81 offset0:148 offset1:181
	s_waitcnt lgkmcnt(0)
	v_cvt_pk_bf16_f32 v114, v114, v115
	ds_read2_b32 v[116:117], v81 offset0:214 offset1:247
	s_waitcnt lgkmcnt(0)
	v_cvt_pk_bf16_f32 v115, v116, v117
	v_or_b32_e32 v116, s0, v109
	v_lshlrev_b32_e32 v116, 11, v116
	v_mov_b32_e32 v117, v5
	v_lshl_add_u64 v[116:117], v[100:101], 0, v[116:117]
	global_store_dwordx4 v[116:117], v[112:115], off
	ds_read2_b32 v[112:113], v81 offset0:24 offset1:57
	s_waitcnt lgkmcnt(0)
	v_cvt_pk_bf16_f32 v112, v112, v113
	ds_read2_b32 v[114:115], v81 offset0:90 offset1:123
	s_waitcnt lgkmcnt(0)
	v_cvt_pk_bf16_f32 v113, v114, v115
	ds_read2_b32 v[114:115], v81 offset0:156 offset1:189
	s_waitcnt lgkmcnt(0)
	v_cvt_pk_bf16_f32 v114, v114, v115
	ds_read2_b32 v[116:117], v81 offset0:222 offset1:255
	s_waitcnt lgkmcnt(0)
	v_cvt_pk_bf16_f32 v115, v116, v117
	v_or_b32_e32 v116, s0, v110
	v_lshlrev_b32_e32 v116, 11, v116
	v_mov_b32_e32 v117, v5
	v_lshl_add_u64 v[100:101], v[100:101], 0, v[116:117]
	global_store_dwordx4 v[100:101], v[112:115], off
	s_waitcnt lgkmcnt(0)

.LBB0_26:
	s_andn2_b64 vcc, exec, s[0:1]
	s_cbranch_vccnz .LBB0_28
	s_add_i32 s10, s21, 0xfffeec00
	v_lshl_add_u64 v[100:101], s[10:11], 2, v[20:21]
	v_lshlrev_b32_e32 v112, 2, v36
	v_mov_b32_e32 v113, v5
	v_lshl_add_u64 v[112:113], v[100:101], 0, v[112:113]
	global_load_dword v125, v[112:113], off nt
	v_lshlrev_b32_e32 v112, 2, v38
	v_mov_b32_e32 v113, v5
	v_lshl_add_u64 v[112:113], v[100:101], 0, v[112:113]
	global_load_dword v128, v[112:113], off nt
	v_mov_b32_e32 v113, v5
	v_lshlrev_b32_e32 v112, 2, v40
	v_lshl_add_u64 v[112:113], v[100:101], 0, v[112:113]
	global_load_dword v130, v[112:113], off nt
	v_lshlrev_b32_e32 v112, 2, v42
	v_mov_b32_e32 v113, v5
	v_lshl_add_u64 v[112:113], v[100:101], 0, v[112:113]
	global_load_dword v131, v[112:113], off nt
	v_mov_b32_e32 v113, v5
	v_lshlrev_b32_e32 v112, 2, v44
	v_lshl_add_u64 v[112:113], v[100:101], 0, v[112:113]
	global_load_dword v132, v[112:113], off nt
	v_lshlrev_b32_e32 v112, 2, v46
	v_mov_b32_e32 v113, v5
	v_lshl_add_u64 v[112:113], v[100:101], 0, v[112:113]
	global_load_dword v133, v[112:113], off nt
	v_lshlrev_b32_e32 v112, 2, v48
	v_mov_b32_e32 v113, v5
	v_lshl_add_u64 v[112:113], v[100:101], 0, v[112:113]
	global_load_dword v134, v[112:113], off nt
	v_lshlrev_b32_e32 v112, 2, v50
	v_mov_b32_e32 v113, v5
	v_lshl_add_u64 v[112:113], v[100:101], 0, v[112:113]
	global_load_dword v135, v[112:113], off nt
	v_mov_b32_e32 v113, v5
	v_lshlrev_b32_e32 v112, 2, v52
	v_lshl_add_u64 v[112:113], v[100:101], 0, v[112:113]
	global_load_dword v136, v[112:113], off nt
	v_lshlrev_b32_e32 v112, 2, v54
	v_mov_b32_e32 v113, v5
	v_lshl_add_u64 v[112:113], v[100:101], 0, v[112:113]
	global_load_dword v137, v[112:113], off nt
	v_mov_b32_e32 v113, v5
	v_lshlrev_b32_e32 v112, 2, v56
	v_lshl_add_u64 v[112:113], v[100:101], 0, v[112:113]
	global_load_dword v138, v[112:113], off nt
	v_lshlrev_b32_e32 v112, 2, v58
	v_mov_b32_e32 v113, v5
	v_lshl_add_u64 v[112:113], v[100:101], 0, v[112:113]
	global_load_dword v139, v[112:113], off nt
	v_lshlrev_b32_e32 v112, 2, v60
	v_mov_b32_e32 v113, v5
	v_lshl_add_u64 v[112:113], v[100:101], 0, v[112:113]
	global_load_dword v140, v[112:113], off nt
	v_lshlrev_b32_e32 v112, 2, v62
	v_mov_b32_e32 v113, v5
	v_lshl_add_u64 v[112:113], v[100:101], 0, v[112:113]
	global_load_dword v141, v[112:113], off nt
	v_mov_b32_e32 v113, v5
	v_lshlrev_b32_e32 v112, 2, v64
	v_lshl_add_u64 v[112:113], v[100:101], 0, v[112:113]
	global_load_dword v142, v[112:113], off nt
	v_lshlrev_b32_e32 v112, 2, v66
	v_mov_b32_e32 v113, v5
	v_lshl_add_u64 v[112:113], v[100:101], 0, v[112:113]
	global_load_dword v143, v[112:113], off nt
	v_mov_b32_e32 v113, v5
	v_lshlrev_b32_e32 v112, 2, v68
	v_lshl_add_u64 v[112:113], v[100:101], 0, v[112:113]
	global_load_dword v144, v[112:113], off nt
	v_lshlrev_b32_e32 v112, 2, v70
	v_mov_b32_e32 v113, v5
	v_lshl_add_u64 v[112:113], v[100:101], 0, v[112:113]
	global_load_dword v145, v[112:113], off nt
	v_lshlrev_b32_e32 v112, 2, v72
	v_mov_b32_e32 v113, v5
	v_lshl_add_u64 v[112:113], v[100:101], 0, v[112:113]
	global_load_dword v146, v[112:113], off nt
	v_lshlrev_b32_e32 v112, 2, v74
	v_mov_b32_e32 v113, v5
	v_lshl_add_u64 v[112:113], v[100:101], 0, v[112:113]
	global_load_dword v148, v[112:113], off nt
	v_mov_b32_e32 v113, v5
	v_lshlrev_b32_e32 v112, 2, v76
	v_lshl_add_u64 v[112:113], v[100:101], 0, v[112:113]
	global_load_dword v150, v[112:113], off nt
	v_lshlrev_b32_e32 v112, 2, v78
	v_mov_b32_e32 v113, v5
	v_lshl_add_u64 v[112:113], v[100:101], 0, v[112:113]
	global_load_dword v151, v[112:113], off nt
	v_mov_b32_e32 v113, v5
	v_lshlrev_b32_e32 v112, 2, v80
	v_lshl_add_u64 v[112:113], v[100:101], 0, v[112:113]
	global_load_dword v152, v[112:113], off nt
	v_lshlrev_b32_e32 v112, 2, v82
	v_mov_b32_e32 v113, v5
	v_lshl_add_u64 v[112:113], v[100:101], 0, v[112:113]
	global_load_dword v153, v[112:113], off nt
	v_lshlrev_b32_e32 v112, 2, v84
	v_mov_b32_e32 v113, v5
	v_lshl_add_u64 v[112:113], v[100:101], 0, v[112:113]
	global_load_dword v154, v[112:113], off nt
	v_lshlrev_b32_e32 v112, 2, v86
	v_mov_b32_e32 v113, v5
	v_lshl_add_u64 v[112:113], v[100:101], 0, v[112:113]
	global_load_dword v155, v[112:113], off nt
	v_mov_b32_e32 v113, v5
	v_lshlrev_b32_e32 v112, 2, v88
	v_lshl_add_u64 v[112:113], v[100:101], 0, v[112:113]
	global_load_dword v156, v[112:113], off nt
	v_lshlrev_b32_e32 v112, 2, v90
	v_mov_b32_e32 v113, v5
	v_lshl_add_u64 v[112:113], v[100:101], 0, v[112:113]
	global_load_dword v157, v[112:113], off nt
	v_mov_b32_e32 v113, v5
	v_lshlrev_b32_e32 v112, 2, v92
	v_lshl_add_u64 v[112:113], v[100:101], 0, v[112:113]
	global_load_dword v158, v[112:113], off nt
	v_lshlrev_b32_e32 v112, 2, v94
	v_mov_b32_e32 v113, v5
	v_lshl_add_u64 v[112:113], v[100:101], 0, v[112:113]
	global_load_dword v159, v[112:113], off nt
	v_mov_b32_e32 v113, v5
	v_lshlrev_b32_e32 v112, 2, v96
	v_lshl_add_u64 v[112:113], v[100:101], 0, v[112:113]
	global_load_dword v160, v[112:113], off nt
	v_lshlrev_b32_e32 v112, 2, v98
	v_mov_b32_e32 v113, v5
	v_lshl_add_u64 v[100:101], v[100:101], 0, v[112:113]
	global_load_dword v161, v[100:101], off nt
	s_waitcnt vmcnt(0)
	v_add_u32_e32 v115, v19, v37
	v_add_u32_e32 v116, s21, v79
	ds_write2_b32 v115, v125, v128 offset1:66
	ds_write2_b32 v115, v130, v131 offset0:132 offset1:198
	v_add_u32_e32 v113, 0x400, v115
	v_add_u32_e32 v115, v19, v51
	ds_write2_b32 v113, v132, v133 offset0:8 offset1:74
	ds_write2_b32 v115, v134, v135 offset1:66
	ds_write2_b32 v115, v136, v137 offset0:132 offset1:198
	v_add_u32_e32 v113, 0x400, v115
	v_add_u32_e32 v115, v19, v65
	ds_write2_b32 v113, v138, v139 offset0:8 offset1:74
	ds_write2_b32 v115, v140, v141 offset1:66
	ds_write2_b32 v115, v142, v143 offset0:132 offset1:198
	v_add_u32_e32 v113, 0x400, v115
	v_add_u32_e32 v115, v19, v75
	ds_write2_b32 v113, v144, v145 offset0:8 offset1:74
	ds_write2_b32 v115, v146, v148 offset1:66
	ds_write2_b32 v115, v150, v151 offset0:132 offset1:198
	v_add_u32_e32 v113, 0x400, v115
	v_add_u32_e32 v115, v19, v77
	ds_write2_b32 v113, v152, v153 offset0:8 offset1:74
	ds_write2_b32 v115, v154, v155 offset1:66
	ds_write2_b32 v115, v156, v157 offset0:132 offset1:198
	v_add_u32_e32 v115, 0x400, v115
	ds_write2_b32 v115, v158, v159 offset0:8 offset1:74
	ds_write2_b32 v115, v160, v161 offset0:140 offset1:206
	s_waitcnt lgkmcnt(0)
	ds_read2_b32 v[100:101], v81 offset1:33
	s_waitcnt lgkmcnt(0)
	v_cvt_pk_bf16_f32 v112, v100, v101
	ds_read2_b32 v[100:101], v81 offset0:66 offset1:99
	s_waitcnt lgkmcnt(0)
	v_cvt_pk_bf16_f32 v113, v100, v101
	ds_read2_b32 v[100:101], v81 offset0:132 offset1:165
	s_waitcnt lgkmcnt(0)
	v_cvt_pk_bf16_f32 v114, v100, v101
	ds_read2_b32 v[100:101], v81 offset0:198 offset1:231
	s_waitcnt lgkmcnt(0)
	v_cvt_pk_bf16_f32 v115, v100, v101
	v_add_u32_e32 v100, 0xfffef000, v116
	v_mov_b32_e32 v101, v5
	v_lshlrev_b64 v[100:101], 8, v[100:101]
	v_lshl_add_u64 v[100:101], v[22:23], 0, v[100:101]
	global_store_dwordx4 v[100:101], v[112:115], off
	ds_read2_b32 v[100:101], v81 offset0:8 offset1:41
	s_waitcnt lgkmcnt(0)
	v_cvt_pk_bf16_f32 v112, v100, v101
	ds_read2_b32 v[100:101], v81 offset0:74 offset1:107
	s_waitcnt lgkmcnt(0)
	v_cvt_pk_bf16_f32 v113, v100, v101
	ds_read2_b32 v[100:101], v81 offset0:140 offset1:173
	s_waitcnt lgkmcnt(0)
	v_cvt_pk_bf16_f32 v114, v100, v101
	ds_read2_b32 v[100:101], v81 offset0:206 offset1:239
	s_waitcnt lgkmcnt(0)
	v_cvt_pk_bf16_f32 v115, v100, v101
	v_add_u32_e32 v100, 0xfffef008, v116
	v_mov_b32_e32 v101, v5
	v_lshlrev_b64 v[100:101], 8, v[100:101]
	v_lshl_add_u64 v[100:101], v[22:23], 0, v[100:101]
	global_store_dwordx4 v[100:101], v[112:115], off
	ds_read2_b32 v[100:101], v81 offset0:16 offset1:49
	s_waitcnt lgkmcnt(0)
	v_cvt_pk_bf16_f32 v112, v100, v101
	ds_read2_b32 v[100:101], v81 offset0:82 offset1:115
	s_waitcnt lgkmcnt(0)
	v_cvt_pk_bf16_f32 v113, v100, v101
	ds_read2_b32 v[100:101], v81 offset0:148 offset1:181
	s_waitcnt lgkmcnt(0)
	v_cvt_pk_bf16_f32 v114, v100, v101
	ds_read2_b32 v[100:101], v81 offset0:214 offset1:247
	s_waitcnt lgkmcnt(0)
	v_cvt_pk_bf16_f32 v115, v100, v101
	v_add_u32_e32 v100, 0xfffef010, v116
	v_mov_b32_e32 v101, v5
	v_lshlrev_b64 v[100:101], 8, v[100:101]
	v_lshl_add_u64 v[100:101], v[22:23], 0, v[100:101]
	global_store_dwordx4 v[100:101], v[112:115], off
	ds_read2_b32 v[100:101], v81 offset0:24 offset1:57
	s_waitcnt lgkmcnt(0)
	v_cvt_pk_bf16_f32 v112, v100, v101
	ds_read2_b32 v[100:101], v81 offset0:90 offset1:123
	s_waitcnt lgkmcnt(0)
	v_cvt_pk_bf16_f32 v113, v100, v101
	ds_read2_b32 v[100:101], v81 offset0:156 offset1:189
	s_waitcnt lgkmcnt(0)
	v_cvt_pk_bf16_f32 v114, v100, v101
	ds_read2_b32 v[100:101], v81 offset0:222 offset1:255
	s_waitcnt lgkmcnt(0)
	v_cvt_pk_bf16_f32 v115, v100, v101
	v_add_u32_e32 v100, 0xfffef018, v116
	v_mov_b32_e32 v101, v5
	v_lshlrev_b64 v[100:101], 8, v[100:101]
	v_lshl_add_u64 v[100:101], v[22:23], 0, v[100:101]
	global_store_dwordx4 v[100:101], v[112:115], off
	s_waitcnt lgkmcnt(0)

.LBB0_29:
	s_andn2_b64 vcc, exec, s[0:1]
	s_cbranch_vccnz .LBB0_31
	s_add_i32 s10, s21, 0xfffef000
	v_lshl_add_u64 v[100:101], s[10:11], 2, v[24:25]
	v_lshlrev_b32_e32 v112, 2, v36
	v_mov_b32_e32 v113, v5
	v_lshl_add_u64 v[112:113], v[100:101], 0, v[112:113]
	global_load_dword v125, v[112:113], off nt
	v_lshlrev_b32_e32 v112, 2, v38
	v_mov_b32_e32 v113, v5
	v_lshl_add_u64 v[112:113], v[100:101], 0, v[112:113]
	global_load_dword v128, v[112:113], off nt
	v_mov_b32_e32 v113, v5
	v_lshlrev_b32_e32 v112, 2, v40
	v_lshl_add_u64 v[112:113], v[100:101], 0, v[112:113]
	global_load_dword v130, v[112:113], off nt
	v_lshlrev_b32_e32 v112, 2, v42
	v_mov_b32_e32 v113, v5
	v_lshl_add_u64 v[112:113], v[100:101], 0, v[112:113]
	global_load_dword v131, v[112:113], off nt
	v_mov_b32_e32 v113, v5
	v_lshlrev_b32_e32 v112, 2, v44
	v_lshl_add_u64 v[112:113], v[100:101], 0, v[112:113]
	global_load_dword v132, v[112:113], off nt
	v_lshlrev_b32_e32 v112, 2, v46
	v_mov_b32_e32 v113, v5
	v_lshl_add_u64 v[112:113], v[100:101], 0, v[112:113]
	global_load_dword v133, v[112:113], off nt
	v_lshlrev_b32_e32 v112, 2, v48
	v_mov_b32_e32 v113, v5
	v_lshl_add_u64 v[112:113], v[100:101], 0, v[112:113]
	global_load_dword v134, v[112:113], off nt
	v_lshlrev_b32_e32 v112, 2, v50
	v_mov_b32_e32 v113, v5
	v_lshl_add_u64 v[112:113], v[100:101], 0, v[112:113]
	global_load_dword v135, v[112:113], off nt
	v_mov_b32_e32 v113, v5
	v_lshlrev_b32_e32 v112, 2, v52
	v_lshl_add_u64 v[112:113], v[100:101], 0, v[112:113]
	global_load_dword v136, v[112:113], off nt
	v_lshlrev_b32_e32 v112, 2, v54
	v_mov_b32_e32 v113, v5
	v_lshl_add_u64 v[112:113], v[100:101], 0, v[112:113]
	global_load_dword v137, v[112:113], off nt
	v_mov_b32_e32 v113, v5
	v_lshlrev_b32_e32 v112, 2, v56
	v_lshl_add_u64 v[112:113], v[100:101], 0, v[112:113]
	global_load_dword v138, v[112:113], off nt
	v_lshlrev_b32_e32 v112, 2, v58
	v_mov_b32_e32 v113, v5
	v_lshl_add_u64 v[112:113], v[100:101], 0, v[112:113]
	global_load_dword v139, v[112:113], off nt
	v_lshlrev_b32_e32 v112, 2, v60
	v_mov_b32_e32 v113, v5
	v_lshl_add_u64 v[112:113], v[100:101], 0, v[112:113]
	global_load_dword v140, v[112:113], off nt
	v_lshlrev_b32_e32 v112, 2, v62
	v_mov_b32_e32 v113, v5
	v_lshl_add_u64 v[112:113], v[100:101], 0, v[112:113]
	global_load_dword v141, v[112:113], off nt
	v_mov_b32_e32 v113, v5
	v_lshlrev_b32_e32 v112, 2, v64
	v_lshl_add_u64 v[112:113], v[100:101], 0, v[112:113]
	global_load_dword v142, v[112:113], off nt
	v_lshlrev_b32_e32 v112, 2, v66
	v_mov_b32_e32 v113, v5
	v_lshl_add_u64 v[112:113], v[100:101], 0, v[112:113]
	global_load_dword v143, v[112:113], off nt
	v_mov_b32_e32 v113, v5
	v_lshlrev_b32_e32 v112, 2, v68
	v_lshl_add_u64 v[112:113], v[100:101], 0, v[112:113]
	global_load_dword v144, v[112:113], off nt
	v_lshlrev_b32_e32 v112, 2, v70
	v_mov_b32_e32 v113, v5
	v_lshl_add_u64 v[112:113], v[100:101], 0, v[112:113]
	global_load_dword v145, v[112:113], off nt
	v_lshlrev_b32_e32 v112, 2, v72
	v_mov_b32_e32 v113, v5
	v_lshl_add_u64 v[112:113], v[100:101], 0, v[112:113]
	global_load_dword v146, v[112:113], off nt
	v_lshlrev_b32_e32 v112, 2, v74
	v_mov_b32_e32 v113, v5
	v_lshl_add_u64 v[112:113], v[100:101], 0, v[112:113]
	global_load_dword v148, v[112:113], off nt
	v_mov_b32_e32 v113, v5
	v_lshlrev_b32_e32 v112, 2, v76
	v_lshl_add_u64 v[112:113], v[100:101], 0, v[112:113]
	global_load_dword v150, v[112:113], off nt
	v_lshlrev_b32_e32 v112, 2, v78
	v_mov_b32_e32 v113, v5
	v_lshl_add_u64 v[112:113], v[100:101], 0, v[112:113]
	global_load_dword v151, v[112:113], off nt
	v_mov_b32_e32 v113, v5
	v_lshlrev_b32_e32 v112, 2, v80
	v_lshl_add_u64 v[112:113], v[100:101], 0, v[112:113]
	global_load_dword v152, v[112:113], off nt
	v_lshlrev_b32_e32 v112, 2, v82
	v_mov_b32_e32 v113, v5
	v_lshl_add_u64 v[112:113], v[100:101], 0, v[112:113]
	global_load_dword v153, v[112:113], off nt
	v_lshlrev_b32_e32 v112, 2, v84
	v_mov_b32_e32 v113, v5
	v_lshl_add_u64 v[112:113], v[100:101], 0, v[112:113]
	global_load_dword v154, v[112:113], off nt
	v_lshlrev_b32_e32 v112, 2, v86
	v_mov_b32_e32 v113, v5
	v_lshl_add_u64 v[112:113], v[100:101], 0, v[112:113]
	global_load_dword v155, v[112:113], off nt
	v_mov_b32_e32 v113, v5
	v_lshlrev_b32_e32 v112, 2, v88
	v_lshl_add_u64 v[112:113], v[100:101], 0, v[112:113]
	global_load_dword v156, v[112:113], off nt
	v_lshlrev_b32_e32 v112, 2, v90
	v_mov_b32_e32 v113, v5
	v_lshl_add_u64 v[112:113], v[100:101], 0, v[112:113]
	global_load_dword v157, v[112:113], off nt
	v_mov_b32_e32 v113, v5
	v_lshlrev_b32_e32 v112, 2, v92
	v_lshl_add_u64 v[112:113], v[100:101], 0, v[112:113]
	global_load_dword v158, v[112:113], off nt
	v_lshlrev_b32_e32 v112, 2, v94
	v_mov_b32_e32 v113, v5
	v_lshl_add_u64 v[112:113], v[100:101], 0, v[112:113]
	global_load_dword v159, v[112:113], off nt
	v_mov_b32_e32 v113, v5
	v_lshlrev_b32_e32 v112, 2, v96
	v_lshl_add_u64 v[112:113], v[100:101], 0, v[112:113]
	global_load_dword v160, v[112:113], off nt
	v_lshlrev_b32_e32 v112, 2, v98
	v_mov_b32_e32 v113, v5
	v_lshl_add_u64 v[100:101], v[100:101], 0, v[112:113]
	global_load_dword v161, v[100:101], off nt
	s_waitcnt vmcnt(0)
	v_add_u32_e32 v115, v19, v37
	v_add_u32_e32 v116, s21, v79
	ds_write2_b32 v115, v125, v128 offset1:66
	ds_write2_b32 v115, v130, v131 offset0:132 offset1:198
	v_add_u32_e32 v113, 0x400, v115
	v_add_u32_e32 v115, v19, v51
	ds_write2_b32 v113, v132, v133 offset0:8 offset1:74
	ds_write2_b32 v115, v134, v135 offset1:66
	ds_write2_b32 v115, v136, v137 offset0:132 offset1:198
	v_add_u32_e32 v113, 0x400, v115
	v_add_u32_e32 v115, v19, v65
	ds_write2_b32 v113, v138, v139 offset0:8 offset1:74
	ds_write2_b32 v115, v140, v141 offset1:66
	ds_write2_b32 v115, v142, v143 offset0:132 offset1:198
	v_add_u32_e32 v113, 0x400, v115
	v_add_u32_e32 v115, v19, v75
	ds_write2_b32 v113, v144, v145 offset0:8 offset1:74
	ds_write2_b32 v115, v146, v148 offset1:66
	ds_write2_b32 v115, v150, v151 offset0:132 offset1:198
	v_add_u32_e32 v113, 0x400, v115
	v_add_u32_e32 v115, v19, v77
	ds_write2_b32 v113, v152, v153 offset0:8 offset1:74
	ds_write2_b32 v115, v154, v155 offset1:66
	ds_write2_b32 v115, v156, v157 offset0:132 offset1:198
	v_add_u32_e32 v115, 0x400, v115
	ds_write2_b32 v115, v158, v159 offset0:8 offset1:74
	ds_write2_b32 v115, v160, v161 offset0:140 offset1:206
	s_waitcnt lgkmcnt(0)
	ds_read2_b32 v[100:101], v81 offset1:33
	s_waitcnt lgkmcnt(0)
	v_cvt_pk_bf16_f32 v112, v100, v101
	ds_read2_b32 v[100:101], v81 offset0:66 offset1:99
	s_waitcnt lgkmcnt(0)
	v_cvt_pk_bf16_f32 v113, v100, v101
	ds_read2_b32 v[100:101], v81 offset0:132 offset1:165
	s_waitcnt lgkmcnt(0)
	v_cvt_pk_bf16_f32 v114, v100, v101
	ds_read2_b32 v[100:101], v81 offset0:198 offset1:231
	s_waitcnt lgkmcnt(0)
	v_cvt_pk_bf16_f32 v115, v100, v101
	v_add_u32_e32 v100, 0xfffef000, v116
	v_mov_b32_e32 v101, v5
	v_lshlrev_b64 v[100:101], 8, v[100:101]
	v_lshl_add_u64 v[100:101], v[26:27], 0, v[100:101]
	global_store_dwordx4 v[100:101], v[112:115], off
	ds_read2_b32 v[100:101], v81 offset0:8 offset1:41
	s_waitcnt lgkmcnt(0)
	v_cvt_pk_bf16_f32 v112, v100, v101
	ds_read2_b32 v[100:101], v81 offset0:74 offset1:107
	s_waitcnt lgkmcnt(0)
	v_cvt_pk_bf16_f32 v113, v100, v101
	ds_read2_b32 v[100:101], v81 offset0:140 offset1:173
	s_waitcnt lgkmcnt(0)
	v_cvt_pk_bf16_f32 v114, v100, v101
	ds_read2_b32 v[100:101], v81 offset0:206 offset1:239
	s_waitcnt lgkmcnt(0)
	v_cvt_pk_bf16_f32 v115, v100, v101
	v_add_u32_e32 v100, 0xfffef008, v116
	v_mov_b32_e32 v101, v5
	v_lshlrev_b64 v[100:101], 8, v[100:101]
	v_lshl_add_u64 v[100:101], v[26:27], 0, v[100:101]
	global_store_dwordx4 v[100:101], v[112:115], off
	ds_read2_b32 v[100:101], v81 offset0:16 offset1:49
	s_waitcnt lgkmcnt(0)
	v_cvt_pk_bf16_f32 v112, v100, v101
	ds_read2_b32 v[100:101], v81 offset0:82 offset1:115
	s_waitcnt lgkmcnt(0)
	v_cvt_pk_bf16_f32 v113, v100, v101
	ds_read2_b32 v[100:101], v81 offset0:148 offset1:181
	s_waitcnt lgkmcnt(0)
	v_cvt_pk_bf16_f32 v114, v100, v101
	ds_read2_b32 v[100:101], v81 offset0:214 offset1:247
	s_waitcnt lgkmcnt(0)
	v_cvt_pk_bf16_f32 v115, v100, v101
	v_add_u32_e32 v100, 0xfffef010, v116
	v_mov_b32_e32 v101, v5
	v_lshlrev_b64 v[100:101], 8, v[100:101]
	v_lshl_add_u64 v[100:101], v[26:27], 0, v[100:101]
	global_store_dwordx4 v[100:101], v[112:115], off
	ds_read2_b32 v[100:101], v81 offset0:24 offset1:57
	s_waitcnt lgkmcnt(0)
	v_cvt_pk_bf16_f32 v112, v100, v101
	ds_read2_b32 v[100:101], v81 offset0:90 offset1:123
	s_waitcnt lgkmcnt(0)
	v_cvt_pk_bf16_f32 v113, v100, v101
	ds_read2_b32 v[100:101], v81 offset0:156 offset1:189
	s_waitcnt lgkmcnt(0)
	v_cvt_pk_bf16_f32 v114, v100, v101
	ds_read2_b32 v[100:101], v81 offset0:222 offset1:255
	s_waitcnt lgkmcnt(0)
	v_cvt_pk_bf16_f32 v115, v100, v101
	v_add_u32_e32 v100, 0xfffef018, v116
	v_mov_b32_e32 v101, v5
	v_lshlrev_b64 v[100:101], 8, v[100:101]
	v_lshl_add_u64 v[100:101], v[26:27], 0, v[100:101]
	global_store_dwordx4 v[100:101], v[112:115], off
	s_waitcnt lgkmcnt(0)

.LBB0_32:
	s_andn2_b64 vcc, exec, s[0:1]
	s_cbranch_vccnz .LBB0_34
	s_add_i32 s0, s21, 0x1400
	s_and_b32 s1, s0, 0x1fc0
	s_and_b32 s0, s21, 32
	s_lshl_b32 s10, s0, 2
	v_or_b32_e32 v114, s1, v3
	v_lshl_add_u64 v[100:101], v[28:29], 0, s[10:11]
	v_lshlrev_b32_e32 v112, 8, v114
	v_mov_b32_e32 v113, v5
	v_lshl_add_u64 v[112:113], v[100:101], 0, v[112:113]
	global_load_dword v125, v[112:113], off nt
	v_lshlrev_b32_e32 v113, 2, v114
	global_load_dword v128, v113, s[6:7] nt
	v_or_b32_e32 v116, s1, v39
	v_lshlrev_b32_e32 v112, 8, v116
	v_mov_b32_e32 v113, v5
	v_lshl_add_u64 v[112:113], v[100:101], 0, v[112:113]
	global_load_dword v130, v[112:113], off nt
	v_lshlrev_b32_e32 v113, 2, v116
	global_load_dword v131, v113, s[6:7] nt
	v_or_b32_e32 v116, s1, v43
	v_or_b32_e32 v114, s1, v41
	v_lshlrev_b32_e32 v112, 8, v114
	v_mov_b32_e32 v113, v5
	v_lshl_add_u64 v[112:113], v[100:101], 0, v[112:113]
	global_load_dword v132, v[112:113], off nt
	v_lshlrev_b32_e32 v113, 2, v114
	global_load_dword v133, v113, s[6:7] nt
	v_lshlrev_b32_e32 v112, 8, v116
	v_mov_b32_e32 v113, v5
	v_lshl_add_u64 v[112:113], v[100:101], 0, v[112:113]
	global_load_dword v134, v[112:113], off nt
	v_lshlrev_b32_e32 v113, 2, v116
	global_load_dword v135, v113, s[6:7] nt
	v_or_b32_e32 v116, s1, v47
	v_or_b32_e32 v114, s1, v45
	v_lshlrev_b32_e32 v112, 8, v114
	v_mov_b32_e32 v113, v5
	v_lshl_add_u64 v[112:113], v[100:101], 0, v[112:113]
	global_load_dword v136, v[112:113], off nt
	v_lshlrev_b32_e32 v113, 2, v114
	global_load_dword v137, v113, s[6:7] nt
	v_lshlrev_b32_e32 v112, 8, v116
	v_mov_b32_e32 v113, v5
	v_lshl_add_u64 v[112:113], v[100:101], 0, v[112:113]
	global_load_dword v138, v[112:113], off nt
	v_lshlrev_b32_e32 v113, 2, v116
	global_load_dword v139, v113, s[6:7] nt
	v_or_b32_e32 v116, s1, v53
	v_or_b32_e32 v114, s1, v49
	v_lshlrev_b32_e32 v112, 8, v114
	v_mov_b32_e32 v113, v5
	v_lshl_add_u64 v[112:113], v[100:101], 0, v[112:113]
	global_load_dword v140, v[112:113], off nt
	v_lshlrev_b32_e32 v113, 2, v114
	global_load_dword v141, v113, s[6:7] nt
	v_lshlrev_b32_e32 v112, 8, v116
	v_mov_b32_e32 v113, v5
	v_lshl_add_u64 v[112:113], v[100:101], 0, v[112:113]
	global_load_dword v142, v[112:113], off nt
	v_lshlrev_b32_e32 v113, 2, v116
	global_load_dword v143, v113, s[6:7] nt
	v_or_b32_e32 v116, s1, v57
	v_or_b32_e32 v114, s1, v55
	v_lshlrev_b32_e32 v112, 8, v114
	v_mov_b32_e32 v113, v5
	v_lshl_add_u64 v[112:113], v[100:101], 0, v[112:113]
	global_load_dword v144, v[112:113], off nt
	v_lshlrev_b32_e32 v113, 2, v114
	global_load_dword v145, v113, s[6:7] nt
	v_lshlrev_b32_e32 v112, 8, v116
	v_mov_b32_e32 v113, v5
	v_lshl_add_u64 v[112:113], v[100:101], 0, v[112:113]
	global_load_dword v146, v[112:113], off nt
	v_lshlrev_b32_e32 v113, 2, v116
	global_load_dword v148, v113, s[6:7] nt
	v_or_b32_e32 v116, s1, v61
	v_or_b32_e32 v114, s1, v59
	v_lshlrev_b32_e32 v112, 8, v114
	v_mov_b32_e32 v113, v5
	v_lshl_add_u64 v[112:113], v[100:101], 0, v[112:113]
	global_load_dword v150, v[112:113], off nt
	v_lshlrev_b32_e32 v113, 2, v114
	global_load_dword v151, v113, s[6:7] nt
	v_lshlrev_b32_e32 v112, 8, v116
	v_mov_b32_e32 v113, v5
	v_lshl_add_u64 v[112:113], v[100:101], 0, v[112:113]
	global_load_dword v152, v[112:113], off nt
	v_lshlrev_b32_e32 v113, 2, v116
	global_load_dword v153, v113, s[6:7] nt
	v_or_b32_e32 v116, s1, v67
	v_or_b32_e32 v114, s1, v63
	v_lshlrev_b32_e32 v112, 8, v114
	v_mov_b32_e32 v113, v5
	v_lshl_add_u64 v[112:113], v[100:101], 0, v[112:113]
	global_load_dword v154, v[112:113], off nt
	v_lshlrev_b32_e32 v113, 2, v114
	global_load_dword v155, v113, s[6:7] nt
	v_lshlrev_b32_e32 v112, 8, v116
	v_mov_b32_e32 v113, v5
	v_lshl_add_u64 v[112:113], v[100:101], 0, v[112:113]
	global_load_dword v156, v[112:113], off nt
	v_lshlrev_b32_e32 v113, 2, v116
	global_load_dword v157, v113, s[6:7] nt
	v_or_b32_e32 v116, s1, v71
	v_or_b32_e32 v114, s1, v69
	v_lshlrev_b32_e32 v112, 8, v114
	v_mov_b32_e32 v113, v5
	v_lshl_add_u64 v[112:113], v[100:101], 0, v[112:113]
	global_load_dword v158, v[112:113], off nt
	v_lshlrev_b32_e32 v113, 2, v114
	global_load_dword v159, v113, s[6:7] nt
	v_lshlrev_b32_e32 v112, 8, v116
	v_mov_b32_e32 v113, v5
	v_lshl_add_u64 v[112:113], v[100:101], 0, v[112:113]
	global_load_dword v160, v[112:113], off nt
	v_lshlrev_b32_e32 v113, 2, v116
	global_load_dword v161, v113, s[6:7] nt
	v_or_b32_e32 v116, s1, v83
	v_or_b32_e32 v114, s1, v73
	v_lshlrev_b32_e32 v112, 8, v114
	v_mov_b32_e32 v113, v5
	v_lshl_add_u64 v[112:113], v[100:101], 0, v[112:113]
	global_load_dword v162, v[112:113], off nt
	v_lshlrev_b32_e32 v113, 2, v114
	global_load_dword v163, v113, s[6:7] nt
	v_lshlrev_b32_e32 v112, 8, v116
	v_mov_b32_e32 v113, v5
	v_lshl_add_u64 v[112:113], v[100:101], 0, v[112:113]
	global_load_dword v164, v[112:113], off nt
	v_lshlrev_b32_e32 v113, 2, v116
	global_load_dword v165, v113, s[6:7] nt
	v_or_b32_e32 v116, s1, v87
	v_or_b32_e32 v114, s1, v85
	v_lshlrev_b32_e32 v112, 8, v114
	v_mov_b32_e32 v113, v5
	v_lshl_add_u64 v[112:113], v[100:101], 0, v[112:113]
	global_load_dword v166, v[112:113], off nt
	v_lshlrev_b32_e32 v113, 2, v114
	global_load_dword v168, v113, s[6:7] nt
	v_lshlrev_b32_e32 v112, 8, v116
	v_mov_b32_e32 v113, v5
	v_lshl_add_u64 v[112:113], v[100:101], 0, v[112:113]
	global_load_dword v170, v[112:113], off nt
	v_lshlrev_b32_e32 v113, 2, v116
	global_load_dword v171, v113, s[6:7] nt
	v_or_b32_e32 v116, s1, v91
	v_or_b32_e32 v114, s1, v89
	v_lshlrev_b32_e32 v112, 8, v114
	v_mov_b32_e32 v113, v5
	v_lshl_add_u64 v[112:113], v[100:101], 0, v[112:113]
	global_load_dword v172, v[112:113], off nt
	v_lshlrev_b32_e32 v113, 2, v114
	global_load_dword v173, v113, s[6:7] nt
	v_lshlrev_b32_e32 v112, 8, v116
	v_mov_b32_e32 v113, v5
	v_lshl_add_u64 v[112:113], v[100:101], 0, v[112:113]
	global_load_dword v174, v[112:113], off nt
	v_lshlrev_b32_e32 v113, 2, v116
	global_load_dword v176, v113, s[6:7] nt
	v_or_b32_e32 v116, s1, v95
	v_or_b32_e32 v114, s1, v93
	v_lshlrev_b32_e32 v112, 8, v114
	v_mov_b32_e32 v113, v5
	v_lshl_add_u64 v[112:113], v[100:101], 0, v[112:113]
	global_load_dword v177, v[112:113], off nt
	v_lshlrev_b32_e32 v113, 2, v114
	global_load_dword v178, v113, s[6:7] nt
	v_lshlrev_b32_e32 v112, 8, v116
	v_mov_b32_e32 v113, v5
	v_lshl_add_u64 v[112:113], v[100:101], 0, v[112:113]
	global_load_dword v179, v[112:113], off nt
	v_lshlrev_b32_e32 v113, 2, v116
	global_load_dword v180, v113, s[6:7] nt
	v_or_b32_e32 v116, s1, v99
	v_or_b32_e32 v114, s1, v97
	v_lshlrev_b32_e32 v112, 8, v114
	v_mov_b32_e32 v113, v5
	v_lshl_add_u64 v[112:113], v[100:101], 0, v[112:113]
	s_waitcnt vmcnt(16)
	global_load_dword v181, v[112:113], off nt
	v_lshlrev_b32_e32 v113, 2, v114
	global_load_dword v182, v113, s[6:7] nt
	v_lshlrev_b32_e32 v112, 8, v116
	v_mov_b32_e32 v113, v5
	v_lshl_add_u64 v[112:113], v[100:101], 0, v[112:113]
	global_load_dword v183, v[112:113], off nt
	v_lshlrev_b32_e32 v113, 2, v116
	global_load_dword v184, v113, s[6:7] nt
	v_or_b32_e32 v116, s1, v103
	v_or_b32_e32 v114, s1, v102
	v_lshlrev_b32_e32 v112, 8, v114
	v_mov_b32_e32 v113, v5
	v_lshl_add_u64 v[112:113], v[100:101], 0, v[112:113]
	global_load_dword v185, v[112:113], off nt
	v_lshlrev_b32_e32 v113, 2, v114
	global_load_dword v186, v113, s[6:7] nt
	v_lshlrev_b32_e32 v112, 8, v116
	v_mov_b32_e32 v113, v5
	v_lshl_add_u64 v[112:113], v[100:101], 0, v[112:113]
	global_load_dword v187, v[112:113], off nt
	v_lshlrev_b32_e32 v113, 2, v116
	global_load_dword v188, v113, s[6:7] nt
	v_or_b32_e32 v116, s1, v105
	v_or_b32_e32 v114, s1, v104
	v_lshlrev_b32_e32 v112, 8, v114
	v_mov_b32_e32 v113, v5
	v_lshl_add_u64 v[112:113], v[100:101], 0, v[112:113]
	global_load_dword v189, v[112:113], off nt
	v_lshlrev_b32_e32 v113, 2, v114
	global_load_dword v190, v113, s[6:7] nt
	v_lshlrev_b32_e32 v112, 8, v116
	v_mov_b32_e32 v113, v5
	v_lshl_add_u64 v[112:113], v[100:101], 0, v[112:113]
	global_load_dword v191, v[112:113], off nt
	v_lshlrev_b32_e32 v113, 2, v116
	global_load_dword v192, v113, s[6:7] nt
	v_or_b32_e32 v116, s1, v107
	v_or_b32_e32 v114, s1, v106
	v_lshlrev_b32_e32 v112, 8, v114
	v_mov_b32_e32 v113, v5
	v_lshl_add_u64 v[112:113], v[100:101], 0, v[112:113]
	global_load_dword v193, v[112:113], off nt
	v_lshlrev_b32_e32 v113, 2, v114
	global_load_dword v194, v113, s[6:7] nt
	v_lshlrev_b32_e32 v112, 8, v116
	v_mov_b32_e32 v113, v5
	v_lshl_add_u64 v[100:101], v[100:101], 0, v[112:113]
	global_load_dword v195, v[100:101], off nt
	v_lshlrev_b32_e32 v101, 2, v116
	global_load_dword v196, v101, s[6:7] nt
	s_waitcnt vmcnt(0)
	v_add_u32_e32 v115, v19, v37
	s_lshl_b32 s10, s1, 1
	v_mul_f32_e32 v114, v125, v128
	v_mul_f32_e32 v112, v130, v131
	ds_write2_b32 v115, v114, v112 offset1:66
	v_mul_f32_e32 v114, v132, v133
	v_mul_f32_e32 v112, v134, v135
	ds_write2_b32 v115, v114, v112 offset0:132 offset1:198
	v_mul_f32_e32 v114, v136, v137
	v_mul_f32_e32 v112, v138, v139
	v_add_u32_e32 v113, 0x400, v115
	ds_write2_b32 v113, v114, v112 offset0:8 offset1:74
	v_add_u32_e32 v115, v19, v51
	v_mul_f32_e32 v114, v140, v141
	v_mul_f32_e32 v112, v142, v143
	ds_write2_b32 v115, v114, v112 offset1:66
	v_mul_f32_e32 v114, v144, v145
	v_mul_f32_e32 v112, v146, v148
	ds_write2_b32 v115, v114, v112 offset0:132 offset1:198
	v_mul_f32_e32 v114, v150, v151
	v_mul_f32_e32 v112, v152, v153
	v_add_u32_e32 v113, 0x400, v115
	ds_write2_b32 v113, v114, v112 offset0:8 offset1:74
	v_add_u32_e32 v115, v19, v65
	v_mul_f32_e32 v114, v154, v155
	v_mul_f32_e32 v112, v156, v157
	ds_write2_b32 v115, v114, v112 offset1:66
	v_mul_f32_e32 v114, v158, v159
	v_mul_f32_e32 v112, v160, v161
	ds_write2_b32 v115, v114, v112 offset0:132 offset1:198
	v_mul_f32_e32 v114, v162, v163
	v_mul_f32_e32 v112, v164, v165
	v_add_u32_e32 v113, 0x400, v115
	ds_write2_b32 v113, v114, v112 offset0:8 offset1:74
	v_add_u32_e32 v115, v19, v75
	v_mul_f32_e32 v114, v166, v168
	v_mul_f32_e32 v112, v170, v171
	ds_write2_b32 v115, v114, v112 offset1:66
	v_mul_f32_e32 v114, v172, v173
	v_mul_f32_e32 v112, v174, v176
	ds_write2_b32 v115, v114, v112 offset0:132 offset1:198
	v_mul_f32_e32 v114, v177, v178
	v_mul_f32_e32 v112, v179, v180
	v_add_u32_e32 v113, 0x400, v115
	ds_write2_b32 v113, v114, v112 offset0:8 offset1:74
	v_add_u32_e32 v115, v19, v77
	v_mul_f32_e32 v114, v181, v182
	v_mul_f32_e32 v112, v183, v184
	ds_write2_b32 v115, v114, v112 offset1:66
	v_mul_f32_e32 v114, v185, v186
	v_mul_f32_e32 v112, v187, v188
	ds_write2_b32 v115, v114, v112 offset0:132 offset1:198
	v_add_u32_e32 v115, 0x400, v115
	v_mul_f32_e32 v114, v189, v190
	v_mul_f32_e32 v112, v191, v192
	ds_write2_b32 v115, v114, v112 offset0:8 offset1:74
	v_mul_f32_e32 v114, v193, v194
	v_mul_f32_e32 v100, v195, v196
	ds_write2_b32 v115, v114, v100 offset0:140 offset1:206
	s_waitcnt lgkmcnt(0)
	ds_read2_b32 v[112:113], v81 offset1:33
	s_waitcnt lgkmcnt(0)
	v_cvt_pk_bf16_f32 v112, v112, v113
	ds_read2_b32 v[114:115], v81 offset0:66 offset1:99
	s_waitcnt lgkmcnt(0)
	v_cvt_pk_bf16_f32 v113, v114, v115
	ds_read2_b32 v[114:115], v81 offset0:132 offset1:165
	s_waitcnt lgkmcnt(0)
	v_cvt_pk_bf16_f32 v114, v114, v115
	ds_read2_b32 v[116:117], v81 offset0:198 offset1:231
	s_waitcnt lgkmcnt(0)
	v_cvt_pk_bf16_f32 v115, v116, v117
	v_or_b32_e32 v116, s0, v79
	v_lshl_add_u64 v[100:101], v[32:33], 0, s[10:11]
	v_lshlrev_b32_e32 v116, 11, v116
	v_mov_b32_e32 v117, v5
	v_lshl_add_u64 v[116:117], v[100:101], 0, v[116:117]
	v_add_co_u32_e32 v116, vcc, s23, v116
	s_nop 1
	v_addc_co_u32_e32 v117, vcc, 0, v117, vcc
	global_store_dwordx4 v[116:117], v[112:115], off
	ds_read2_b32 v[112:113], v81 offset0:8 offset1:41
	s_waitcnt lgkmcnt(0)
	v_cvt_pk_bf16_f32 v112, v112, v113
	ds_read2_b32 v[114:115], v81 offset0:74 offset1:107
	s_waitcnt lgkmcnt(0)
	v_cvt_pk_bf16_f32 v113, v114, v115
	ds_read2_b32 v[114:115], v81 offset0:140 offset1:173
	s_waitcnt lgkmcnt(0)
	v_cvt_pk_bf16_f32 v114, v114, v115
	ds_read2_b32 v[116:117], v81 offset0:206 offset1:239
	s_waitcnt lgkmcnt(0)
	v_cvt_pk_bf16_f32 v115, v116, v117
	v_or_b32_e32 v116, s0, v108
	v_lshlrev_b32_e32 v116, 11, v116
	v_mov_b32_e32 v117, v5
	v_lshl_add_u64 v[116:117], v[100:101], 0, v[116:117]
	v_add_co_u32_e32 v116, vcc, s23, v116
	s_nop 1
	v_addc_co_u32_e32 v117, vcc, 0, v117, vcc
	global_store_dwordx4 v[116:117], v[112:115], off
	ds_read2_b32 v[112:113], v81 offset0:16 offset1:49
	s_waitcnt lgkmcnt(0)
	v_cvt_pk_bf16_f32 v112, v112, v113
	ds_read2_b32 v[114:115], v81 offset0:82 offset1:115
	s_waitcnt lgkmcnt(0)
	v_cvt_pk_bf16_f32 v113, v114, v115
	ds_read2_b32 v[114:115], v81 offset0:148 offset1:181
	s_waitcnt lgkmcnt(0)
	v_cvt_pk_bf16_f32 v114, v114, v115
	ds_read2_b32 v[116:117], v81 offset0:214 offset1:247
	s_waitcnt lgkmcnt(0)
	v_cvt_pk_bf16_f32 v115, v116, v117
	v_or_b32_e32 v116, s0, v109
	v_lshlrev_b32_e32 v116, 11, v116
	v_mov_b32_e32 v117, v5
	v_lshl_add_u64 v[116:117], v[100:101], 0, v[116:117]
	v_add_co_u32_e32 v116, vcc, s23, v116
	s_nop 1
	v_addc_co_u32_e32 v117, vcc, 0, v117, vcc
	global_store_dwordx4 v[116:117], v[112:115], off
	ds_read2_b32 v[112:113], v81 offset0:24 offset1:57
	s_waitcnt lgkmcnt(0)
	v_cvt_pk_bf16_f32 v112, v112, v113
	ds_read2_b32 v[114:115], v81 offset0:90 offset1:123
	s_waitcnt lgkmcnt(0)
	v_cvt_pk_bf16_f32 v113, v114, v115
	ds_read2_b32 v[114:115], v81 offset0:156 offset1:189
	s_waitcnt lgkmcnt(0)
	v_cvt_pk_bf16_f32 v114, v114, v115
	ds_read2_b32 v[116:117], v81 offset0:222 offset1:255
	s_waitcnt lgkmcnt(0)
	v_cvt_pk_bf16_f32 v115, v116, v117
	v_or_b32_e32 v116, s0, v110
	v_lshlrev_b32_e32 v116, 11, v116
	v_mov_b32_e32 v117, v5
	v_lshl_add_u64 v[100:101], v[100:101], 0, v[116:117]
	v_add_co_u32_e32 v100, vcc, 0x60000, v100
	s_nop 1
	v_addc_co_u32_e32 v101, vcc, 0, v101, vcc
	global_store_dwordx4 v[100:101], v[112:115], off
	s_waitcnt lgkmcnt(0)

.LBB0_35:
	s_andn2_b64 vcc, exec, s[0:1]
	s_cbranch_vccnz .LBB0_37
	s_add_i32 s0, s21, 0x1800
	s_and_b32 s1, s0, 0x1fc0
	s_and_b32 s0, s21, 32
	s_lshl_b32 s10, s0, 2
	v_or_b32_e32 v114, s1, v3
	v_lshl_add_u64 v[100:101], v[28:29], 0, s[10:11]
	v_lshlrev_b32_e32 v112, 8, v114
	v_mov_b32_e32 v113, v5
	v_lshl_add_u64 v[112:113], v[100:101], 0, v[112:113]
	global_load_dword v125, v[112:113], off nt
	v_lshlrev_b32_e32 v113, 2, v114
	global_load_dword v128, v113, s[6:7] nt
	v_or_b32_e32 v116, s1, v39
	v_lshlrev_b32_e32 v112, 8, v116
	v_mov_b32_e32 v113, v5
	v_lshl_add_u64 v[112:113], v[100:101], 0, v[112:113]
	global_load_dword v130, v[112:113], off nt
	v_lshlrev_b32_e32 v113, 2, v116
	global_load_dword v131, v113, s[6:7] nt
	v_or_b32_e32 v116, s1, v43
	v_or_b32_e32 v114, s1, v41
	v_lshlrev_b32_e32 v112, 8, v114
	v_mov_b32_e32 v113, v5
	v_lshl_add_u64 v[112:113], v[100:101], 0, v[112:113]
	global_load_dword v132, v[112:113], off nt
	v_lshlrev_b32_e32 v113, 2, v114
	global_load_dword v133, v113, s[6:7] nt
	v_lshlrev_b32_e32 v112, 8, v116
	v_mov_b32_e32 v113, v5
	v_lshl_add_u64 v[112:113], v[100:101], 0, v[112:113]
	global_load_dword v134, v[112:113], off nt
	v_lshlrev_b32_e32 v113, 2, v116
	global_load_dword v135, v113, s[6:7] nt
	v_or_b32_e32 v116, s1, v47
	v_or_b32_e32 v114, s1, v45
	v_lshlrev_b32_e32 v112, 8, v114
	v_mov_b32_e32 v113, v5
	v_lshl_add_u64 v[112:113], v[100:101], 0, v[112:113]
	global_load_dword v136, v[112:113], off nt
	v_lshlrev_b32_e32 v113, 2, v114
	global_load_dword v137, v113, s[6:7] nt
	v_lshlrev_b32_e32 v112, 8, v116
	v_mov_b32_e32 v113, v5
	v_lshl_add_u64 v[112:113], v[100:101], 0, v[112:113]
	global_load_dword v138, v[112:113], off nt
	v_lshlrev_b32_e32 v113, 2, v116
	global_load_dword v139, v113, s[6:7] nt
	v_or_b32_e32 v116, s1, v53
	v_or_b32_e32 v114, s1, v49
	v_lshlrev_b32_e32 v112, 8, v114
	v_mov_b32_e32 v113, v5
	v_lshl_add_u64 v[112:113], v[100:101], 0, v[112:113]
	global_load_dword v140, v[112:113], off nt
	v_lshlrev_b32_e32 v113, 2, v114
	global_load_dword v141, v113, s[6:7] nt
	v_lshlrev_b32_e32 v112, 8, v116
	v_mov_b32_e32 v113, v5
	v_lshl_add_u64 v[112:113], v[100:101], 0, v[112:113]
	global_load_dword v142, v[112:113], off nt
	v_lshlrev_b32_e32 v113, 2, v116
	global_load_dword v143, v113, s[6:7] nt
	v_or_b32_e32 v116, s1, v57
	v_or_b32_e32 v114, s1, v55
	v_lshlrev_b32_e32 v112, 8, v114
	v_mov_b32_e32 v113, v5
	v_lshl_add_u64 v[112:113], v[100:101], 0, v[112:113]
	global_load_dword v144, v[112:113], off nt
	v_lshlrev_b32_e32 v113, 2, v114
	global_load_dword v145, v113, s[6:7] nt
	v_lshlrev_b32_e32 v112, 8, v116
	v_mov_b32_e32 v113, v5
	v_lshl_add_u64 v[112:113], v[100:101], 0, v[112:113]
	global_load_dword v146, v[112:113], off nt
	v_lshlrev_b32_e32 v113, 2, v116
	global_load_dword v148, v113, s[6:7] nt
	v_or_b32_e32 v116, s1, v61
	v_or_b32_e32 v114, s1, v59
	v_lshlrev_b32_e32 v112, 8, v114
	v_mov_b32_e32 v113, v5
	v_lshl_add_u64 v[112:113], v[100:101], 0, v[112:113]
	global_load_dword v150, v[112:113], off nt
	v_lshlrev_b32_e32 v113, 2, v114
	global_load_dword v151, v113, s[6:7] nt
	v_lshlrev_b32_e32 v112, 8, v116
	v_mov_b32_e32 v113, v5
	v_lshl_add_u64 v[112:113], v[100:101], 0, v[112:113]
	global_load_dword v152, v[112:113], off nt
	v_lshlrev_b32_e32 v113, 2, v116
	global_load_dword v153, v113, s[6:7] nt
	v_or_b32_e32 v116, s1, v67
	v_or_b32_e32 v114, s1, v63
	v_lshlrev_b32_e32 v112, 8, v114
	v_mov_b32_e32 v113, v5
	v_lshl_add_u64 v[112:113], v[100:101], 0, v[112:113]
	global_load_dword v154, v[112:113], off nt
	v_lshlrev_b32_e32 v113, 2, v114
	global_load_dword v155, v113, s[6:7] nt
	v_lshlrev_b32_e32 v112, 8, v116
	v_mov_b32_e32 v113, v5
	v_lshl_add_u64 v[112:113], v[100:101], 0, v[112:113]
	global_load_dword v156, v[112:113], off nt
	v_lshlrev_b32_e32 v113, 2, v116
	global_load_dword v157, v113, s[6:7] nt
	v_or_b32_e32 v116, s1, v71
	v_or_b32_e32 v114, s1, v69
	v_lshlrev_b32_e32 v112, 8, v114
	v_mov_b32_e32 v113, v5
	v_lshl_add_u64 v[112:113], v[100:101], 0, v[112:113]
	global_load_dword v158, v[112:113], off nt
	v_lshlrev_b32_e32 v113, 2, v114
	global_load_dword v159, v113, s[6:7] nt
	v_lshlrev_b32_e32 v112, 8, v116
	v_mov_b32_e32 v113, v5
	v_lshl_add_u64 v[112:113], v[100:101], 0, v[112:113]
	global_load_dword v160, v[112:113], off nt
	v_lshlrev_b32_e32 v113, 2, v116
	global_load_dword v161, v113, s[6:7] nt
	v_or_b32_e32 v116, s1, v83
	v_or_b32_e32 v114, s1, v73
	v_lshlrev_b32_e32 v112, 8, v114
	v_mov_b32_e32 v113, v5
	v_lshl_add_u64 v[112:113], v[100:101], 0, v[112:113]
	global_load_dword v162, v[112:113], off nt
	v_lshlrev_b32_e32 v113, 2, v114
	global_load_dword v163, v113, s[6:7] nt
	v_lshlrev_b32_e32 v112, 8, v116
	v_mov_b32_e32 v113, v5
	v_lshl_add_u64 v[112:113], v[100:101], 0, v[112:113]
	global_load_dword v164, v[112:113], off nt
	v_lshlrev_b32_e32 v113, 2, v116
	global_load_dword v165, v113, s[6:7] nt
	v_or_b32_e32 v116, s1, v87
	v_or_b32_e32 v114, s1, v85
	v_lshlrev_b32_e32 v112, 8, v114
	v_mov_b32_e32 v113, v5
	v_lshl_add_u64 v[112:113], v[100:101], 0, v[112:113]
	global_load_dword v166, v[112:113], off nt
	v_lshlrev_b32_e32 v113, 2, v114
	global_load_dword v168, v113, s[6:7] nt
	v_lshlrev_b32_e32 v112, 8, v116
	v_mov_b32_e32 v113, v5
	v_lshl_add_u64 v[112:113], v[100:101], 0, v[112:113]
	global_load_dword v170, v[112:113], off nt
	v_lshlrev_b32_e32 v113, 2, v116
	global_load_dword v171, v113, s[6:7] nt
	v_or_b32_e32 v116, s1, v91
	v_or_b32_e32 v114, s1, v89
	v_lshlrev_b32_e32 v112, 8, v114
	v_mov_b32_e32 v113, v5
	v_lshl_add_u64 v[112:113], v[100:101], 0, v[112:113]
	global_load_dword v172, v[112:113], off nt
	v_lshlrev_b32_e32 v113, 2, v114
	global_load_dword v173, v113, s[6:7] nt
	v_lshlrev_b32_e32 v112, 8, v116
	v_mov_b32_e32 v113, v5
	v_lshl_add_u64 v[112:113], v[100:101], 0, v[112:113]
	global_load_dword v174, v[112:113], off nt
	v_lshlrev_b32_e32 v113, 2, v116
	global_load_dword v176, v113, s[6:7] nt
	v_or_b32_e32 v116, s1, v95
	v_or_b32_e32 v114, s1, v93
	v_lshlrev_b32_e32 v112, 8, v114
	v_mov_b32_e32 v113, v5
	v_lshl_add_u64 v[112:113], v[100:101], 0, v[112:113]
	global_load_dword v177, v[112:113], off nt
	v_lshlrev_b32_e32 v113, 2, v114
	global_load_dword v178, v113, s[6:7] nt
	v_lshlrev_b32_e32 v112, 8, v116
	v_mov_b32_e32 v113, v5
	v_lshl_add_u64 v[112:113], v[100:101], 0, v[112:113]
	global_load_dword v179, v[112:113], off nt
	v_lshlrev_b32_e32 v113, 2, v116
	global_load_dword v180, v113, s[6:7] nt
	v_or_b32_e32 v116, s1, v99
	v_or_b32_e32 v114, s1, v97
	v_lshlrev_b32_e32 v112, 8, v114
	v_mov_b32_e32 v113, v5
	v_lshl_add_u64 v[112:113], v[100:101], 0, v[112:113]
	s_waitcnt vmcnt(16)
	global_load_dword v181, v[112:113], off nt
	v_lshlrev_b32_e32 v113, 2, v114
	global_load_dword v182, v113, s[6:7] nt
	v_lshlrev_b32_e32 v112, 8, v116
	v_mov_b32_e32 v113, v5
	v_lshl_add_u64 v[112:113], v[100:101], 0, v[112:113]
	global_load_dword v183, v[112:113], off nt
	v_lshlrev_b32_e32 v113, 2, v116
	global_load_dword v184, v113, s[6:7] nt
	v_or_b32_e32 v116, s1, v103
	v_or_b32_e32 v114, s1, v102
	v_lshlrev_b32_e32 v112, 8, v114
	v_mov_b32_e32 v113, v5
	v_lshl_add_u64 v[112:113], v[100:101], 0, v[112:113]
	global_load_dword v185, v[112:113], off nt
	v_lshlrev_b32_e32 v113, 2, v114
	global_load_dword v186, v113, s[6:7] nt
	v_lshlrev_b32_e32 v112, 8, v116
	v_mov_b32_e32 v113, v5
	v_lshl_add_u64 v[112:113], v[100:101], 0, v[112:113]
	global_load_dword v187, v[112:113], off nt
	v_lshlrev_b32_e32 v113, 2, v116
	global_load_dword v188, v113, s[6:7] nt
	v_or_b32_e32 v116, s1, v105
	v_or_b32_e32 v114, s1, v104
	v_lshlrev_b32_e32 v112, 8, v114
	v_mov_b32_e32 v113, v5
	v_lshl_add_u64 v[112:113], v[100:101], 0, v[112:113]
	global_load_dword v189, v[112:113], off nt
	v_lshlrev_b32_e32 v113, 2, v114
	global_load_dword v190, v113, s[6:7] nt
	v_lshlrev_b32_e32 v112, 8, v116
	v_mov_b32_e32 v113, v5
	v_lshl_add_u64 v[112:113], v[100:101], 0, v[112:113]
	global_load_dword v191, v[112:113], off nt
	v_lshlrev_b32_e32 v113, 2, v116
	global_load_dword v192, v113, s[6:7] nt
	v_or_b32_e32 v116, s1, v107
	v_or_b32_e32 v114, s1, v106
	v_lshlrev_b32_e32 v112, 8, v114
	v_mov_b32_e32 v113, v5
	v_lshl_add_u64 v[112:113], v[100:101], 0, v[112:113]
	global_load_dword v193, v[112:113], off nt
	v_lshlrev_b32_e32 v113, 2, v114
	global_load_dword v194, v113, s[6:7] nt
	v_lshlrev_b32_e32 v112, 8, v116
	v_mov_b32_e32 v113, v5
	v_lshl_add_u64 v[100:101], v[100:101], 0, v[112:113]
	global_load_dword v195, v[100:101], off nt
	v_lshlrev_b32_e32 v101, 2, v116
	global_load_dword v196, v101, s[6:7] nt
	s_waitcnt vmcnt(0)
	v_add_u32_e32 v115, v19, v37
	s_lshl_b32 s10, s1, 1
	v_sub_f32_e32 v113, 1.0, v128
	v_mul_f32_e32 v114, v125, v113
	v_sub_f32_e32 v113, 1.0, v131
	v_mul_f32_e32 v112, v130, v113
	ds_write2_b32 v115, v114, v112 offset1:66
	v_sub_f32_e32 v113, 1.0, v133
	v_mul_f32_e32 v114, v132, v113
	v_sub_f32_e32 v113, 1.0, v135
	v_mul_f32_e32 v112, v134, v113
	ds_write2_b32 v115, v114, v112 offset0:132 offset1:198
	v_sub_f32_e32 v113, 1.0, v137
	v_mul_f32_e32 v114, v136, v113
	v_sub_f32_e32 v113, 1.0, v139
	v_mul_f32_e32 v112, v138, v113
	v_add_u32_e32 v113, 0x400, v115
	ds_write2_b32 v113, v114, v112 offset0:8 offset1:74
	v_add_u32_e32 v115, v19, v51
	v_sub_f32_e32 v113, 1.0, v141
	v_mul_f32_e32 v114, v140, v113
	v_sub_f32_e32 v113, 1.0, v143
	v_mul_f32_e32 v112, v142, v113
	ds_write2_b32 v115, v114, v112 offset1:66
	v_sub_f32_e32 v113, 1.0, v145
	v_mul_f32_e32 v114, v144, v113
	v_sub_f32_e32 v113, 1.0, v148
	v_mul_f32_e32 v112, v146, v113
	ds_write2_b32 v115, v114, v112 offset0:132 offset1:198
	v_sub_f32_e32 v113, 1.0, v151
	v_mul_f32_e32 v114, v150, v113
	v_sub_f32_e32 v113, 1.0, v153
	v_mul_f32_e32 v112, v152, v113
	v_add_u32_e32 v113, 0x400, v115
	ds_write2_b32 v113, v114, v112 offset0:8 offset1:74
	v_add_u32_e32 v115, v19, v65
	v_sub_f32_e32 v113, 1.0, v155
	v_mul_f32_e32 v114, v154, v113
	v_sub_f32_e32 v113, 1.0, v157
	v_mul_f32_e32 v112, v156, v113
	ds_write2_b32 v115, v114, v112 offset1:66
	v_sub_f32_e32 v113, 1.0, v159
	v_mul_f32_e32 v114, v158, v113
	v_sub_f32_e32 v113, 1.0, v161
	v_mul_f32_e32 v112, v160, v113
	ds_write2_b32 v115, v114, v112 offset0:132 offset1:198
	v_sub_f32_e32 v113, 1.0, v163
	v_mul_f32_e32 v114, v162, v113
	v_sub_f32_e32 v113, 1.0, v165
	v_mul_f32_e32 v112, v164, v113
	v_add_u32_e32 v113, 0x400, v115
	ds_write2_b32 v113, v114, v112 offset0:8 offset1:74
	v_add_u32_e32 v115, v19, v75
	v_sub_f32_e32 v113, 1.0, v168
	v_mul_f32_e32 v114, v166, v113
	v_sub_f32_e32 v113, 1.0, v171
	v_mul_f32_e32 v112, v170, v113
	ds_write2_b32 v115, v114, v112 offset1:66
	v_sub_f32_e32 v113, 1.0, v173
	v_mul_f32_e32 v114, v172, v113
	v_sub_f32_e32 v113, 1.0, v176
	v_mul_f32_e32 v112, v174, v113
	ds_write2_b32 v115, v114, v112 offset0:132 offset1:198
	v_sub_f32_e32 v113, 1.0, v178
	v_mul_f32_e32 v114, v177, v113
	v_sub_f32_e32 v113, 1.0, v180
	v_mul_f32_e32 v112, v179, v113
	v_add_u32_e32 v113, 0x400, v115
	ds_write2_b32 v113, v114, v112 offset0:8 offset1:74
	v_add_u32_e32 v115, v19, v77
	v_sub_f32_e32 v113, 1.0, v182
	v_mul_f32_e32 v114, v181, v113
	v_sub_f32_e32 v113, 1.0, v184
	v_mul_f32_e32 v112, v183, v113
	ds_write2_b32 v115, v114, v112 offset1:66
	v_sub_f32_e32 v113, 1.0, v186
	v_mul_f32_e32 v114, v185, v113
	v_sub_f32_e32 v113, 1.0, v188
	v_mul_f32_e32 v112, v187, v113
	ds_write2_b32 v115, v114, v112 offset0:132 offset1:198
	v_add_u32_e32 v115, 0x400, v115
	v_sub_f32_e32 v113, 1.0, v190
	v_mul_f32_e32 v114, v189, v113
	v_sub_f32_e32 v113, 1.0, v192
	v_mul_f32_e32 v112, v191, v113
	ds_write2_b32 v115, v114, v112 offset0:8 offset1:74
	v_sub_f32_e32 v113, 1.0, v194
	v_mul_f32_e32 v114, v193, v113
	v_sub_f32_e32 v101, 1.0, v196
	v_mul_f32_e32 v100, v195, v101
	ds_write2_b32 v115, v114, v100 offset0:140 offset1:206
	s_waitcnt lgkmcnt(0)
	ds_read2_b32 v[112:113], v81 offset1:33
	s_waitcnt lgkmcnt(0)
	v_cvt_pk_bf16_f32 v112, v112, v113
	ds_read2_b32 v[114:115], v81 offset0:66 offset1:99
	s_waitcnt lgkmcnt(0)
	v_cvt_pk_bf16_f32 v113, v114, v115
	ds_read2_b32 v[114:115], v81 offset0:132 offset1:165
	s_waitcnt lgkmcnt(0)
	v_cvt_pk_bf16_f32 v114, v114, v115
	ds_read2_b32 v[116:117], v81 offset0:198 offset1:231
	s_waitcnt lgkmcnt(0)
	v_cvt_pk_bf16_f32 v115, v116, v117
	v_or_b32_e32 v116, s0, v79
	v_lshl_add_u64 v[100:101], v[32:33], 0, s[10:11]
	v_lshlrev_b32_e32 v116, 11, v116
	v_mov_b32_e32 v117, v5
	v_lshl_add_u64 v[116:117], v[100:101], 0, v[116:117]
	v_add_co_u32_e32 v116, vcc, s24, v116
	s_nop 1
	v_addc_co_u32_e32 v117, vcc, 0, v117, vcc
	global_store_dwordx4 v[116:117], v[112:115], off
	ds_read2_b32 v[112:113], v81 offset0:8 offset1:41
	s_waitcnt lgkmcnt(0)
	v_cvt_pk_bf16_f32 v112, v112, v113
	ds_read2_b32 v[114:115], v81 offset0:74 offset1:107
	s_waitcnt lgkmcnt(0)
	v_cvt_pk_bf16_f32 v113, v114, v115
	ds_read2_b32 v[114:115], v81 offset0:140 offset1:173
	s_waitcnt lgkmcnt(0)
	v_cvt_pk_bf16_f32 v114, v114, v115
	ds_read2_b32 v[116:117], v81 offset0:206 offset1:239
	s_waitcnt lgkmcnt(0)
	v_cvt_pk_bf16_f32 v115, v116, v117
	v_or_b32_e32 v116, s0, v108
	v_lshlrev_b32_e32 v116, 11, v116
	v_mov_b32_e32 v117, v5
	v_lshl_add_u64 v[116:117], v[100:101], 0, v[116:117]
	v_add_co_u32_e32 v116, vcc, s24, v116
	s_nop 1
	v_addc_co_u32_e32 v117, vcc, 0, v117, vcc
	global_store_dwordx4 v[116:117], v[112:115], off
	ds_read2_b32 v[112:113], v81 offset0:16 offset1:49
	s_waitcnt lgkmcnt(0)
	v_cvt_pk_bf16_f32 v112, v112, v113
	ds_read2_b32 v[114:115], v81 offset0:82 offset1:115
	s_waitcnt lgkmcnt(0)
	v_cvt_pk_bf16_f32 v113, v114, v115
	ds_read2_b32 v[114:115], v81 offset0:148 offset1:181
	s_waitcnt lgkmcnt(0)
	v_cvt_pk_bf16_f32 v114, v114, v115
	ds_read2_b32 v[116:117], v81 offset0:214 offset1:247
	s_waitcnt lgkmcnt(0)
	v_cvt_pk_bf16_f32 v115, v116, v117
	v_or_b32_e32 v116, s0, v109
	v_lshlrev_b32_e32 v116, 11, v116
	v_mov_b32_e32 v117, v5
	v_lshl_add_u64 v[116:117], v[100:101], 0, v[116:117]
	v_add_co_u32_e32 v116, vcc, s24, v116
	s_nop 1
	v_addc_co_u32_e32 v117, vcc, 0, v117, vcc
	global_store_dwordx4 v[116:117], v[112:115], off
	ds_read2_b32 v[112:113], v81 offset0:24 offset1:57
	s_waitcnt lgkmcnt(0)
	v_cvt_pk_bf16_f32 v112, v112, v113
	ds_read2_b32 v[114:115], v81 offset0:90 offset1:123
	s_waitcnt lgkmcnt(0)
	v_cvt_pk_bf16_f32 v113, v114, v115
	ds_read2_b32 v[114:115], v81 offset0:156 offset1:189
	s_waitcnt lgkmcnt(0)
	v_cvt_pk_bf16_f32 v114, v114, v115
	ds_read2_b32 v[116:117], v81 offset0:222 offset1:255
	s_waitcnt lgkmcnt(0)
	v_cvt_pk_bf16_f32 v115, v116, v117
	v_or_b32_e32 v116, s0, v110
	v_lshlrev_b32_e32 v116, 11, v116
	v_mov_b32_e32 v117, v5
	v_lshl_add_u64 v[100:101], v[100:101], 0, v[116:117]
	v_add_co_u32_e32 v100, vcc, 0x40000, v100
	s_nop 1
	v_addc_co_u32_e32 v101, vcc, 0, v101, vcc
	global_store_dwordx4 v[100:101], v[112:115], off
	s_waitcnt lgkmcnt(0)

.LBB0_38:
	s_andn2_b64 vcc, exec, s[0:1]
	s_cbranch_vccnz .LBB0_40
	s_add_i32 s0, s21, 0x1c00
	s_and_b32 s1, s0, 0x1fc0
	s_and_b32 s0, s21, 32
	s_lshl_b32 s10, s0, 2
	v_or_b32_e32 v114, s1, v3
	v_lshl_add_u64 v[100:101], v[30:31], 0, s[10:11]
	v_lshlrev_b32_e32 v112, 8, v114
	v_mov_b32_e32 v113, v5
	v_lshl_add_u64 v[112:113], v[100:101], 0, v[112:113]
	global_load_dword v125, v[112:113], off nt
	v_lshlrev_b32_e32 v113, 2, v114
	global_load_dword v128, v113, s[8:9] nt
	v_or_b32_e32 v116, s1, v39
	v_lshlrev_b32_e32 v112, 8, v116
	v_mov_b32_e32 v113, v5
	v_lshl_add_u64 v[112:113], v[100:101], 0, v[112:113]
	global_load_dword v130, v[112:113], off nt
	v_lshlrev_b32_e32 v113, 2, v116
	global_load_dword v131, v113, s[8:9] nt
	v_or_b32_e32 v116, s1, v43
	v_or_b32_e32 v114, s1, v41
	v_lshlrev_b32_e32 v112, 8, v114
	v_mov_b32_e32 v113, v5
	v_lshl_add_u64 v[112:113], v[100:101], 0, v[112:113]
	global_load_dword v132, v[112:113], off nt
	v_lshlrev_b32_e32 v113, 2, v114
	global_load_dword v133, v113, s[8:9] nt
	v_lshlrev_b32_e32 v112, 8, v116
	v_mov_b32_e32 v113, v5
	v_lshl_add_u64 v[112:113], v[100:101], 0, v[112:113]
	global_load_dword v134, v[112:113], off nt
	v_lshlrev_b32_e32 v113, 2, v116
	global_load_dword v135, v113, s[8:9] nt
	v_or_b32_e32 v116, s1, v47
	v_or_b32_e32 v114, s1, v45
	v_lshlrev_b32_e32 v112, 8, v114
	v_mov_b32_e32 v113, v5
	v_lshl_add_u64 v[112:113], v[100:101], 0, v[112:113]
	global_load_dword v136, v[112:113], off nt
	v_lshlrev_b32_e32 v113, 2, v114
	global_load_dword v137, v113, s[8:9] nt
	v_lshlrev_b32_e32 v112, 8, v116
	v_mov_b32_e32 v113, v5
	v_lshl_add_u64 v[112:113], v[100:101], 0, v[112:113]
	global_load_dword v138, v[112:113], off nt
	v_lshlrev_b32_e32 v113, 2, v116
	global_load_dword v139, v113, s[8:9] nt
	v_or_b32_e32 v116, s1, v53
	v_or_b32_e32 v114, s1, v49
	v_lshlrev_b32_e32 v112, 8, v114
	v_mov_b32_e32 v113, v5
	v_lshl_add_u64 v[112:113], v[100:101], 0, v[112:113]
	global_load_dword v140, v[112:113], off nt
	v_lshlrev_b32_e32 v113, 2, v114
	global_load_dword v141, v113, s[8:9] nt
	v_lshlrev_b32_e32 v112, 8, v116
	v_mov_b32_e32 v113, v5
	v_lshl_add_u64 v[112:113], v[100:101], 0, v[112:113]
	global_load_dword v142, v[112:113], off nt
	v_lshlrev_b32_e32 v113, 2, v116
	global_load_dword v143, v113, s[8:9] nt
	v_or_b32_e32 v116, s1, v57
	v_or_b32_e32 v114, s1, v55
	v_lshlrev_b32_e32 v112, 8, v114
	v_mov_b32_e32 v113, v5
	v_lshl_add_u64 v[112:113], v[100:101], 0, v[112:113]
	global_load_dword v144, v[112:113], off nt
	v_lshlrev_b32_e32 v113, 2, v114
	global_load_dword v145, v113, s[8:9] nt
	v_lshlrev_b32_e32 v112, 8, v116
	v_mov_b32_e32 v113, v5
	v_lshl_add_u64 v[112:113], v[100:101], 0, v[112:113]
	global_load_dword v146, v[112:113], off nt
	v_lshlrev_b32_e32 v113, 2, v116
	global_load_dword v148, v113, s[8:9] nt
	v_or_b32_e32 v116, s1, v61
	v_or_b32_e32 v114, s1, v59
	v_lshlrev_b32_e32 v112, 8, v114
	v_mov_b32_e32 v113, v5
	v_lshl_add_u64 v[112:113], v[100:101], 0, v[112:113]
	global_load_dword v150, v[112:113], off nt
	v_lshlrev_b32_e32 v113, 2, v114
	global_load_dword v151, v113, s[8:9] nt
	v_lshlrev_b32_e32 v112, 8, v116
	v_mov_b32_e32 v113, v5
	v_lshl_add_u64 v[112:113], v[100:101], 0, v[112:113]
	global_load_dword v152, v[112:113], off nt
	v_lshlrev_b32_e32 v113, 2, v116
	global_load_dword v153, v113, s[8:9] nt
	v_or_b32_e32 v116, s1, v67
	v_or_b32_e32 v114, s1, v63
	v_lshlrev_b32_e32 v112, 8, v114
	v_mov_b32_e32 v113, v5
	v_lshl_add_u64 v[112:113], v[100:101], 0, v[112:113]
	global_load_dword v154, v[112:113], off nt
	v_lshlrev_b32_e32 v113, 2, v114
	global_load_dword v155, v113, s[8:9] nt
	v_lshlrev_b32_e32 v112, 8, v116
	v_mov_b32_e32 v113, v5
	v_lshl_add_u64 v[112:113], v[100:101], 0, v[112:113]
	global_load_dword v156, v[112:113], off nt
	v_lshlrev_b32_e32 v113, 2, v116
	global_load_dword v157, v113, s[8:9] nt
	v_or_b32_e32 v116, s1, v71
	v_or_b32_e32 v114, s1, v69
	v_lshlrev_b32_e32 v112, 8, v114
	v_mov_b32_e32 v113, v5
	v_lshl_add_u64 v[112:113], v[100:101], 0, v[112:113]
	global_load_dword v158, v[112:113], off nt
	v_lshlrev_b32_e32 v113, 2, v114
	global_load_dword v159, v113, s[8:9] nt
	v_lshlrev_b32_e32 v112, 8, v116
	v_mov_b32_e32 v113, v5
	v_lshl_add_u64 v[112:113], v[100:101], 0, v[112:113]
	global_load_dword v160, v[112:113], off nt
	v_lshlrev_b32_e32 v113, 2, v116
	global_load_dword v161, v113, s[8:9] nt
	v_or_b32_e32 v116, s1, v83
	v_or_b32_e32 v114, s1, v73
	v_lshlrev_b32_e32 v112, 8, v114
	v_mov_b32_e32 v113, v5
	v_lshl_add_u64 v[112:113], v[100:101], 0, v[112:113]
	global_load_dword v162, v[112:113], off nt
	v_lshlrev_b32_e32 v113, 2, v114
	global_load_dword v163, v113, s[8:9] nt
	v_lshlrev_b32_e32 v112, 8, v116
	v_mov_b32_e32 v113, v5
	v_lshl_add_u64 v[112:113], v[100:101], 0, v[112:113]
	global_load_dword v164, v[112:113], off nt
	v_lshlrev_b32_e32 v113, 2, v116
	global_load_dword v165, v113, s[8:9] nt
	v_or_b32_e32 v116, s1, v87
	v_or_b32_e32 v114, s1, v85
	v_lshlrev_b32_e32 v112, 8, v114
	v_mov_b32_e32 v113, v5
	v_lshl_add_u64 v[112:113], v[100:101], 0, v[112:113]
	global_load_dword v166, v[112:113], off nt
	v_lshlrev_b32_e32 v113, 2, v114
	global_load_dword v168, v113, s[8:9] nt
	v_lshlrev_b32_e32 v112, 8, v116
	v_mov_b32_e32 v113, v5
	v_lshl_add_u64 v[112:113], v[100:101], 0, v[112:113]
	global_load_dword v170, v[112:113], off nt
	v_lshlrev_b32_e32 v113, 2, v116
	global_load_dword v171, v113, s[8:9] nt
	v_or_b32_e32 v116, s1, v91
	v_or_b32_e32 v114, s1, v89
	v_lshlrev_b32_e32 v112, 8, v114
	v_mov_b32_e32 v113, v5
	v_lshl_add_u64 v[112:113], v[100:101], 0, v[112:113]
	global_load_dword v172, v[112:113], off nt
	v_lshlrev_b32_e32 v113, 2, v114
	global_load_dword v173, v113, s[8:9] nt
	v_lshlrev_b32_e32 v112, 8, v116
	v_mov_b32_e32 v113, v5
	v_lshl_add_u64 v[112:113], v[100:101], 0, v[112:113]
	global_load_dword v174, v[112:113], off nt
	v_lshlrev_b32_e32 v113, 2, v116
	global_load_dword v176, v113, s[8:9] nt
	v_or_b32_e32 v116, s1, v95
	v_or_b32_e32 v114, s1, v93
	v_lshlrev_b32_e32 v112, 8, v114
	v_mov_b32_e32 v113, v5
	v_lshl_add_u64 v[112:113], v[100:101], 0, v[112:113]
	global_load_dword v177, v[112:113], off nt
	v_lshlrev_b32_e32 v113, 2, v114
	global_load_dword v178, v113, s[8:9] nt
	v_lshlrev_b32_e32 v112, 8, v116
	v_mov_b32_e32 v113, v5
	v_lshl_add_u64 v[112:113], v[100:101], 0, v[112:113]
	global_load_dword v179, v[112:113], off nt
	v_lshlrev_b32_e32 v113, 2, v116
	global_load_dword v180, v113, s[8:9] nt
	v_or_b32_e32 v116, s1, v99
	v_or_b32_e32 v114, s1, v97
	v_lshlrev_b32_e32 v112, 8, v114
	v_mov_b32_e32 v113, v5
	v_lshl_add_u64 v[112:113], v[100:101], 0, v[112:113]
	s_waitcnt vmcnt(16)
	global_load_dword v181, v[112:113], off nt
	v_lshlrev_b32_e32 v113, 2, v114
	global_load_dword v182, v113, s[8:9] nt
	v_lshlrev_b32_e32 v112, 8, v116
	v_mov_b32_e32 v113, v5
	v_lshl_add_u64 v[112:113], v[100:101], 0, v[112:113]
	global_load_dword v183, v[112:113], off nt
	v_lshlrev_b32_e32 v113, 2, v116
	global_load_dword v184, v113, s[8:9] nt
	v_or_b32_e32 v116, s1, v103
	v_or_b32_e32 v114, s1, v102
	v_lshlrev_b32_e32 v112, 8, v114
	v_mov_b32_e32 v113, v5
	v_lshl_add_u64 v[112:113], v[100:101], 0, v[112:113]
	global_load_dword v185, v[112:113], off nt
	v_lshlrev_b32_e32 v113, 2, v114
	global_load_dword v186, v113, s[8:9] nt
	v_lshlrev_b32_e32 v112, 8, v116
	v_mov_b32_e32 v113, v5
	v_lshl_add_u64 v[112:113], v[100:101], 0, v[112:113]
	global_load_dword v187, v[112:113], off nt
	v_lshlrev_b32_e32 v113, 2, v116
	global_load_dword v188, v113, s[8:9] nt
	v_or_b32_e32 v116, s1, v105
	v_or_b32_e32 v114, s1, v104
	v_lshlrev_b32_e32 v112, 8, v114
	v_mov_b32_e32 v113, v5
	v_lshl_add_u64 v[112:113], v[100:101], 0, v[112:113]
	global_load_dword v189, v[112:113], off nt
	v_lshlrev_b32_e32 v113, 2, v114
	global_load_dword v190, v113, s[8:9] nt
	v_lshlrev_b32_e32 v112, 8, v116
	v_mov_b32_e32 v113, v5
	v_lshl_add_u64 v[112:113], v[100:101], 0, v[112:113]
	global_load_dword v191, v[112:113], off nt
	v_lshlrev_b32_e32 v113, 2, v116
	global_load_dword v192, v113, s[8:9] nt
	v_or_b32_e32 v116, s1, v107
	v_or_b32_e32 v114, s1, v106
	v_lshlrev_b32_e32 v112, 8, v114
	v_mov_b32_e32 v113, v5
	v_lshl_add_u64 v[112:113], v[100:101], 0, v[112:113]
	global_load_dword v193, v[112:113], off nt
	v_lshlrev_b32_e32 v113, 2, v114
	global_load_dword v194, v113, s[8:9] nt
	v_lshlrev_b32_e32 v112, 8, v116
	v_mov_b32_e32 v113, v5
	v_lshl_add_u64 v[100:101], v[100:101], 0, v[112:113]
	global_load_dword v195, v[100:101], off nt
	v_lshlrev_b32_e32 v101, 2, v116
	global_load_dword v196, v101, s[8:9] nt
	s_waitcnt vmcnt(0)
	v_add_u32_e32 v115, v19, v37
	s_lshl_b32 s10, s1, 1
	v_mul_f32_e32 v114, v125, v128
	v_mul_f32_e32 v112, v130, v131
	ds_write2_b32 v115, v114, v112 offset1:66
	v_mul_f32_e32 v114, v132, v133
	v_mul_f32_e32 v112, v134, v135
	ds_write2_b32 v115, v114, v112 offset0:132 offset1:198
	v_mul_f32_e32 v114, v136, v137
	v_mul_f32_e32 v112, v138, v139
	v_add_u32_e32 v113, 0x400, v115
	ds_write2_b32 v113, v114, v112 offset0:8 offset1:74
	v_add_u32_e32 v115, v19, v51
	v_mul_f32_e32 v114, v140, v141
	v_mul_f32_e32 v112, v142, v143
	ds_write2_b32 v115, v114, v112 offset1:66
	v_mul_f32_e32 v114, v144, v145
	v_mul_f32_e32 v112, v146, v148
	ds_write2_b32 v115, v114, v112 offset0:132 offset1:198
	v_mul_f32_e32 v114, v150, v151
	v_mul_f32_e32 v112, v152, v153
	v_add_u32_e32 v113, 0x400, v115
	ds_write2_b32 v113, v114, v112 offset0:8 offset1:74
	v_add_u32_e32 v115, v19, v65
	v_mul_f32_e32 v114, v154, v155
	v_mul_f32_e32 v112, v156, v157
	ds_write2_b32 v115, v114, v112 offset1:66
	v_mul_f32_e32 v114, v158, v159
	v_mul_f32_e32 v112, v160, v161
	ds_write2_b32 v115, v114, v112 offset0:132 offset1:198
	v_mul_f32_e32 v114, v162, v163
	v_mul_f32_e32 v112, v164, v165
	v_add_u32_e32 v113, 0x400, v115
	ds_write2_b32 v113, v114, v112 offset0:8 offset1:74
	v_add_u32_e32 v115, v19, v75
	v_mul_f32_e32 v114, v166, v168
	v_mul_f32_e32 v112, v170, v171
	ds_write2_b32 v115, v114, v112 offset1:66
	v_mul_f32_e32 v114, v172, v173
	v_mul_f32_e32 v112, v174, v176
	ds_write2_b32 v115, v114, v112 offset0:132 offset1:198
	v_mul_f32_e32 v114, v177, v178
	v_mul_f32_e32 v112, v179, v180
	v_add_u32_e32 v113, 0x400, v115
	ds_write2_b32 v113, v114, v112 offset0:8 offset1:74
	v_add_u32_e32 v115, v19, v77
	v_mul_f32_e32 v114, v181, v182
	v_mul_f32_e32 v112, v183, v184
	ds_write2_b32 v115, v114, v112 offset1:66
	v_mul_f32_e32 v114, v185, v186
	v_mul_f32_e32 v112, v187, v188
	ds_write2_b32 v115, v114, v112 offset0:132 offset1:198
	v_add_u32_e32 v115, 0x400, v115
	v_mul_f32_e32 v114, v189, v190
	v_mul_f32_e32 v112, v191, v192
	ds_write2_b32 v115, v114, v112 offset0:8 offset1:74
	v_mul_f32_e32 v114, v193, v194
	v_mul_f32_e32 v100, v195, v196
	ds_write2_b32 v115, v114, v100 offset0:140 offset1:206
	s_waitcnt lgkmcnt(0)
	ds_read2_b32 v[112:113], v81 offset1:33
	s_waitcnt lgkmcnt(0)
	v_cvt_pk_bf16_f32 v112, v112, v113
	ds_read2_b32 v[114:115], v81 offset0:66 offset1:99
	s_waitcnt lgkmcnt(0)
	v_cvt_pk_bf16_f32 v113, v114, v115
	ds_read2_b32 v[114:115], v81 offset0:132 offset1:165
	s_waitcnt lgkmcnt(0)
	v_cvt_pk_bf16_f32 v114, v114, v115
	ds_read2_b32 v[116:117], v81 offset0:198 offset1:231
	s_waitcnt lgkmcnt(0)
	v_cvt_pk_bf16_f32 v115, v116, v117
	v_or_b32_e32 v116, s0, v79
	v_lshl_add_u64 v[100:101], v[32:33], 0, s[10:11]
	v_lshlrev_b32_e32 v116, 11, v116
	v_mov_b32_e32 v117, v5
	v_lshl_add_u64 v[116:117], v[100:101], 0, v[116:117]
	v_add_co_u32_e32 v116, vcc, s25, v116
	s_nop 1
	v_addc_co_u32_e32 v117, vcc, 0, v117, vcc
	global_store_dwordx4 v[116:117], v[112:115], off
	ds_read2_b32 v[112:113], v81 offset0:8 offset1:41
	s_waitcnt lgkmcnt(0)
	v_cvt_pk_bf16_f32 v112, v112, v113
	ds_read2_b32 v[114:115], v81 offset0:74 offset1:107
	s_waitcnt lgkmcnt(0)
	v_cvt_pk_bf16_f32 v113, v114, v115
	ds_read2_b32 v[114:115], v81 offset0:140 offset1:173
	s_waitcnt lgkmcnt(0)
	v_cvt_pk_bf16_f32 v114, v114, v115
	ds_read2_b32 v[116:117], v81 offset0:206 offset1:239
	s_waitcnt lgkmcnt(0)
	v_cvt_pk_bf16_f32 v115, v116, v117
	v_or_b32_e32 v116, s0, v108
	v_lshlrev_b32_e32 v116, 11, v116
	v_mov_b32_e32 v117, v5
	v_lshl_add_u64 v[116:117], v[100:101], 0, v[116:117]
	v_add_co_u32_e32 v116, vcc, s25, v116
	s_nop 1
	v_addc_co_u32_e32 v117, vcc, 0, v117, vcc
	global_store_dwordx4 v[116:117], v[112:115], off
	ds_read2_b32 v[112:113], v81 offset0:16 offset1:49
	s_waitcnt lgkmcnt(0)
	v_cvt_pk_bf16_f32 v112, v112, v113
	ds_read2_b32 v[114:115], v81 offset0:82 offset1:115
	s_waitcnt lgkmcnt(0)
	v_cvt_pk_bf16_f32 v113, v114, v115
	ds_read2_b32 v[114:115], v81 offset0:148 offset1:181
	s_waitcnt lgkmcnt(0)
	v_cvt_pk_bf16_f32 v114, v114, v115
	ds_read2_b32 v[116:117], v81 offset0:214 offset1:247
	s_waitcnt lgkmcnt(0)
	v_cvt_pk_bf16_f32 v115, v116, v117
	v_or_b32_e32 v116, s0, v109
	v_lshlrev_b32_e32 v116, 11, v116
	v_mov_b32_e32 v117, v5
	v_lshl_add_u64 v[116:117], v[100:101], 0, v[116:117]
	v_add_co_u32_e32 v116, vcc, s25, v116
	s_nop 1
	v_addc_co_u32_e32 v117, vcc, 0, v117, vcc
	global_store_dwordx4 v[116:117], v[112:115], off
	ds_read2_b32 v[112:113], v81 offset0:24 offset1:57
	s_waitcnt lgkmcnt(0)
	v_cvt_pk_bf16_f32 v112, v112, v113
	ds_read2_b32 v[114:115], v81 offset0:90 offset1:123
	s_waitcnt lgkmcnt(0)
	v_cvt_pk_bf16_f32 v113, v114, v115
	ds_read2_b32 v[114:115], v81 offset0:156 offset1:189
	s_waitcnt lgkmcnt(0)
	v_cvt_pk_bf16_f32 v114, v114, v115
	ds_read2_b32 v[116:117], v81 offset0:222 offset1:255
	s_waitcnt lgkmcnt(0)
	v_cvt_pk_bf16_f32 v115, v116, v117
	v_or_b32_e32 v116, s0, v110
	v_lshlrev_b32_e32 v116, 11, v116
	v_mov_b32_e32 v117, v5
	v_lshl_add_u64 v[100:101], v[100:101], 0, v[116:117]
	v_add_co_u32_e32 v100, vcc, 0x20000, v100
	s_nop 1
	v_addc_co_u32_e32 v101, vcc, 0, v101, vcc
	global_store_dwordx4 v[100:101], v[112:115], off
	s_waitcnt lgkmcnt(0)

.LBB0_41:
	s_andn2_b64 vcc, exec, s[0:1]
	s_cbranch_vccnz .LBB0_43
	s_and_b32 s1, s21, 0x1fc0
	s_and_b32 s0, s21, 32
	s_lshl_b32 s10, s0, 2
	v_or_b32_e32 v114, s1, v3
	v_lshl_add_u64 v[100:101], v[30:31], 0, s[10:11]
	v_lshlrev_b32_e32 v112, 8, v114
	v_mov_b32_e32 v113, v5
	v_lshl_add_u64 v[112:113], v[100:101], 0, v[112:113]
	global_load_dword v125, v[112:113], off nt
	v_lshlrev_b32_e32 v113, 2, v114
	global_load_dword v128, v113, s[8:9] nt
	v_or_b32_e32 v116, s1, v39
	v_lshlrev_b32_e32 v112, 8, v116
	v_mov_b32_e32 v113, v5
	v_lshl_add_u64 v[112:113], v[100:101], 0, v[112:113]
	global_load_dword v130, v[112:113], off nt
	v_lshlrev_b32_e32 v113, 2, v116
	global_load_dword v131, v113, s[8:9] nt
	v_or_b32_e32 v116, s1, v43
	v_or_b32_e32 v114, s1, v41
	v_lshlrev_b32_e32 v112, 8, v114
	v_mov_b32_e32 v113, v5
	v_lshl_add_u64 v[112:113], v[100:101], 0, v[112:113]
	global_load_dword v132, v[112:113], off nt
	v_lshlrev_b32_e32 v113, 2, v114
	global_load_dword v133, v113, s[8:9] nt
	v_lshlrev_b32_e32 v112, 8, v116
	v_mov_b32_e32 v113, v5
	v_lshl_add_u64 v[112:113], v[100:101], 0, v[112:113]
	global_load_dword v134, v[112:113], off nt
	v_lshlrev_b32_e32 v113, 2, v116
	global_load_dword v135, v113, s[8:9] nt
	v_or_b32_e32 v116, s1, v47
	v_or_b32_e32 v114, s1, v45
	v_lshlrev_b32_e32 v112, 8, v114
	v_mov_b32_e32 v113, v5
	v_lshl_add_u64 v[112:113], v[100:101], 0, v[112:113]
	global_load_dword v136, v[112:113], off nt
	v_lshlrev_b32_e32 v113, 2, v114
	global_load_dword v137, v113, s[8:9] nt
	v_lshlrev_b32_e32 v112, 8, v116
	v_mov_b32_e32 v113, v5
	v_lshl_add_u64 v[112:113], v[100:101], 0, v[112:113]
	global_load_dword v138, v[112:113], off nt
	v_lshlrev_b32_e32 v113, 2, v116
	global_load_dword v139, v113, s[8:9] nt
	v_or_b32_e32 v116, s1, v53
	v_or_b32_e32 v114, s1, v49
	v_lshlrev_b32_e32 v112, 8, v114
	v_mov_b32_e32 v113, v5
	v_lshl_add_u64 v[112:113], v[100:101], 0, v[112:113]
	global_load_dword v140, v[112:113], off nt
	v_lshlrev_b32_e32 v113, 2, v114
	global_load_dword v141, v113, s[8:9] nt
	v_lshlrev_b32_e32 v112, 8, v116
	v_mov_b32_e32 v113, v5
	v_lshl_add_u64 v[112:113], v[100:101], 0, v[112:113]
	global_load_dword v142, v[112:113], off nt
	v_lshlrev_b32_e32 v113, 2, v116
	global_load_dword v143, v113, s[8:9] nt
	v_or_b32_e32 v116, s1, v57
	v_or_b32_e32 v114, s1, v55
	v_lshlrev_b32_e32 v112, 8, v114
	v_mov_b32_e32 v113, v5
	v_lshl_add_u64 v[112:113], v[100:101], 0, v[112:113]
	global_load_dword v144, v[112:113], off nt
	v_lshlrev_b32_e32 v113, 2, v114
	global_load_dword v145, v113, s[8:9] nt
	v_lshlrev_b32_e32 v112, 8, v116
	v_mov_b32_e32 v113, v5
	v_lshl_add_u64 v[112:113], v[100:101], 0, v[112:113]
	global_load_dword v146, v[112:113], off nt
	v_lshlrev_b32_e32 v113, 2, v116
	global_load_dword v148, v113, s[8:9] nt
	v_or_b32_e32 v116, s1, v61
	v_or_b32_e32 v114, s1, v59
	v_lshlrev_b32_e32 v112, 8, v114
	v_mov_b32_e32 v113, v5
	v_lshl_add_u64 v[112:113], v[100:101], 0, v[112:113]
	global_load_dword v150, v[112:113], off nt
	v_lshlrev_b32_e32 v113, 2, v114
	global_load_dword v151, v113, s[8:9] nt
	v_lshlrev_b32_e32 v112, 8, v116
	v_mov_b32_e32 v113, v5
	v_lshl_add_u64 v[112:113], v[100:101], 0, v[112:113]
	global_load_dword v152, v[112:113], off nt
	v_lshlrev_b32_e32 v113, 2, v116
	global_load_dword v153, v113, s[8:9] nt
	v_or_b32_e32 v116, s1, v67
	v_or_b32_e32 v114, s1, v63
	v_lshlrev_b32_e32 v112, 8, v114
	v_mov_b32_e32 v113, v5
	v_lshl_add_u64 v[112:113], v[100:101], 0, v[112:113]
	global_load_dword v154, v[112:113], off nt
	v_lshlrev_b32_e32 v113, 2, v114
	global_load_dword v155, v113, s[8:9] nt
	v_lshlrev_b32_e32 v112, 8, v116
	v_mov_b32_e32 v113, v5
	v_lshl_add_u64 v[112:113], v[100:101], 0, v[112:113]
	global_load_dword v156, v[112:113], off nt
	v_lshlrev_b32_e32 v113, 2, v116
	global_load_dword v157, v113, s[8:9] nt
	v_or_b32_e32 v116, s1, v71
	v_or_b32_e32 v114, s1, v69
	v_lshlrev_b32_e32 v112, 8, v114
	v_mov_b32_e32 v113, v5
	v_lshl_add_u64 v[112:113], v[100:101], 0, v[112:113]
	global_load_dword v158, v[112:113], off nt
	v_lshlrev_b32_e32 v113, 2, v114
	global_load_dword v159, v113, s[8:9] nt
	v_lshlrev_b32_e32 v112, 8, v116
	v_mov_b32_e32 v113, v5
	v_lshl_add_u64 v[112:113], v[100:101], 0, v[112:113]
	global_load_dword v160, v[112:113], off nt
	v_lshlrev_b32_e32 v113, 2, v116
	global_load_dword v161, v113, s[8:9] nt
	v_or_b32_e32 v116, s1, v83
	v_or_b32_e32 v114, s1, v73
	v_lshlrev_b32_e32 v112, 8, v114
	v_mov_b32_e32 v113, v5
	v_lshl_add_u64 v[112:113], v[100:101], 0, v[112:113]
	global_load_dword v162, v[112:113], off nt
	v_lshlrev_b32_e32 v113, 2, v114
	global_load_dword v163, v113, s[8:9] nt
	v_lshlrev_b32_e32 v112, 8, v116
	v_mov_b32_e32 v113, v5
	v_lshl_add_u64 v[112:113], v[100:101], 0, v[112:113]
	global_load_dword v164, v[112:113], off nt
	v_lshlrev_b32_e32 v113, 2, v116
	global_load_dword v165, v113, s[8:9] nt
	v_or_b32_e32 v116, s1, v87
	v_or_b32_e32 v114, s1, v85
	v_lshlrev_b32_e32 v112, 8, v114
	v_mov_b32_e32 v113, v5
	v_lshl_add_u64 v[112:113], v[100:101], 0, v[112:113]
	global_load_dword v166, v[112:113], off nt
	v_lshlrev_b32_e32 v113, 2, v114
	global_load_dword v168, v113, s[8:9] nt
	v_lshlrev_b32_e32 v112, 8, v116
	v_mov_b32_e32 v113, v5
	v_lshl_add_u64 v[112:113], v[100:101], 0, v[112:113]
	global_load_dword v170, v[112:113], off nt
	v_lshlrev_b32_e32 v113, 2, v116
	global_load_dword v171, v113, s[8:9] nt
	v_or_b32_e32 v116, s1, v91
	v_or_b32_e32 v114, s1, v89
	v_lshlrev_b32_e32 v112, 8, v114
	v_mov_b32_e32 v113, v5
	v_lshl_add_u64 v[112:113], v[100:101], 0, v[112:113]
	global_load_dword v172, v[112:113], off nt
	v_lshlrev_b32_e32 v113, 2, v114
	global_load_dword v173, v113, s[8:9] nt
	v_lshlrev_b32_e32 v112, 8, v116
	v_mov_b32_e32 v113, v5
	v_lshl_add_u64 v[112:113], v[100:101], 0, v[112:113]
	global_load_dword v174, v[112:113], off nt
	v_lshlrev_b32_e32 v113, 2, v116
	global_load_dword v176, v113, s[8:9] nt
	v_or_b32_e32 v116, s1, v95
	v_or_b32_e32 v114, s1, v93
	v_lshlrev_b32_e32 v112, 8, v114
	v_mov_b32_e32 v113, v5
	v_lshl_add_u64 v[112:113], v[100:101], 0, v[112:113]
	global_load_dword v177, v[112:113], off nt
	v_lshlrev_b32_e32 v113, 2, v114
	global_load_dword v178, v113, s[8:9] nt
	v_lshlrev_b32_e32 v112, 8, v116
	v_mov_b32_e32 v113, v5
	v_lshl_add_u64 v[112:113], v[100:101], 0, v[112:113]
	global_load_dword v179, v[112:113], off nt
	v_lshlrev_b32_e32 v113, 2, v116
	global_load_dword v180, v113, s[8:9] nt
	v_or_b32_e32 v116, s1, v99
	v_or_b32_e32 v114, s1, v97
	v_lshlrev_b32_e32 v112, 8, v114
	v_mov_b32_e32 v113, v5
	v_lshl_add_u64 v[112:113], v[100:101], 0, v[112:113]
	s_waitcnt vmcnt(16)
	global_load_dword v181, v[112:113], off nt
	v_lshlrev_b32_e32 v113, 2, v114
	global_load_dword v182, v113, s[8:9] nt
	v_lshlrev_b32_e32 v112, 8, v116
	v_mov_b32_e32 v113, v5
	v_lshl_add_u64 v[112:113], v[100:101], 0, v[112:113]
	global_load_dword v183, v[112:113], off nt
	v_lshlrev_b32_e32 v113, 2, v116
	global_load_dword v184, v113, s[8:9] nt
	v_or_b32_e32 v116, s1, v103
	v_or_b32_e32 v114, s1, v102
	v_lshlrev_b32_e32 v112, 8, v114
	v_mov_b32_e32 v113, v5
	v_lshl_add_u64 v[112:113], v[100:101], 0, v[112:113]
	global_load_dword v185, v[112:113], off nt
	v_lshlrev_b32_e32 v113, 2, v114
	global_load_dword v186, v113, s[8:9] nt
	v_lshlrev_b32_e32 v112, 8, v116
	v_mov_b32_e32 v113, v5
	v_lshl_add_u64 v[112:113], v[100:101], 0, v[112:113]
	global_load_dword v187, v[112:113], off nt
	v_lshlrev_b32_e32 v113, 2, v116
	global_load_dword v188, v113, s[8:9] nt
	v_or_b32_e32 v116, s1, v105
	v_or_b32_e32 v114, s1, v104
	v_lshlrev_b32_e32 v112, 8, v114
	v_mov_b32_e32 v113, v5
	v_lshl_add_u64 v[112:113], v[100:101], 0, v[112:113]
	global_load_dword v189, v[112:113], off nt
	v_lshlrev_b32_e32 v113, 2, v114
	global_load_dword v190, v113, s[8:9] nt
	v_lshlrev_b32_e32 v112, 8, v116
	v_mov_b32_e32 v113, v5
	v_lshl_add_u64 v[112:113], v[100:101], 0, v[112:113]
	global_load_dword v191, v[112:113], off nt
	v_lshlrev_b32_e32 v113, 2, v116
	global_load_dword v192, v113, s[8:9] nt
	v_or_b32_e32 v116, s1, v107
	v_or_b32_e32 v114, s1, v106
	v_lshlrev_b32_e32 v112, 8, v114
	v_mov_b32_e32 v113, v5
	v_lshl_add_u64 v[112:113], v[100:101], 0, v[112:113]
	global_load_dword v193, v[112:113], off nt
	v_lshlrev_b32_e32 v113, 2, v114
	global_load_dword v194, v113, s[8:9] nt
	v_lshlrev_b32_e32 v112, 8, v116
	v_mov_b32_e32 v113, v5
	v_lshl_add_u64 v[100:101], v[100:101], 0, v[112:113]
	global_load_dword v195, v[100:101], off nt
	v_lshlrev_b32_e32 v101, 2, v116
	global_load_dword v196, v101, s[8:9] nt
	s_waitcnt vmcnt(0)
	v_add_u32_e32 v115, v19, v37
	s_lshl_b32 s10, s1, 1
	v_sub_f32_e32 v113, 1.0, v128
	v_mul_f32_e32 v114, v125, v113
	v_sub_f32_e32 v113, 1.0, v131
	v_mul_f32_e32 v112, v130, v113
	ds_write2_b32 v115, v114, v112 offset1:66
	v_sub_f32_e32 v113, 1.0, v133
	v_mul_f32_e32 v114, v132, v113
	v_sub_f32_e32 v113, 1.0, v135
	v_mul_f32_e32 v112, v134, v113
	ds_write2_b32 v115, v114, v112 offset0:132 offset1:198
	v_sub_f32_e32 v113, 1.0, v137
	v_mul_f32_e32 v114, v136, v113
	v_sub_f32_e32 v113, 1.0, v139
	v_mul_f32_e32 v112, v138, v113
	v_add_u32_e32 v113, 0x400, v115
	ds_write2_b32 v113, v114, v112 offset0:8 offset1:74
	v_add_u32_e32 v115, v19, v51
	v_sub_f32_e32 v113, 1.0, v141
	v_mul_f32_e32 v114, v140, v113
	v_sub_f32_e32 v113, 1.0, v143
	v_mul_f32_e32 v112, v142, v113
	ds_write2_b32 v115, v114, v112 offset1:66
	v_sub_f32_e32 v113, 1.0, v145
	v_mul_f32_e32 v114, v144, v113
	v_sub_f32_e32 v113, 1.0, v148
	v_mul_f32_e32 v112, v146, v113
	ds_write2_b32 v115, v114, v112 offset0:132 offset1:198
	v_sub_f32_e32 v113, 1.0, v151
	v_mul_f32_e32 v114, v150, v113
	v_sub_f32_e32 v113, 1.0, v153
	v_mul_f32_e32 v112, v152, v113
	v_add_u32_e32 v113, 0x400, v115
	ds_write2_b32 v113, v114, v112 offset0:8 offset1:74
	v_add_u32_e32 v115, v19, v65
	v_sub_f32_e32 v113, 1.0, v155
	v_mul_f32_e32 v114, v154, v113
	v_sub_f32_e32 v113, 1.0, v157
	v_mul_f32_e32 v112, v156, v113
	ds_write2_b32 v115, v114, v112 offset1:66
	v_sub_f32_e32 v113, 1.0, v159
	v_mul_f32_e32 v114, v158, v113
	v_sub_f32_e32 v113, 1.0, v161
	v_mul_f32_e32 v112, v160, v113
	ds_write2_b32 v115, v114, v112 offset0:132 offset1:198
	v_sub_f32_e32 v113, 1.0, v163
	v_mul_f32_e32 v114, v162, v113
	v_sub_f32_e32 v113, 1.0, v165
	v_mul_f32_e32 v112, v164, v113
	v_add_u32_e32 v113, 0x400, v115
	ds_write2_b32 v113, v114, v112 offset0:8 offset1:74
	v_add_u32_e32 v115, v19, v75
	v_sub_f32_e32 v113, 1.0, v168
	v_mul_f32_e32 v114, v166, v113
	v_sub_f32_e32 v113, 1.0, v171
	v_mul_f32_e32 v112, v170, v113
	ds_write2_b32 v115, v114, v112 offset1:66
	v_sub_f32_e32 v113, 1.0, v173
	v_mul_f32_e32 v114, v172, v113
	v_sub_f32_e32 v113, 1.0, v176
	v_mul_f32_e32 v112, v174, v113
	ds_write2_b32 v115, v114, v112 offset0:132 offset1:198
	v_sub_f32_e32 v113, 1.0, v178
	v_mul_f32_e32 v114, v177, v113
	v_sub_f32_e32 v113, 1.0, v180
	v_mul_f32_e32 v112, v179, v113
	v_add_u32_e32 v113, 0x400, v115
	ds_write2_b32 v113, v114, v112 offset0:8 offset1:74
	v_add_u32_e32 v115, v19, v77
	v_sub_f32_e32 v113, 1.0, v182
	v_mul_f32_e32 v114, v181, v113
	v_sub_f32_e32 v113, 1.0, v184
	v_mul_f32_e32 v112, v183, v113
	ds_write2_b32 v115, v114, v112 offset1:66
	v_sub_f32_e32 v113, 1.0, v186
	v_mul_f32_e32 v114, v185, v113
	v_sub_f32_e32 v113, 1.0, v188
	v_mul_f32_e32 v112, v187, v113
	ds_write2_b32 v115, v114, v112 offset0:132 offset1:198
	v_add_u32_e32 v115, 0x400, v115
	v_sub_f32_e32 v113, 1.0, v190
	v_mul_f32_e32 v114, v189, v113
	v_sub_f32_e32 v113, 1.0, v192
	v_mul_f32_e32 v112, v191, v113
	ds_write2_b32 v115, v114, v112 offset0:8 offset1:74
	v_sub_f32_e32 v113, 1.0, v194
	v_mul_f32_e32 v114, v193, v113
	v_sub_f32_e32 v101, 1.0, v196
	v_mul_f32_e32 v100, v195, v101
	ds_write2_b32 v115, v114, v100 offset0:140 offset1:206
	s_waitcnt lgkmcnt(0)
	ds_read2_b32 v[112:113], v81 offset1:33
	s_waitcnt lgkmcnt(0)
	v_cvt_pk_bf16_f32 v112, v112, v113
	ds_read2_b32 v[114:115], v81 offset0:66 offset1:99
	s_waitcnt lgkmcnt(0)
	v_cvt_pk_bf16_f32 v113, v114, v115
	ds_read2_b32 v[114:115], v81 offset0:132 offset1:165
	s_waitcnt lgkmcnt(0)
	v_cvt_pk_bf16_f32 v114, v114, v115
	ds_read2_b32 v[116:117], v81 offset0:198 offset1:231
	s_waitcnt lgkmcnt(0)
	v_cvt_pk_bf16_f32 v115, v116, v117
	v_or_b32_e32 v116, s0, v79
	v_lshl_add_u64 v[100:101], v[32:33], 0, s[10:11]
	v_lshlrev_b32_e32 v116, 11, v116
	v_mov_b32_e32 v117, v5
	v_lshl_add_u64 v[116:117], v[100:101], 0, v[116:117]
	global_store_dwordx4 v[116:117], v[112:115], off
	ds_read2_b32 v[112:113], v81 offset0:8 offset1:41
	s_waitcnt lgkmcnt(0)
	v_cvt_pk_bf16_f32 v112, v112, v113
	ds_read2_b32 v[114:115], v81 offset0:74 offset1:107
	s_waitcnt lgkmcnt(0)
	v_cvt_pk_bf16_f32 v113, v114, v115
	ds_read2_b32 v[114:115], v81 offset0:140 offset1:173
	s_waitcnt lgkmcnt(0)
	v_cvt_pk_bf16_f32 v114, v114, v115
	ds_read2_b32 v[116:117], v81 offset0:206 offset1:239
	s_waitcnt lgkmcnt(0)
	v_cvt_pk_bf16_f32 v115, v116, v117
	v_or_b32_e32 v116, s0, v108
	v_lshlrev_b32_e32 v116, 11, v116
	v_mov_b32_e32 v117, v5
	v_lshl_add_u64 v[116:117], v[100:101], 0, v[116:117]
	global_store_dwordx4 v[116:117], v[112:115], off
	ds_read2_b32 v[112:113], v81 offset0:16 offset1:49
	s_waitcnt lgkmcnt(0)
	v_cvt_pk_bf16_f32 v112, v112, v113
	ds_read2_b32 v[114:115], v81 offset0:82 offset1:115
	s_waitcnt lgkmcnt(0)
	v_cvt_pk_bf16_f32 v113, v114, v115
	ds_read2_b32 v[114:115], v81 offset0:148 offset1:181
	s_waitcnt lgkmcnt(0)
	v_cvt_pk_bf16_f32 v114, v114, v115
	ds_read2_b32 v[116:117], v81 offset0:214 offset1:247
	s_waitcnt lgkmcnt(0)
	v_cvt_pk_bf16_f32 v115, v116, v117
	v_or_b32_e32 v116, s0, v109
	v_lshlrev_b32_e32 v116, 11, v116
	v_mov_b32_e32 v117, v5
	v_lshl_add_u64 v[116:117], v[100:101], 0, v[116:117]
	global_store_dwordx4 v[116:117], v[112:115], off
	ds_read2_b32 v[112:113], v81 offset0:24 offset1:57
	s_waitcnt lgkmcnt(0)
	v_cvt_pk_bf16_f32 v112, v112, v113
	ds_read2_b32 v[114:115], v81 offset0:90 offset1:123
	s_waitcnt lgkmcnt(0)
	v_cvt_pk_bf16_f32 v113, v114, v115
	ds_read2_b32 v[114:115], v81 offset0:156 offset1:189
	s_waitcnt lgkmcnt(0)
	v_cvt_pk_bf16_f32 v114, v114, v115
	ds_read2_b32 v[116:117], v81 offset0:222 offset1:255
	s_waitcnt lgkmcnt(0)
	v_cvt_pk_bf16_f32 v115, v116, v117
	v_or_b32_e32 v116, s0, v110
	v_lshlrev_b32_e32 v116, 11, v116
	v_mov_b32_e32 v117, v5
	v_lshl_add_u64 v[100:101], v[100:101], 0, v[116:117]
	global_store_dwordx4 v[100:101], v[112:115], off
	s_waitcnt lgkmcnt(0)

.LBB0_44:
	s_andn2_b64 vcc, exec, s[0:1]
	s_cbranch_vccnz .LBB0_9
	s_ashr_i32 s0, s3, 31
	s_lshr_b32 s0, s0, 23
	s_add_i32 s10, s3, s0
	s_ashr_i32 s0, s10, 9
	s_ashr_i32 s1, s0, 31
	s_lshl_b64 s[14:15], s[0:1], 22
	s_add_u32 s17, s46, s14
	s_addc_u32 s28, s47, s15
	s_and_b32 s1, s10, 0xfe00
	s_sub_i32 s1, s3, s1
	s_sext_i32_i16 s10, s1
	s_bfe_u32 s10, s10, 0x5001a
	s_add_i32 s10, s1, s10
	s_sext_i32_i16 s14, s10
	s_and_b32 s10, s10, 0xffe0
	s_sub_i32 s1, s1, s10
	s_sext_i32_i16 s10, s1
	s_lshl_b32 s14, s14, 1
	s_and_b32 s16, s14, 0xffffffc0
	s_lshl_b32 s14, s10, 5
	s_ashr_i32 s15, s14, 31
	s_lshl_b64 s[26:27], s[14:15], 2
	s_add_u32 s26, s17, s26
	v_or_b32_e32 v112, s16, v3
	s_addc_u32 s27, s28, s27
	v_ashrrev_i32_e32 v113, 31, v112
	v_lshl_add_u64 v[100:101], s[26:27], 0, v[4:5]
	v_lshlrev_b64 v[112:113], 12, v[112:113]
	v_lshl_add_u64 v[112:113], v[100:101], 0, v[112:113]
	global_load_dword v125, v[112:113], off nt
	v_or_b32_e32 v112, s16, v39
	v_ashrrev_i32_e32 v113, 31, v112
	v_lshlrev_b64 v[112:113], 12, v[112:113]
	v_lshl_add_u64 v[112:113], v[100:101], 0, v[112:113]
	global_load_dword v128, v[112:113], off nt
	v_or_b32_e32 v112, s16, v41
	v_ashrrev_i32_e32 v113, 31, v112
	v_lshlrev_b64 v[112:113], 12, v[112:113]
	v_lshl_add_u64 v[112:113], v[100:101], 0, v[112:113]
	global_load_dword v130, v[112:113], off nt
	v_or_b32_e32 v112, s16, v43
	v_ashrrev_i32_e32 v113, 31, v112
	v_lshlrev_b64 v[112:113], 12, v[112:113]
	v_lshl_add_u64 v[112:113], v[100:101], 0, v[112:113]
	global_load_dword v131, v[112:113], off nt
	v_or_b32_e32 v112, s16, v45
	v_ashrrev_i32_e32 v113, 31, v112
	v_lshlrev_b64 v[112:113], 12, v[112:113]
	v_lshl_add_u64 v[112:113], v[100:101], 0, v[112:113]
	global_load_dword v132, v[112:113], off nt
	v_or_b32_e32 v112, s16, v47
	v_ashrrev_i32_e32 v113, 31, v112
	v_lshlrev_b64 v[112:113], 12, v[112:113]
	v_lshl_add_u64 v[112:113], v[100:101], 0, v[112:113]
	global_load_dword v133, v[112:113], off nt
	v_or_b32_e32 v112, s16, v49
	v_ashrrev_i32_e32 v113, 31, v112
	v_lshlrev_b64 v[112:113], 12, v[112:113]
	v_lshl_add_u64 v[112:113], v[100:101], 0, v[112:113]
	global_load_dword v134, v[112:113], off nt
	v_or_b32_e32 v112, s16, v53
	v_ashrrev_i32_e32 v113, 31, v112
	v_lshlrev_b64 v[112:113], 12, v[112:113]
	v_lshl_add_u64 v[112:113], v[100:101], 0, v[112:113]
	global_load_dword v135, v[112:113], off nt
	v_or_b32_e32 v112, s16, v55
	v_ashrrev_i32_e32 v113, 31, v112
	v_lshlrev_b64 v[112:113], 12, v[112:113]
	v_lshl_add_u64 v[112:113], v[100:101], 0, v[112:113]
	global_load_dword v136, v[112:113], off nt
	v_or_b32_e32 v112, s16, v57
	v_ashrrev_i32_e32 v113, 31, v112
	v_lshlrev_b64 v[112:113], 12, v[112:113]
	v_lshl_add_u64 v[112:113], v[100:101], 0, v[112:113]
	global_load_dword v137, v[112:113], off nt
	v_or_b32_e32 v112, s16, v59
	v_ashrrev_i32_e32 v113, 31, v112
	v_lshlrev_b64 v[112:113], 12, v[112:113]
	v_lshl_add_u64 v[112:113], v[100:101], 0, v[112:113]
	global_load_dword v138, v[112:113], off nt
	v_or_b32_e32 v112, s16, v61
	v_ashrrev_i32_e32 v113, 31, v112
	v_lshlrev_b64 v[112:113], 12, v[112:113]
	v_lshl_add_u64 v[112:113], v[100:101], 0, v[112:113]
	global_load_dword v139, v[112:113], off nt
	v_or_b32_e32 v112, s16, v63
	v_ashrrev_i32_e32 v113, 31, v112
	v_lshlrev_b64 v[112:113], 12, v[112:113]
	v_lshl_add_u64 v[112:113], v[100:101], 0, v[112:113]
	global_load_dword v140, v[112:113], off nt
	v_or_b32_e32 v112, s16, v67
	v_ashrrev_i32_e32 v113, 31, v112
	v_lshlrev_b64 v[112:113], 12, v[112:113]
	v_lshl_add_u64 v[112:113], v[100:101], 0, v[112:113]
	global_load_dword v141, v[112:113], off nt
	v_or_b32_e32 v112, s16, v69
	v_ashrrev_i32_e32 v113, 31, v112
	v_lshlrev_b64 v[112:113], 12, v[112:113]
	v_lshl_add_u64 v[112:113], v[100:101], 0, v[112:113]
	global_load_dword v142, v[112:113], off nt
	v_or_b32_e32 v112, s16, v71
	v_ashrrev_i32_e32 v113, 31, v112
	v_lshlrev_b64 v[112:113], 12, v[112:113]
	v_lshl_add_u64 v[112:113], v[100:101], 0, v[112:113]
	global_load_dword v143, v[112:113], off nt
	v_or_b32_e32 v112, s16, v73
	v_ashrrev_i32_e32 v113, 31, v112
	v_lshlrev_b64 v[112:113], 12, v[112:113]
	v_lshl_add_u64 v[112:113], v[100:101], 0, v[112:113]
	global_load_dword v144, v[112:113], off nt
	v_or_b32_e32 v112, s16, v83
	v_ashrrev_i32_e32 v113, 31, v112
	v_lshlrev_b64 v[112:113], 12, v[112:113]
	v_lshl_add_u64 v[112:113], v[100:101], 0, v[112:113]
	global_load_dword v145, v[112:113], off nt
	v_or_b32_e32 v112, s16, v85
	v_ashrrev_i32_e32 v113, 31, v112
	v_lshlrev_b64 v[112:113], 12, v[112:113]
	v_lshl_add_u64 v[112:113], v[100:101], 0, v[112:113]
	global_load_dword v146, v[112:113], off nt
	v_or_b32_e32 v112, s16, v87
	v_ashrrev_i32_e32 v113, 31, v112
	v_lshlrev_b64 v[112:113], 12, v[112:113]
	v_lshl_add_u64 v[112:113], v[100:101], 0, v[112:113]
	global_load_dword v148, v[112:113], off nt
	v_or_b32_e32 v112, s16, v89
	v_ashrrev_i32_e32 v113, 31, v112
	v_lshlrev_b64 v[112:113], 12, v[112:113]
	v_lshl_add_u64 v[112:113], v[100:101], 0, v[112:113]
	global_load_dword v150, v[112:113], off nt
	v_or_b32_e32 v112, s16, v91
	v_ashrrev_i32_e32 v113, 31, v112
	v_lshlrev_b64 v[112:113], 12, v[112:113]
	v_lshl_add_u64 v[112:113], v[100:101], 0, v[112:113]
	global_load_dword v151, v[112:113], off nt
	v_or_b32_e32 v112, s16, v93
	v_ashrrev_i32_e32 v113, 31, v112
	v_lshlrev_b64 v[112:113], 12, v[112:113]
	v_lshl_add_u64 v[112:113], v[100:101], 0, v[112:113]
	global_load_dword v152, v[112:113], off nt
	v_or_b32_e32 v112, s16, v95
	v_ashrrev_i32_e32 v113, 31, v112
	v_lshlrev_b64 v[112:113], 12, v[112:113]
	v_lshl_add_u64 v[112:113], v[100:101], 0, v[112:113]
	global_load_dword v153, v[112:113], off nt
	v_or_b32_e32 v112, s16, v97
	v_ashrrev_i32_e32 v113, 31, v112
	v_lshlrev_b64 v[112:113], 12, v[112:113]
	v_lshl_add_u64 v[112:113], v[100:101], 0, v[112:113]
	global_load_dword v154, v[112:113], off nt
	v_or_b32_e32 v112, s16, v99
	v_ashrrev_i32_e32 v113, 31, v112
	v_lshlrev_b64 v[112:113], 12, v[112:113]
	v_lshl_add_u64 v[112:113], v[100:101], 0, v[112:113]
	global_load_dword v155, v[112:113], off nt
	v_or_b32_e32 v112, s16, v102
	v_ashrrev_i32_e32 v113, 31, v112
	v_lshlrev_b64 v[112:113], 12, v[112:113]
	v_lshl_add_u64 v[112:113], v[100:101], 0, v[112:113]
	global_load_dword v156, v[112:113], off nt
	v_or_b32_e32 v112, s16, v103
	v_ashrrev_i32_e32 v113, 31, v112
	v_lshlrev_b64 v[112:113], 12, v[112:113]
	v_lshl_add_u64 v[112:113], v[100:101], 0, v[112:113]
	global_load_dword v157, v[112:113], off nt
	v_or_b32_e32 v112, s16, v104
	v_ashrrev_i32_e32 v113, 31, v112
	v_lshlrev_b64 v[112:113], 12, v[112:113]
	v_lshl_add_u64 v[112:113], v[100:101], 0, v[112:113]
	global_load_dword v158, v[112:113], off nt
	v_or_b32_e32 v112, s16, v105
	v_ashrrev_i32_e32 v113, 31, v112
	v_lshlrev_b64 v[112:113], 12, v[112:113]
	v_lshl_add_u64 v[112:113], v[100:101], 0, v[112:113]
	global_load_dword v159, v[112:113], off nt
	v_or_b32_e32 v112, s16, v106
	v_ashrrev_i32_e32 v113, 31, v112
	v_lshlrev_b64 v[112:113], 12, v[112:113]
	v_lshl_add_u64 v[112:113], v[100:101], 0, v[112:113]
	global_load_dword v160, v[112:113], off nt
	v_or_b32_e32 v112, s16, v107
	v_ashrrev_i32_e32 v113, 31, v112
	v_lshlrev_b64 v[112:113], 12, v[112:113]
	v_lshl_add_u64 v[100:101], v[100:101], 0, v[112:113]
	global_load_dword v161, v[100:101], off nt
	s_waitcnt vmcnt(0)
	s_lshl_b32 s0, s0, 10
	v_add_u32_e32 v115, v19, v37
	s_and_b32 s10, s14, 0xffffffc0
	s_ashr_i32 s17, s16, 31
	s_and_b32 s1, s1, 0x8001
	s_cmpk_eq_u32 s1, 0x8000
	v_or_b32_e32 v118, s10, v111
	s_cselect_b64 vcc, -1, 0
	ds_write2_b32 v115, v125, v128 offset1:66
	ds_write2_b32 v115, v130, v131 offset0:132 offset1:198
	v_add_u32_e32 v113, 0x400, v115
	v_add_u32_e32 v115, v19, v51
	ds_write2_b32 v113, v132, v133 offset0:8 offset1:74
	ds_write2_b32 v115, v134, v135 offset1:66
	ds_write2_b32 v115, v136, v137 offset0:132 offset1:198
	v_add_u32_e32 v113, 0x400, v115
	v_add_u32_e32 v115, v19, v65
	ds_write2_b32 v113, v138, v139 offset0:8 offset1:74
	ds_write2_b32 v115, v140, v141 offset1:66
	ds_write2_b32 v115, v142, v143 offset0:132 offset1:198
	v_add_u32_e32 v113, 0x400, v115
	v_add_u32_e32 v115, v19, v75
	ds_write2_b32 v113, v144, v145 offset0:8 offset1:74
	ds_write2_b32 v115, v146, v148 offset1:66
	ds_write2_b32 v115, v150, v151 offset0:132 offset1:198
	v_add_u32_e32 v113, 0x400, v115
	v_add_u32_e32 v115, v19, v77
	ds_write2_b32 v113, v152, v153 offset0:8 offset1:74
	ds_write2_b32 v115, v154, v155 offset1:66
	ds_write2_b32 v115, v156, v157 offset0:132 offset1:198
	v_add_u32_e32 v115, 0x400, v115
	ds_write2_b32 v115, v158, v159 offset0:8 offset1:74
	ds_write2_b32 v115, v160, v161 offset0:140 offset1:206
	s_waitcnt lgkmcnt(0)
	ds_read2_b32 v[112:113], v81 offset1:33
	s_waitcnt lgkmcnt(0)
	v_cvt_pk_bf16_f32 v112, v112, v113
	ds_read2_b32 v[114:115], v81 offset0:66 offset1:99
	s_waitcnt lgkmcnt(0)
	v_cvt_pk_bf16_f32 v113, v114, v115
	ds_read2_b32 v[114:115], v81 offset0:132 offset1:165
	s_waitcnt lgkmcnt(0)
	v_cvt_pk_bf16_f32 v114, v114, v115
	ds_read2_b32 v[116:117], v81 offset0:198 offset1:231
	s_waitcnt lgkmcnt(0)
	v_cvt_pk_bf16_f32 v115, v116, v117
	v_or_b32_e32 v116, s14, v79
	v_cndmask_b32_e32 v116, v116, v118, vcc
	v_add_u32_e32 v116, s0, v116
	v_ashrrev_i32_e32 v117, 31, v116
	v_lshl_add_u64 v[100:101], s[16:17], 1, v[34:35]
	v_lshlrev_b64 v[116:117], 11, v[116:117]
	v_lshl_add_u64 v[116:117], v[100:101], 0, v[116:117]
	global_store_dwordx4 v[116:117], v[112:115], off
	ds_read2_b32 v[112:113], v81 offset0:8 offset1:41
	s_waitcnt lgkmcnt(0)
	v_cvt_pk_bf16_f32 v112, v112, v113
	ds_read2_b32 v[114:115], v81 offset0:74 offset1:107
	s_waitcnt lgkmcnt(0)
	v_cvt_pk_bf16_f32 v113, v114, v115
	ds_read2_b32 v[114:115], v81 offset0:140 offset1:173
	s_waitcnt lgkmcnt(0)
	v_cvt_pk_bf16_f32 v114, v114, v115
	ds_read2_b32 v[116:117], v81 offset0:206 offset1:239
	s_waitcnt lgkmcnt(0)
	v_cvt_pk_bf16_f32 v115, v116, v117
	v_or_b32_e32 v116, s14, v108
	v_or_b32_e32 v117, 1, v118
	v_cndmask_b32_e32 v116, v116, v117, vcc
	v_add_u32_e32 v116, s0, v116
	v_ashrrev_i32_e32 v117, 31, v116
	v_lshlrev_b64 v[116:117], 11, v[116:117]
	v_lshl_add_u64 v[116:117], v[100:101], 0, v[116:117]
	global_store_dwordx4 v[116:117], v[112:115], off
	ds_read2_b32 v[112:113], v81 offset0:16 offset1:49
	s_waitcnt lgkmcnt(0)
	v_cvt_pk_bf16_f32 v112, v112, v113
	ds_read2_b32 v[114:115], v81 offset0:82 offset1:115
	s_waitcnt lgkmcnt(0)
	v_cvt_pk_bf16_f32 v113, v114, v115
	ds_read2_b32 v[114:115], v81 offset0:148 offset1:181
	s_waitcnt lgkmcnt(0)
	v_cvt_pk_bf16_f32 v114, v114, v115
	ds_read2_b32 v[116:117], v81 offset0:214 offset1:247
	s_waitcnt lgkmcnt(0)
	v_cvt_pk_bf16_f32 v115, v116, v117
	v_or_b32_e32 v116, s0, v109
	v_add_u32_e32 v116, s14, v116
	v_ashrrev_i32_e32 v117, 31, v116
	v_lshlrev_b64 v[116:117], 11, v[116:117]
	v_lshl_add_u64 v[116:117], v[100:101], 0, v[116:117]
	global_store_dwordx4 v[116:117], v[112:115], off
	ds_read2_b32 v[112:113], v81 offset0:24 offset1:57
	s_waitcnt lgkmcnt(0)
	v_cvt_pk_bf16_f32 v112, v112, v113
	ds_read2_b32 v[114:115], v81 offset0:90 offset1:123
	s_waitcnt lgkmcnt(0)
	v_cvt_pk_bf16_f32 v113, v114, v115
	ds_read2_b32 v[114:115], v81 offset0:156 offset1:189
	s_waitcnt lgkmcnt(0)
	v_cvt_pk_bf16_f32 v114, v114, v115
	ds_read2_b32 v[116:117], v81 offset0:222 offset1:255
	s_waitcnt lgkmcnt(0)
	v_cvt_pk_bf16_f32 v115, v116, v117
	v_or_b32_e32 v116, s0, v110
	v_add_u32_e32 v116, s14, v116
	v_ashrrev_i32_e32 v117, 31, v116
	v_lshlrev_b64 v[116:117], 11, v[116:117]
	v_lshl_add_u64 v[100:101], v[100:101], 0, v[116:117]
	global_store_dwordx4 v[100:101], v[112:115], off
	s_waitcnt lgkmcnt(0)
	s_branch .LBB0_9

.LBB0_54:
	global_load_dwordx4 v[8:11], v[6:7], off offset:-16 nt
	global_load_dwordx4 v[12:15], v[6:7], off nt
	v_lshl_add_u64 v[4:5], v[4:5], 0, s[8:9]
	v_cmp_lt_u64_e32 vcc, s[16:17], v[4:5]
	v_lshl_add_u64 v[6:7], v[6:7], 0, s[10:11]
	s_or_b64 s[14:15], vcc, s[14:15]
	s_waitcnt vmcnt(1)
	v_cvt_pk_bf16_f32 v8, v8, v9
	v_cvt_pk_bf16_f32 v9, v10, v11
	s_waitcnt vmcnt(0)
	v_cvt_pk_bf16_f32 v10, v12, v13
	v_cvt_pk_bf16_f32 v11, v14, v15
	global_store_dwordx4 v[2:3], v[8:11], off
	v_lshl_add_u64 v[2:3], v[2:3], 0, s[0:1]
	s_andn2_b64 exec, exec, s[14:15]
	s_cbranch_execnz .LBB0_54

.LBB0_544:
	s_cmpk_gt_i32 s30, 0x3ff
	s_mov_b64 s[0:1], -1
	s_cbranch_scc0 .LBB0_558
	s_cmpk_gt_u32 s30, 0x7ff
	s_cbranch_scc0 .LBB0_555
	s_cmpk_gt_u32 s30, 0x9ff
	s_cbranch_scc0 .LBB0_552
	s_cmpk_gt_u32 s30, 0xa7f
	s_cbranch_scc0 .LBB0_549
	s_add_i32 s0, s11, 0x1eb00
	s_and_b32 s1, s0, 0x1ffc0
	s_and_b32 s0, s9, 0x3e0
	s_lshl_b32 s12, s0, 2
	v_or_b32_e32 v2, s1, v0
	v_lshl_add_u64 v[22:23], v[4:5], 0, s[12:13]
	v_lshlrev_b32_e32 v2, 12, v2
	v_lshl_add_u64 v[24:25], v[22:23], 0, v[2:3]
	v_or_b32_e32 v2, s1, v28
	v_lshlrev_b32_e32 v2, 12, v2
	v_lshl_add_u64 v[90:91], v[22:23], 0, v[2:3]
	v_or_b32_e32 v2, s1, v29
	v_lshlrev_b32_e32 v2, 12, v2
	v_lshl_add_u64 v[92:93], v[22:23], 0, v[2:3]
	v_or_b32_e32 v2, s1, v30
	v_lshlrev_b32_e32 v2, 12, v2
	v_lshl_add_u64 v[94:95], v[22:23], 0, v[2:3]
	v_or_b32_e32 v2, s1, v31
	v_lshlrev_b32_e32 v2, 12, v2
	v_lshl_add_u64 v[96:97], v[22:23], 0, v[2:3]
	v_or_b32_e32 v2, s1, v32
	v_lshlrev_b32_e32 v2, 12, v2
	v_lshl_add_u64 v[98:99], v[22:23], 0, v[2:3]
	v_or_b32_e32 v2, s1, v33
	v_lshlrev_b32_e32 v2, 12, v2
	v_lshl_add_u64 v[100:101], v[22:23], 0, v[2:3]
	v_or_b32_e32 v2, s1, v35
	v_lshlrev_b32_e32 v2, 12, v2
	v_lshl_add_u64 v[102:103], v[22:23], 0, v[2:3]
	v_or_b32_e32 v2, s1, v36
	v_lshlrev_b32_e32 v2, 12, v2
	global_load_dword v104, v[24:25], off nt
	global_load_dword v105, v[90:91], off nt
	global_load_dword v106, v[92:93], off nt
	global_load_dword v107, v[94:95], off nt
	global_load_dword v108, v[96:97], off nt
	global_load_dword v109, v[98:99], off nt
	global_load_dword v110, v[100:101], off nt
	global_load_dword v111, v[102:103], off nt
	v_lshl_add_u64 v[24:25], v[22:23], 0, v[2:3]
	v_or_b32_e32 v2, s1, v37
	v_lshlrev_b32_e32 v2, 12, v2
	v_lshl_add_u64 v[90:91], v[22:23], 0, v[2:3]
	v_or_b32_e32 v2, s1, v38
	v_lshlrev_b32_e32 v2, 12, v2
	v_lshl_add_u64 v[92:93], v[22:23], 0, v[2:3]
	v_or_b32_e32 v2, s1, v39
	v_lshlrev_b32_e32 v2, 12, v2
	v_lshl_add_u64 v[94:95], v[22:23], 0, v[2:3]
	v_or_b32_e32 v2, s1, v40
	v_lshlrev_b32_e32 v2, 12, v2
	v_lshl_add_u64 v[96:97], v[22:23], 0, v[2:3]
	v_or_b32_e32 v2, s1, v42
	v_lshlrev_b32_e32 v2, 12, v2
	v_lshl_add_u64 v[98:99], v[22:23], 0, v[2:3]
	v_or_b32_e32 v2, s1, v43
	v_lshlrev_b32_e32 v2, 12, v2
	v_lshl_add_u64 v[100:101], v[22:23], 0, v[2:3]
	v_or_b32_e32 v2, s1, v44
	v_lshlrev_b32_e32 v2, 12, v2
	v_lshl_add_u64 v[102:103], v[22:23], 0, v[2:3]
	v_or_b32_e32 v2, s1, v45
	v_lshlrev_b32_e32 v2, 12, v2
	global_load_dword v112, v[24:25], off nt
	global_load_dword v113, v[90:91], off nt
	global_load_dword v114, v[92:93], off nt
	global_load_dword v115, v[94:95], off nt
	global_load_dword v116, v[96:97], off nt
	global_load_dword v117, v[98:99], off nt
	global_load_dword v118, v[100:101], off nt
	global_load_dword v119, v[102:103], off nt
	v_lshl_add_u64 v[24:25], v[22:23], 0, v[2:3]
	v_or_b32_e32 v2, s1, v46
	v_lshlrev_b32_e32 v2, 12, v2
	v_lshl_add_u64 v[90:91], v[22:23], 0, v[2:3]
	v_or_b32_e32 v2, s1, v47
	v_lshlrev_b32_e32 v2, 12, v2
	v_lshl_add_u64 v[92:93], v[22:23], 0, v[2:3]
	v_or_b32_e32 v2, s1, v49
	v_lshlrev_b32_e32 v2, 12, v2
	v_lshl_add_u64 v[94:95], v[22:23], 0, v[2:3]
	v_or_b32_e32 v2, s1, v50
	v_lshlrev_b32_e32 v2, 12, v2
	v_lshl_add_u64 v[96:97], v[22:23], 0, v[2:3]
	v_or_b32_e32 v2, s1, v51
	v_lshlrev_b32_e32 v2, 12, v2
	v_lshl_add_u64 v[98:99], v[22:23], 0, v[2:3]
	v_or_b32_e32 v2, s1, v52
	v_lshlrev_b32_e32 v2, 12, v2
	v_lshl_add_u64 v[100:101], v[22:23], 0, v[2:3]
	v_or_b32_e32 v2, s1, v53
	v_lshlrev_b32_e32 v2, 12, v2
	v_lshl_add_u64 v[102:103], v[22:23], 0, v[2:3]
	v_or_b32_e32 v2, s1, v54
	v_lshlrev_b32_e32 v2, 12, v2
	global_load_dword v120, v[24:25], off nt
	global_load_dword v121, v[90:91], off nt
	global_load_dword v122, v[92:93], off nt
	global_load_dword v123, v[94:95], off nt
	global_load_dword v124, v[96:97], off nt
	global_load_dword v125, v[98:99], off nt
	global_load_dword v126, v[100:101], off nt
	s_nop 0
	global_load_dword v102, v[102:103], off nt
	v_lshl_add_u64 v[24:25], v[22:23], 0, v[2:3]
	v_or_b32_e32 v2, s1, v56
	v_lshlrev_b32_e32 v2, 12, v2
	v_lshl_add_u64 v[90:91], v[22:23], 0, v[2:3]
	v_or_b32_e32 v2, s1, v57
	v_lshlrev_b32_e32 v2, 12, v2
	v_lshl_add_u64 v[92:93], v[22:23], 0, v[2:3]
	v_or_b32_e32 v2, s1, v58
	v_lshlrev_b32_e32 v2, 12, v2
	v_lshl_add_u64 v[94:95], v[22:23], 0, v[2:3]
	v_or_b32_e32 v2, s1, v59
	v_lshlrev_b32_e32 v2, 12, v2
	v_lshl_add_u64 v[96:97], v[22:23], 0, v[2:3]
	v_or_b32_e32 v2, s1, v60
	v_lshlrev_b32_e32 v2, 12, v2
	v_lshl_add_u64 v[98:99], v[22:23], 0, v[2:3]
	v_or_b32_e32 v2, s1, v61
	v_lshlrev_b32_e32 v2, 12, v2
	v_lshl_add_u64 v[100:101], v[22:23], 0, v[2:3]
	v_or_b32_e32 v2, s1, v62
	v_lshlrev_b32_e32 v2, 12, v2
	v_lshl_add_u64 v[22:23], v[22:23], 0, v[2:3]
	global_load_dword v2, v[24:25], off nt
	s_nop 0
	global_load_dword v24, v[90:91], off nt
	global_load_dword v25, v[92:93], off nt
	s_nop 0
	global_load_dword v90, v[94:95], off nt
	global_load_dword v91, v[96:97], off nt
	global_load_dword v92, v[98:99], off nt
	global_load_dword v93, v[100:101], off nt
	s_nop 0
	global_load_dword v22, v[22:23], off nt
	v_add_u32_e32 v23, v26, v27
	s_waitcnt vmcnt(30)
	ds_write2_b32 v23, v104, v105 offset1:66
	s_waitcnt vmcnt(28)
	ds_write2_b32 v23, v106, v107 offset0:132 offset1:198
	v_add_u32_e32 v23, 0x400, v23
	s_waitcnt vmcnt(26)
	ds_write2_b32 v23, v108, v109 offset0:8 offset1:74
	v_add_u32_e32 v23, v26, v34
	s_waitcnt vmcnt(24)
	ds_write2_b32 v23, v110, v111 offset1:66
	s_waitcnt vmcnt(22)
	ds_write2_b32 v23, v112, v113 offset0:132 offset1:198
	v_add_u32_e32 v23, 0x400, v23
	s_waitcnt vmcnt(20)
	ds_write2_b32 v23, v114, v115 offset0:8 offset1:74
	v_add_u32_e32 v23, v26, v41
	s_waitcnt vmcnt(18)
	ds_write2_b32 v23, v116, v117 offset1:66
	s_waitcnt vmcnt(16)
	ds_write2_b32 v23, v118, v119 offset0:132 offset1:198
	v_add_u32_e32 v23, 0x400, v23
	s_lshl_b32 s12, s1, 1
	s_waitcnt vmcnt(14)
	ds_write2_b32 v23, v120, v121 offset0:8 offset1:74
	v_add_u32_e32 v23, v26, v48
	s_waitcnt vmcnt(12)
	ds_write2_b32 v23, v122, v123 offset1:66
	s_waitcnt vmcnt(10)
	ds_write2_b32 v23, v124, v125 offset0:132 offset1:198
	v_add_u32_e32 v23, 0x400, v23
	s_waitcnt vmcnt(8)
	ds_write2_b32 v23, v126, v102 offset0:8 offset1:74
	v_add_u32_e32 v23, v26, v55
	s_waitcnt vmcnt(6)
	ds_write2_b32 v23, v2, v24 offset1:66
	s_waitcnt vmcnt(4)
	ds_write2_b32 v23, v25, v90 offset0:132 offset1:198
	v_add_u32_e32 v2, 0x400, v23
	s_waitcnt vmcnt(2)
	ds_write2_b32 v2, v91, v92 offset0:8 offset1:74
	s_waitcnt vmcnt(0)
	ds_write2_b32 v2, v93, v22 offset0:140 offset1:206
	s_waitcnt lgkmcnt(0)
	ds_read2_b32 v[22:23], v64 offset1:33
	s_waitcnt lgkmcnt(0)
	v_cvt_pk_bf16_f32 v22, v22, v23
	ds_read2_b32 v[24:25], v64 offset0:66 offset1:99
	v_or_b32_e32 v2, s0, v63
	s_waitcnt lgkmcnt(0)
	v_cvt_pk_bf16_f32 v23, v24, v25
	ds_read2_b32 v[24:25], v64 offset0:132 offset1:165
	v_lshl_add_u64 v[92:93], v[6:7], 0, s[12:13]
	v_lshlrev_b32_e32 v2, 11, v2
	s_waitcnt lgkmcnt(0)
	v_cvt_pk_bf16_f32 v24, v24, v25
	ds_read2_b32 v[90:91], v64 offset0:198 offset1:231
	s_waitcnt lgkmcnt(0)
	v_cvt_pk_bf16_f32 v25, v90, v91
	v_lshl_add_u64 v[94:95], v[92:93], 0, v[2:3]
	ds_read2_b32 v[90:91], v64 offset0:8 offset1:41
	global_store_dwordx4 v[94:95], v[22:25], off
	v_or_b32_e32 v2, s0, v65
	v_lshlrev_b32_e32 v2, 11, v2
	s_waitcnt lgkmcnt(0)
	v_cvt_pk_bf16_f32 v22, v90, v91
	ds_read2_b32 v[24:25], v64 offset0:74 offset1:107
	s_waitcnt lgkmcnt(0)
	v_cvt_pk_bf16_f32 v23, v24, v25
	ds_read2_b32 v[24:25], v64 offset0:140 offset1:173
	s_waitcnt lgkmcnt(0)
	v_cvt_pk_bf16_f32 v24, v24, v25
	ds_read2_b32 v[90:91], v64 offset0:206 offset1:239
	s_waitcnt lgkmcnt(0)
	v_cvt_pk_bf16_f32 v25, v90, v91
	v_lshl_add_u64 v[94:95], v[92:93], 0, v[2:3]
	ds_read2_b32 v[90:91], v64 offset0:16 offset1:49
	global_store_dwordx4 v[94:95], v[22:25], off
	v_or_b32_e32 v2, s0, v66
	v_lshlrev_b32_e32 v2, 11, v2
	s_waitcnt lgkmcnt(0)
	v_cvt_pk_bf16_f32 v22, v90, v91
	ds_read2_b32 v[24:25], v64 offset0:82 offset1:115
	s_waitcnt lgkmcnt(0)
	v_cvt_pk_bf16_f32 v23, v24, v25
	ds_read2_b32 v[24:25], v64 offset0:148 offset1:181
	s_waitcnt lgkmcnt(0)
	v_cvt_pk_bf16_f32 v24, v24, v25
	ds_read2_b32 v[90:91], v64 offset0:214 offset1:247
	s_waitcnt lgkmcnt(0)
	v_cvt_pk_bf16_f32 v25, v90, v91
	v_lshl_add_u64 v[94:95], v[92:93], 0, v[2:3]
	ds_read2_b32 v[90:91], v64 offset0:24 offset1:57
	global_store_dwordx4 v[94:95], v[22:25], off
	v_or_b32_e32 v2, s0, v67
	v_lshlrev_b32_e32 v2, 11, v2
	s_waitcnt lgkmcnt(0)
	v_cvt_pk_bf16_f32 v22, v90, v91
	ds_read2_b32 v[24:25], v64 offset0:90 offset1:123
	s_waitcnt lgkmcnt(0)
	v_cvt_pk_bf16_f32 v23, v24, v25
	ds_read2_b32 v[24:25], v64 offset0:156 offset1:189
	s_waitcnt lgkmcnt(0)
	v_cvt_pk_bf16_f32 v24, v24, v25
	ds_read2_b32 v[90:91], v64 offset0:222 offset1:255
	s_waitcnt lgkmcnt(0)
	v_cvt_pk_bf16_f32 v25, v90, v91
	v_lshl_add_u64 v[90:91], v[92:93], 0, v[2:3]
	global_store_dwordx4 v[90:91], v[22:25], off
	s_waitcnt lgkmcnt(0)
	s_mov_b64 s[0:1], 0
.LBB0_549:
	s_andn2_b64 vcc, exec, s[0:1]
	s_cbranch_vccnz .LBB0_551
	s_and_b32 s1, s11, 0x1c0
	s_and_b32 s0, s9, 0x3e0
	s_lshl_b32 s12, s0, 2
	v_or_b32_e32 v2, s1, v0
	v_lshl_add_u64 v[22:23], v[8:9], 0, s[12:13]
	v_lshlrev_b32_e32 v2, 12, v2
	v_lshl_add_u64 v[24:25], v[22:23], 0, v[2:3]
	v_or_b32_e32 v2, s1, v28
	v_lshlrev_b32_e32 v2, 12, v2
	v_lshl_add_u64 v[90:91], v[22:23], 0, v[2:3]
	v_or_b32_e32 v2, s1, v29
	v_lshlrev_b32_e32 v2, 12, v2
	v_lshl_add_u64 v[92:93], v[22:23], 0, v[2:3]
	v_or_b32_e32 v2, s1, v30
	v_lshlrev_b32_e32 v2, 12, v2
	v_lshl_add_u64 v[94:95], v[22:23], 0, v[2:3]
	v_or_b32_e32 v2, s1, v31
	v_lshlrev_b32_e32 v2, 12, v2
	v_lshl_add_u64 v[96:97], v[22:23], 0, v[2:3]
	v_or_b32_e32 v2, s1, v32
	v_lshlrev_b32_e32 v2, 12, v2
	v_lshl_add_u64 v[98:99], v[22:23], 0, v[2:3]
	v_or_b32_e32 v2, s1, v33
	v_lshlrev_b32_e32 v2, 12, v2
	v_lshl_add_u64 v[100:101], v[22:23], 0, v[2:3]
	v_or_b32_e32 v2, s1, v35
	v_lshlrev_b32_e32 v2, 12, v2
	v_lshl_add_u64 v[102:103], v[22:23], 0, v[2:3]
	v_or_b32_e32 v2, s1, v36
	v_lshlrev_b32_e32 v2, 12, v2
	global_load_dword v104, v[24:25], off nt
	global_load_dword v105, v[90:91], off nt
	global_load_dword v106, v[92:93], off nt
	global_load_dword v107, v[94:95], off nt
	global_load_dword v108, v[96:97], off nt
	global_load_dword v109, v[98:99], off nt
	global_load_dword v110, v[100:101], off nt
	global_load_dword v111, v[102:103], off nt
	v_lshl_add_u64 v[24:25], v[22:23], 0, v[2:3]
	v_or_b32_e32 v2, s1, v37
	v_lshlrev_b32_e32 v2, 12, v2
	v_lshl_add_u64 v[90:91], v[22:23], 0, v[2:3]
	v_or_b32_e32 v2, s1, v38
	v_lshlrev_b32_e32 v2, 12, v2
	v_lshl_add_u64 v[92:93], v[22:23], 0, v[2:3]
	v_or_b32_e32 v2, s1, v39
	v_lshlrev_b32_e32 v2, 12, v2
	v_lshl_add_u64 v[94:95], v[22:23], 0, v[2:3]
	v_or_b32_e32 v2, s1, v40
	v_lshlrev_b32_e32 v2, 12, v2
	v_lshl_add_u64 v[96:97], v[22:23], 0, v[2:3]
	v_or_b32_e32 v2, s1, v42
	v_lshlrev_b32_e32 v2, 12, v2
	v_lshl_add_u64 v[98:99], v[22:23], 0, v[2:3]
	v_or_b32_e32 v2, s1, v43
	v_lshlrev_b32_e32 v2, 12, v2
	v_lshl_add_u64 v[100:101], v[22:23], 0, v[2:3]
	v_or_b32_e32 v2, s1, v44
	v_lshlrev_b32_e32 v2, 12, v2
	v_lshl_add_u64 v[102:103], v[22:23], 0, v[2:3]
	v_or_b32_e32 v2, s1, v45
	v_lshlrev_b32_e32 v2, 12, v2
	global_load_dword v112, v[24:25], off nt
	global_load_dword v113, v[90:91], off nt
	global_load_dword v114, v[92:93], off nt
	global_load_dword v115, v[94:95], off nt
	global_load_dword v116, v[96:97], off nt
	global_load_dword v117, v[98:99], off nt
	global_load_dword v118, v[100:101], off nt
	global_load_dword v119, v[102:103], off nt
	v_lshl_add_u64 v[24:25], v[22:23], 0, v[2:3]
	v_or_b32_e32 v2, s1, v46
	v_lshlrev_b32_e32 v2, 12, v2
	v_lshl_add_u64 v[90:91], v[22:23], 0, v[2:3]
	v_or_b32_e32 v2, s1, v47
	v_lshlrev_b32_e32 v2, 12, v2
	v_lshl_add_u64 v[92:93], v[22:23], 0, v[2:3]
	v_or_b32_e32 v2, s1, v49
	v_lshlrev_b32_e32 v2, 12, v2
	v_lshl_add_u64 v[94:95], v[22:23], 0, v[2:3]
	v_or_b32_e32 v2, s1, v50
	v_lshlrev_b32_e32 v2, 12, v2
	v_lshl_add_u64 v[96:97], v[22:23], 0, v[2:3]
	v_or_b32_e32 v2, s1, v51
	v_lshlrev_b32_e32 v2, 12, v2
	v_lshl_add_u64 v[98:99], v[22:23], 0, v[2:3]
	v_or_b32_e32 v2, s1, v52
	v_lshlrev_b32_e32 v2, 12, v2
	v_lshl_add_u64 v[100:101], v[22:23], 0, v[2:3]
	v_or_b32_e32 v2, s1, v53
	v_lshlrev_b32_e32 v2, 12, v2
	v_lshl_add_u64 v[102:103], v[22:23], 0, v[2:3]
	v_or_b32_e32 v2, s1, v54
	v_lshlrev_b32_e32 v2, 12, v2
	global_load_dword v120, v[24:25], off nt
	global_load_dword v121, v[90:91], off nt
	global_load_dword v122, v[92:93], off nt
	global_load_dword v123, v[94:95], off nt
	global_load_dword v124, v[96:97], off nt
	global_load_dword v125, v[98:99], off nt
	global_load_dword v126, v[100:101], off nt
	s_nop 0
	global_load_dword v102, v[102:103], off nt
	v_lshl_add_u64 v[24:25], v[22:23], 0, v[2:3]
	v_or_b32_e32 v2, s1, v56
	v_lshlrev_b32_e32 v2, 12, v2
	v_lshl_add_u64 v[90:91], v[22:23], 0, v[2:3]
	v_or_b32_e32 v2, s1, v57
	v_lshlrev_b32_e32 v2, 12, v2
	v_lshl_add_u64 v[92:93], v[22:23], 0, v[2:3]
	v_or_b32_e32 v2, s1, v58
	v_lshlrev_b32_e32 v2, 12, v2
	v_lshl_add_u64 v[94:95], v[22:23], 0, v[2:3]
	v_or_b32_e32 v2, s1, v59
	v_lshlrev_b32_e32 v2, 12, v2
	v_lshl_add_u64 v[96:97], v[22:23], 0, v[2:3]
	v_or_b32_e32 v2, s1, v60
	v_lshlrev_b32_e32 v2, 12, v2
	v_lshl_add_u64 v[98:99], v[22:23], 0, v[2:3]
	v_or_b32_e32 v2, s1, v61
	v_lshlrev_b32_e32 v2, 12, v2
	v_lshl_add_u64 v[100:101], v[22:23], 0, v[2:3]
	v_or_b32_e32 v2, s1, v62
	v_lshlrev_b32_e32 v2, 12, v2
	v_lshl_add_u64 v[22:23], v[22:23], 0, v[2:3]
	global_load_dword v2, v[24:25], off nt
	s_nop 0
	global_load_dword v24, v[90:91], off nt
	global_load_dword v25, v[92:93], off nt
	s_nop 0
	global_load_dword v90, v[94:95], off nt
	global_load_dword v91, v[96:97], off nt
	global_load_dword v92, v[98:99], off nt
	global_load_dword v93, v[100:101], off nt
	s_nop 0
	global_load_dword v22, v[22:23], off nt
	v_add_u32_e32 v23, v26, v27
	s_waitcnt vmcnt(30)
	ds_write2_b32 v23, v104, v105 offset1:66
	s_waitcnt vmcnt(28)
	ds_write2_b32 v23, v106, v107 offset0:132 offset1:198
	v_add_u32_e32 v23, 0x400, v23
	s_waitcnt vmcnt(26)
	ds_write2_b32 v23, v108, v109 offset0:8 offset1:74
	v_add_u32_e32 v23, v26, v34
	s_waitcnt vmcnt(24)
	ds_write2_b32 v23, v110, v111 offset1:66
	s_waitcnt vmcnt(22)
	ds_write2_b32 v23, v112, v113 offset0:132 offset1:198
	v_add_u32_e32 v23, 0x400, v23
	s_waitcnt vmcnt(20)
	ds_write2_b32 v23, v114, v115 offset0:8 offset1:74
	v_add_u32_e32 v23, v26, v41
	s_waitcnt vmcnt(18)
	ds_write2_b32 v23, v116, v117 offset1:66
	s_waitcnt vmcnt(16)
	ds_write2_b32 v23, v118, v119 offset0:132 offset1:198
	v_add_u32_e32 v23, 0x400, v23
	s_lshl_b32 s12, s1, 1
	s_waitcnt vmcnt(14)
	ds_write2_b32 v23, v120, v121 offset0:8 offset1:74
	v_add_u32_e32 v23, v26, v48
	s_waitcnt vmcnt(12)
	ds_write2_b32 v23, v122, v123 offset1:66
	s_waitcnt vmcnt(10)
	ds_write2_b32 v23, v124, v125 offset0:132 offset1:198
	v_add_u32_e32 v23, 0x400, v23
	s_waitcnt vmcnt(8)
	ds_write2_b32 v23, v126, v102 offset0:8 offset1:74
	v_add_u32_e32 v23, v26, v55
	s_waitcnt vmcnt(6)
	ds_write2_b32 v23, v2, v24 offset1:66
	s_waitcnt vmcnt(4)
	ds_write2_b32 v23, v25, v90 offset0:132 offset1:198
	v_add_u32_e32 v2, 0x400, v23
	s_waitcnt vmcnt(2)
	ds_write2_b32 v2, v91, v92 offset0:8 offset1:74
	s_waitcnt vmcnt(0)
	ds_write2_b32 v2, v93, v22 offset0:140 offset1:206
	s_waitcnt lgkmcnt(0)
	ds_read2_b32 v[22:23], v64 offset1:33
	s_waitcnt lgkmcnt(0)
	v_cvt_pk_bf16_f32 v22, v22, v23
	ds_read2_b32 v[24:25], v64 offset0:66 offset1:99
	v_or_b32_e32 v2, s0, v63
	s_waitcnt lgkmcnt(0)
	v_cvt_pk_bf16_f32 v23, v24, v25
	ds_read2_b32 v[24:25], v64 offset0:132 offset1:165
	v_lshl_add_u64 v[92:93], v[10:11], 0, s[12:13]
	v_lshlrev_b32_e32 v2, 9, v2
	s_waitcnt lgkmcnt(0)
	v_cvt_pk_bf16_f32 v24, v24, v25
	ds_read2_b32 v[90:91], v64 offset0:198 offset1:231
	s_waitcnt lgkmcnt(0)
	v_cvt_pk_bf16_f32 v25, v90, v91
	v_lshl_add_u64 v[94:95], v[92:93], 0, v[2:3]
	ds_read2_b32 v[90:91], v64 offset0:8 offset1:41
	global_store_dwordx4 v[94:95], v[22:25], off
	v_or_b32_e32 v2, s0, v65
	v_lshlrev_b32_e32 v2, 9, v2
	s_waitcnt lgkmcnt(0)
	v_cvt_pk_bf16_f32 v22, v90, v91
	ds_read2_b32 v[24:25], v64 offset0:74 offset1:107
	s_waitcnt lgkmcnt(0)
	v_cvt_pk_bf16_f32 v23, v24, v25
	ds_read2_b32 v[24:25], v64 offset0:140 offset1:173
	s_waitcnt lgkmcnt(0)
	v_cvt_pk_bf16_f32 v24, v24, v25
	ds_read2_b32 v[90:91], v64 offset0:206 offset1:239
	s_waitcnt lgkmcnt(0)
	v_cvt_pk_bf16_f32 v25, v90, v91
	v_lshl_add_u64 v[94:95], v[92:93], 0, v[2:3]
	ds_read2_b32 v[90:91], v64 offset0:16 offset1:49
	global_store_dwordx4 v[94:95], v[22:25], off
	v_or_b32_e32 v2, s0, v66
	v_lshlrev_b32_e32 v2, 9, v2
	s_waitcnt lgkmcnt(0)
	v_cvt_pk_bf16_f32 v22, v90, v91
	ds_read2_b32 v[24:25], v64 offset0:82 offset1:115
	s_waitcnt lgkmcnt(0)
	v_cvt_pk_bf16_f32 v23, v24, v25
	ds_read2_b32 v[24:25], v64 offset0:148 offset1:181
	s_waitcnt lgkmcnt(0)
	v_cvt_pk_bf16_f32 v24, v24, v25
	ds_read2_b32 v[90:91], v64 offset0:214 offset1:247
	s_waitcnt lgkmcnt(0)
	v_cvt_pk_bf16_f32 v25, v90, v91
	v_lshl_add_u64 v[94:95], v[92:93], 0, v[2:3]
	ds_read2_b32 v[90:91], v64 offset0:24 offset1:57
	global_store_dwordx4 v[94:95], v[22:25], off
	v_or_b32_e32 v2, s0, v67
	v_lshlrev_b32_e32 v2, 9, v2
	s_waitcnt lgkmcnt(0)
	v_cvt_pk_bf16_f32 v22, v90, v91
	ds_read2_b32 v[24:25], v64 offset0:90 offset1:123
	s_waitcnt lgkmcnt(0)
	v_cvt_pk_bf16_f32 v23, v24, v25
	ds_read2_b32 v[24:25], v64 offset0:156 offset1:189
	s_waitcnt lgkmcnt(0)
	v_cvt_pk_bf16_f32 v24, v24, v25
	ds_read2_b32 v[90:91], v64 offset0:222 offset1:255
	s_waitcnt lgkmcnt(0)
	v_cvt_pk_bf16_f32 v25, v90, v91
	v_lshl_add_u64 v[90:91], v[92:93], 0, v[2:3]
	global_store_dwordx4 v[90:91], v[22:25], off
	s_waitcnt lgkmcnt(0)

.LBB0_552:
	s_andn2_b64 vcc, exec, s[0:1]
	s_cbranch_vccnz .LBB0_554
	s_add_i32 s0, s11, 0x1f000
	s_and_b32 s1, s0, 0x1ffc0
	s_and_b32 s0, s9, 0x3e0
	s_lshl_b32 s12, s0, 2
	v_or_b32_e32 v2, s1, v0
	v_lshl_add_u64 v[22:23], v[12:13], 0, s[12:13]
	v_lshlrev_b32_e32 v2, 12, v2
	v_lshl_add_u64 v[24:25], v[22:23], 0, v[2:3]
	v_or_b32_e32 v2, s1, v28
	v_lshlrev_b32_e32 v2, 12, v2
	v_lshl_add_u64 v[90:91], v[22:23], 0, v[2:3]
	v_or_b32_e32 v2, s1, v29
	v_lshlrev_b32_e32 v2, 12, v2
	v_lshl_add_u64 v[92:93], v[22:23], 0, v[2:3]
	v_or_b32_e32 v2, s1, v30
	v_lshlrev_b32_e32 v2, 12, v2
	v_lshl_add_u64 v[94:95], v[22:23], 0, v[2:3]
	v_or_b32_e32 v2, s1, v31
	v_lshlrev_b32_e32 v2, 12, v2
	v_lshl_add_u64 v[96:97], v[22:23], 0, v[2:3]
	v_or_b32_e32 v2, s1, v32
	v_lshlrev_b32_e32 v2, 12, v2
	v_lshl_add_u64 v[98:99], v[22:23], 0, v[2:3]
	v_or_b32_e32 v2, s1, v33
	v_lshlrev_b32_e32 v2, 12, v2
	v_lshl_add_u64 v[100:101], v[22:23], 0, v[2:3]
	v_or_b32_e32 v2, s1, v35
	v_lshlrev_b32_e32 v2, 12, v2
	v_lshl_add_u64 v[102:103], v[22:23], 0, v[2:3]
	v_or_b32_e32 v2, s1, v36
	v_lshlrev_b32_e32 v2, 12, v2
	global_load_dword v104, v[24:25], off nt
	global_load_dword v105, v[90:91], off nt
	global_load_dword v106, v[92:93], off nt
	global_load_dword v107, v[94:95], off nt
	global_load_dword v108, v[96:97], off nt
	global_load_dword v109, v[98:99], off nt
	global_load_dword v110, v[100:101], off nt
	global_load_dword v111, v[102:103], off nt
	v_lshl_add_u64 v[24:25], v[22:23], 0, v[2:3]
	v_or_b32_e32 v2, s1, v37
	v_lshlrev_b32_e32 v2, 12, v2
	v_lshl_add_u64 v[90:91], v[22:23], 0, v[2:3]
	v_or_b32_e32 v2, s1, v38
	v_lshlrev_b32_e32 v2, 12, v2
	v_lshl_add_u64 v[92:93], v[22:23], 0, v[2:3]
	v_or_b32_e32 v2, s1, v39
	v_lshlrev_b32_e32 v2, 12, v2
	v_lshl_add_u64 v[94:95], v[22:23], 0, v[2:3]
	v_or_b32_e32 v2, s1, v40
	v_lshlrev_b32_e32 v2, 12, v2
	v_lshl_add_u64 v[96:97], v[22:23], 0, v[2:3]
	v_or_b32_e32 v2, s1, v42
	v_lshlrev_b32_e32 v2, 12, v2
	v_lshl_add_u64 v[98:99], v[22:23], 0, v[2:3]
	v_or_b32_e32 v2, s1, v43
	v_lshlrev_b32_e32 v2, 12, v2
	v_lshl_add_u64 v[100:101], v[22:23], 0, v[2:3]
	v_or_b32_e32 v2, s1, v44
	v_lshlrev_b32_e32 v2, 12, v2
	v_lshl_add_u64 v[102:103], v[22:23], 0, v[2:3]
	v_or_b32_e32 v2, s1, v45
	v_lshlrev_b32_e32 v2, 12, v2
	global_load_dword v112, v[24:25], off nt
	global_load_dword v113, v[90:91], off nt
	global_load_dword v114, v[92:93], off nt
	global_load_dword v115, v[94:95], off nt
	global_load_dword v116, v[96:97], off nt
	global_load_dword v117, v[98:99], off nt
	global_load_dword v118, v[100:101], off nt
	global_load_dword v119, v[102:103], off nt
	v_lshl_add_u64 v[24:25], v[22:23], 0, v[2:3]
	v_or_b32_e32 v2, s1, v46
	v_lshlrev_b32_e32 v2, 12, v2
	v_lshl_add_u64 v[90:91], v[22:23], 0, v[2:3]
	v_or_b32_e32 v2, s1, v47
	v_lshlrev_b32_e32 v2, 12, v2
	v_lshl_add_u64 v[92:93], v[22:23], 0, v[2:3]
	v_or_b32_e32 v2, s1, v49
	v_lshlrev_b32_e32 v2, 12, v2
	v_lshl_add_u64 v[94:95], v[22:23], 0, v[2:3]
	v_or_b32_e32 v2, s1, v50
	v_lshlrev_b32_e32 v2, 12, v2
	v_lshl_add_u64 v[96:97], v[22:23], 0, v[2:3]
	v_or_b32_e32 v2, s1, v51
	v_lshlrev_b32_e32 v2, 12, v2
	v_lshl_add_u64 v[98:99], v[22:23], 0, v[2:3]
	v_or_b32_e32 v2, s1, v52
	v_lshlrev_b32_e32 v2, 12, v2
	v_lshl_add_u64 v[100:101], v[22:23], 0, v[2:3]
	v_or_b32_e32 v2, s1, v53
	v_lshlrev_b32_e32 v2, 12, v2
	v_lshl_add_u64 v[102:103], v[22:23], 0, v[2:3]
	v_or_b32_e32 v2, s1, v54
	v_lshlrev_b32_e32 v2, 12, v2
	global_load_dword v120, v[24:25], off nt
	global_load_dword v121, v[90:91], off nt
	global_load_dword v122, v[92:93], off nt
	global_load_dword v123, v[94:95], off nt
	global_load_dword v124, v[96:97], off nt
	global_load_dword v125, v[98:99], off nt
	global_load_dword v126, v[100:101], off nt
	s_nop 0
	global_load_dword v102, v[102:103], off nt
	v_lshl_add_u64 v[24:25], v[22:23], 0, v[2:3]
	v_or_b32_e32 v2, s1, v56
	v_lshlrev_b32_e32 v2, 12, v2
	v_lshl_add_u64 v[90:91], v[22:23], 0, v[2:3]
	v_or_b32_e32 v2, s1, v57
	v_lshlrev_b32_e32 v2, 12, v2
	v_lshl_add_u64 v[92:93], v[22:23], 0, v[2:3]
	v_or_b32_e32 v2, s1, v58
	v_lshlrev_b32_e32 v2, 12, v2
	v_lshl_add_u64 v[94:95], v[22:23], 0, v[2:3]
	v_or_b32_e32 v2, s1, v59
	v_lshlrev_b32_e32 v2, 12, v2
	v_lshl_add_u64 v[96:97], v[22:23], 0, v[2:3]
	v_or_b32_e32 v2, s1, v60
	v_lshlrev_b32_e32 v2, 12, v2
	v_lshl_add_u64 v[98:99], v[22:23], 0, v[2:3]
	v_or_b32_e32 v2, s1, v61
	v_lshlrev_b32_e32 v2, 12, v2
	v_lshl_add_u64 v[100:101], v[22:23], 0, v[2:3]
	v_or_b32_e32 v2, s1, v62
	v_lshlrev_b32_e32 v2, 12, v2
	v_lshl_add_u64 v[22:23], v[22:23], 0, v[2:3]
	global_load_dword v2, v[24:25], off nt
	s_nop 0
	global_load_dword v24, v[90:91], off nt
	global_load_dword v25, v[92:93], off nt
	s_nop 0
	global_load_dword v90, v[94:95], off nt
	global_load_dword v91, v[96:97], off nt
	global_load_dword v92, v[98:99], off nt
	global_load_dword v93, v[100:101], off nt
	s_nop 0
	global_load_dword v22, v[22:23], off nt
	v_add_u32_e32 v23, v26, v27
	s_waitcnt vmcnt(30)
	ds_write2_b32 v23, v104, v105 offset1:66
	s_waitcnt vmcnt(28)
	ds_write2_b32 v23, v106, v107 offset0:132 offset1:198
	v_add_u32_e32 v23, 0x400, v23
	s_waitcnt vmcnt(26)
	ds_write2_b32 v23, v108, v109 offset0:8 offset1:74
	v_add_u32_e32 v23, v26, v34
	s_waitcnt vmcnt(24)
	ds_write2_b32 v23, v110, v111 offset1:66
	s_waitcnt vmcnt(22)
	ds_write2_b32 v23, v112, v113 offset0:132 offset1:198
	v_add_u32_e32 v23, 0x400, v23
	s_waitcnt vmcnt(20)
	ds_write2_b32 v23, v114, v115 offset0:8 offset1:74
	v_add_u32_e32 v23, v26, v41
	s_waitcnt vmcnt(18)
	ds_write2_b32 v23, v116, v117 offset1:66
	s_waitcnt vmcnt(16)
	ds_write2_b32 v23, v118, v119 offset0:132 offset1:198
	v_add_u32_e32 v23, 0x400, v23
	s_lshl_b32 s12, s1, 1
	s_waitcnt vmcnt(14)
	ds_write2_b32 v23, v120, v121 offset0:8 offset1:74
	v_add_u32_e32 v23, v26, v48
	s_waitcnt vmcnt(12)
	ds_write2_b32 v23, v122, v123 offset1:66
	s_waitcnt vmcnt(10)
	ds_write2_b32 v23, v124, v125 offset0:132 offset1:198
	v_add_u32_e32 v23, 0x400, v23
	s_waitcnt vmcnt(8)
	ds_write2_b32 v23, v126, v102 offset0:8 offset1:74
	v_add_u32_e32 v23, v26, v55
	s_waitcnt vmcnt(6)
	ds_write2_b32 v23, v2, v24 offset1:66
	s_waitcnt vmcnt(4)
	ds_write2_b32 v23, v25, v90 offset0:132 offset1:198
	v_add_u32_e32 v2, 0x400, v23
	s_waitcnt vmcnt(2)
	ds_write2_b32 v2, v91, v92 offset0:8 offset1:74
	s_waitcnt vmcnt(0)
	ds_write2_b32 v2, v93, v22 offset0:140 offset1:206
	s_waitcnt lgkmcnt(0)
	ds_read2_b32 v[22:23], v64 offset1:33
	s_waitcnt lgkmcnt(0)
	v_cvt_pk_bf16_f32 v22, v22, v23
	ds_read2_b32 v[24:25], v64 offset0:66 offset1:99
	v_or_b32_e32 v2, s0, v63
	s_waitcnt lgkmcnt(0)
	v_cvt_pk_bf16_f32 v23, v24, v25
	ds_read2_b32 v[24:25], v64 offset0:132 offset1:165
	v_lshl_add_u64 v[92:93], v[14:15], 0, s[12:13]
	v_lshlrev_b32_e32 v2, 11, v2
	s_waitcnt lgkmcnt(0)
	v_cvt_pk_bf16_f32 v24, v24, v25
	ds_read2_b32 v[90:91], v64 offset0:198 offset1:231
	s_waitcnt lgkmcnt(0)
	v_cvt_pk_bf16_f32 v25, v90, v91
	v_lshl_add_u64 v[94:95], v[92:93], 0, v[2:3]
	ds_read2_b32 v[90:91], v64 offset0:8 offset1:41
	global_store_dwordx4 v[94:95], v[22:25], off
	v_or_b32_e32 v2, s0, v65
	v_lshlrev_b32_e32 v2, 11, v2
	s_waitcnt lgkmcnt(0)
	v_cvt_pk_bf16_f32 v22, v90, v91
	ds_read2_b32 v[24:25], v64 offset0:74 offset1:107
	s_waitcnt lgkmcnt(0)
	v_cvt_pk_bf16_f32 v23, v24, v25
	ds_read2_b32 v[24:25], v64 offset0:140 offset1:173
	s_waitcnt lgkmcnt(0)
	v_cvt_pk_bf16_f32 v24, v24, v25
	ds_read2_b32 v[90:91], v64 offset0:206 offset1:239
	s_waitcnt lgkmcnt(0)
	v_cvt_pk_bf16_f32 v25, v90, v91
	v_lshl_add_u64 v[94:95], v[92:93], 0, v[2:3]
	ds_read2_b32 v[90:91], v64 offset0:16 offset1:49
	global_store_dwordx4 v[94:95], v[22:25], off
	v_or_b32_e32 v2, s0, v66
	v_lshlrev_b32_e32 v2, 11, v2
	s_waitcnt lgkmcnt(0)
	v_cvt_pk_bf16_f32 v22, v90, v91
	ds_read2_b32 v[24:25], v64 offset0:82 offset1:115
	s_waitcnt lgkmcnt(0)
	v_cvt_pk_bf16_f32 v23, v24, v25
	ds_read2_b32 v[24:25], v64 offset0:148 offset1:181
	s_waitcnt lgkmcnt(0)
	v_cvt_pk_bf16_f32 v24, v24, v25
	ds_read2_b32 v[90:91], v64 offset0:214 offset1:247
	s_waitcnt lgkmcnt(0)
	v_cvt_pk_bf16_f32 v25, v90, v91
	v_lshl_add_u64 v[94:95], v[92:93], 0, v[2:3]
	ds_read2_b32 v[90:91], v64 offset0:24 offset1:57
	global_store_dwordx4 v[94:95], v[22:25], off
	v_or_b32_e32 v2, s0, v67
	v_lshlrev_b32_e32 v2, 11, v2
	s_waitcnt lgkmcnt(0)
	v_cvt_pk_bf16_f32 v22, v90, v91
	ds_read2_b32 v[24:25], v64 offset0:90 offset1:123
	s_waitcnt lgkmcnt(0)
	v_cvt_pk_bf16_f32 v23, v24, v25
	ds_read2_b32 v[24:25], v64 offset0:156 offset1:189
	s_waitcnt lgkmcnt(0)
	v_cvt_pk_bf16_f32 v24, v24, v25
	ds_read2_b32 v[90:91], v64 offset0:222 offset1:255
	s_waitcnt lgkmcnt(0)
	v_cvt_pk_bf16_f32 v25, v90, v91
	v_lshl_add_u64 v[90:91], v[92:93], 0, v[2:3]
	global_store_dwordx4 v[90:91], v[22:25], off
	s_waitcnt lgkmcnt(0)

.LBB0_555:
	s_andn2_b64 vcc, exec, s[0:1]
	s_cbranch_vccnz .LBB0_557
	s_add_i32 s0, s30, 0xfc00
	s_and_b32 s1, s0, 0xffc0
	s_and_b32 s0, s30, 63
	s_lshl_b32 s12, s0, 7
	v_or_b32_e32 v90, s1, v0
	v_lshl_add_u64 v[22:23], v[16:17], 0, s[12:13]
	v_lshlrev_b32_e32 v2, 13, v90
	v_lshl_add_u64 v[24:25], v[22:23], 0, v[2:3]
	v_lshlrev_b32_e32 v2, 2, v90
	v_or_b32_e32 v92, s1, v28
	global_load_dword v90, v2, s[20:21] nt
	v_lshlrev_b32_e32 v2, 13, v92
	global_load_dword v91, v[24:25], off nt
	v_lshl_add_u64 v[24:25], v[22:23], 0, v[2:3]
	v_lshlrev_b32_e32 v2, 2, v92
	v_or_b32_e32 v94, s1, v29
	global_load_dword v92, v2, s[20:21] nt
	v_lshlrev_b32_e32 v2, 13, v94
	global_load_dword v93, v[24:25], off nt
	v_lshl_add_u64 v[24:25], v[22:23], 0, v[2:3]
	v_lshlrev_b32_e32 v2, 2, v94
	v_or_b32_e32 v96, s1, v30
	global_load_dword v94, v2, s[20:21] nt
	v_lshlrev_b32_e32 v2, 13, v96
	global_load_dword v95, v[24:25], off nt
	v_lshl_add_u64 v[24:25], v[22:23], 0, v[2:3]
	v_lshlrev_b32_e32 v2, 2, v96
	v_or_b32_e32 v98, s1, v31
	global_load_dword v96, v2, s[20:21] nt
	v_lshlrev_b32_e32 v2, 13, v98
	global_load_dword v97, v[24:25], off nt
	v_lshl_add_u64 v[24:25], v[22:23], 0, v[2:3]
	v_lshlrev_b32_e32 v2, 2, v98
	v_or_b32_e32 v100, s1, v32
	global_load_dword v98, v2, s[20:21] nt
	v_lshlrev_b32_e32 v2, 13, v100
	global_load_dword v99, v[24:25], off nt
	v_lshl_add_u64 v[24:25], v[22:23], 0, v[2:3]
	v_lshlrev_b32_e32 v2, 2, v100
	v_or_b32_e32 v102, s1, v33
	global_load_dword v100, v2, s[20:21] nt
	v_lshlrev_b32_e32 v2, 13, v102
	global_load_dword v101, v[24:25], off nt
	v_lshl_add_u64 v[24:25], v[22:23], 0, v[2:3]
	v_lshlrev_b32_e32 v2, 2, v102
	v_or_b32_e32 v104, s1, v35
	global_load_dword v102, v2, s[20:21] nt
	v_lshlrev_b32_e32 v2, 13, v104
	global_load_dword v103, v[24:25], off nt
	v_lshl_add_u64 v[24:25], v[22:23], 0, v[2:3]
	v_lshlrev_b32_e32 v2, 2, v104
	v_or_b32_e32 v106, s1, v36
	global_load_dword v104, v2, s[20:21] nt
	v_lshlrev_b32_e32 v2, 13, v106
	global_load_dword v105, v[24:25], off nt
	v_lshl_add_u64 v[24:25], v[22:23], 0, v[2:3]
	v_lshlrev_b32_e32 v2, 2, v106
	v_or_b32_e32 v108, s1, v37
	global_load_dword v106, v2, s[20:21] nt
	v_lshlrev_b32_e32 v2, 13, v108
	global_load_dword v107, v[24:25], off nt
	v_lshl_add_u64 v[24:25], v[22:23], 0, v[2:3]
	v_lshlrev_b32_e32 v2, 2, v108
	v_or_b32_e32 v110, s1, v38
	global_load_dword v108, v2, s[20:21] nt
	v_lshlrev_b32_e32 v2, 13, v110
	global_load_dword v109, v[24:25], off nt
	v_lshl_add_u64 v[24:25], v[22:23], 0, v[2:3]
	v_lshlrev_b32_e32 v2, 2, v110
	v_or_b32_e32 v112, s1, v39
	global_load_dword v110, v2, s[20:21] nt
	v_lshlrev_b32_e32 v2, 13, v112
	global_load_dword v111, v[24:25], off nt
	v_lshl_add_u64 v[24:25], v[22:23], 0, v[2:3]
	v_lshlrev_b32_e32 v2, 2, v112
	v_or_b32_e32 v114, s1, v40
	global_load_dword v112, v2, s[20:21] nt
	v_lshlrev_b32_e32 v2, 13, v114
	global_load_dword v113, v[24:25], off nt
	v_lshl_add_u64 v[24:25], v[22:23], 0, v[2:3]
	v_lshlrev_b32_e32 v2, 2, v114
	v_or_b32_e32 v116, s1, v42
	global_load_dword v114, v2, s[20:21] nt
	v_lshlrev_b32_e32 v2, 13, v116
	global_load_dword v115, v[24:25], off nt
	v_lshl_add_u64 v[24:25], v[22:23], 0, v[2:3]
	v_lshlrev_b32_e32 v2, 2, v116
	v_or_b32_e32 v118, s1, v43
	global_load_dword v116, v2, s[20:21] nt
	v_lshlrev_b32_e32 v2, 13, v118
	global_load_dword v117, v[24:25], off nt
	v_lshl_add_u64 v[24:25], v[22:23], 0, v[2:3]
	v_lshlrev_b32_e32 v2, 2, v118
	v_or_b32_e32 v120, s1, v44
	global_load_dword v118, v2, s[20:21] nt
	v_lshlrev_b32_e32 v2, 13, v120
	global_load_dword v119, v[24:25], off nt
	v_lshl_add_u64 v[24:25], v[22:23], 0, v[2:3]
	v_lshlrev_b32_e32 v2, 2, v120
	v_or_b32_e32 v122, s1, v45
	global_load_dword v120, v2, s[20:21] nt
	v_lshlrev_b32_e32 v2, 13, v122
	global_load_dword v121, v[24:25], off nt
	v_lshl_add_u64 v[24:25], v[22:23], 0, v[2:3]
	v_lshlrev_b32_e32 v2, 2, v122
	v_or_b32_e32 v124, s1, v46
	global_load_dword v122, v2, s[20:21] nt
	v_lshlrev_b32_e32 v2, 13, v124
	global_load_dword v123, v[24:25], off nt
	v_lshl_add_u64 v[24:25], v[22:23], 0, v[2:3]
	v_lshlrev_b32_e32 v2, 2, v124
	v_or_b32_e32 v126, s1, v47
	global_load_dword v124, v2, s[20:21] nt
	v_lshlrev_b32_e32 v2, 13, v126
	global_load_dword v125, v[24:25], off nt
	v_lshl_add_u64 v[24:25], v[22:23], 0, v[2:3]
	v_lshlrev_b32_e32 v2, 2, v126
	v_or_b32_e32 v129, s1, v49
	global_load_dword v126, v2, s[20:21] nt
	v_lshlrev_b32_e32 v2, 13, v129
	global_load_dword v127, v[24:25], off nt
	v_lshl_add_u64 v[24:25], v[22:23], 0, v[2:3]
	v_lshlrev_b32_e32 v2, 2, v129
	v_or_b32_e32 v131, s1, v50
	global_load_dword v129, v2, s[20:21] nt
	v_lshlrev_b32_e32 v2, 13, v131
	global_load_dword v130, v[24:25], off nt
	v_lshl_add_u64 v[24:25], v[22:23], 0, v[2:3]
	v_lshlrev_b32_e32 v2, 2, v131
	v_or_b32_e32 v133, s1, v51
	global_load_dword v131, v2, s[20:21] nt
	v_lshlrev_b32_e32 v2, 13, v133
	global_load_dword v132, v[24:25], off nt
	v_lshl_add_u64 v[24:25], v[22:23], 0, v[2:3]
	v_lshlrev_b32_e32 v2, 2, v133
	v_or_b32_e32 v135, s1, v52
	global_load_dword v133, v2, s[20:21] nt
	v_lshlrev_b32_e32 v2, 13, v135
	global_load_dword v134, v[24:25], off nt
	v_lshl_add_u64 v[24:25], v[22:23], 0, v[2:3]
	v_lshlrev_b32_e32 v2, 2, v135
	v_or_b32_e32 v137, s1, v53
	global_load_dword v135, v2, s[20:21] nt
	v_lshlrev_b32_e32 v2, 13, v137
	global_load_dword v136, v[24:25], off nt
	v_lshl_add_u64 v[24:25], v[22:23], 0, v[2:3]
	v_lshlrev_b32_e32 v2, 2, v137
	v_or_b32_e32 v139, s1, v54
	global_load_dword v137, v2, s[20:21] nt
	v_lshlrev_b32_e32 v2, 13, v139
	global_load_dword v138, v[24:25], off nt
	v_lshl_add_u64 v[24:25], v[22:23], 0, v[2:3]
	v_lshlrev_b32_e32 v2, 2, v139
	v_or_b32_e32 v141, s1, v56
	global_load_dword v139, v2, s[20:21] nt
	v_lshlrev_b32_e32 v2, 13, v141
	global_load_dword v140, v[24:25], off nt
	v_lshl_add_u64 v[24:25], v[22:23], 0, v[2:3]
	v_lshlrev_b32_e32 v2, 2, v141
	v_or_b32_e32 v143, s1, v57
	global_load_dword v141, v2, s[20:21] nt
	v_lshlrev_b32_e32 v2, 13, v143
	global_load_dword v142, v[24:25], off nt
	v_lshl_add_u64 v[24:25], v[22:23], 0, v[2:3]
	v_lshlrev_b32_e32 v2, 2, v143
	v_or_b32_e32 v145, s1, v58
	global_load_dword v143, v2, s[20:21] nt
	v_lshlrev_b32_e32 v2, 13, v145
	global_load_dword v144, v[24:25], off nt
	v_lshl_add_u64 v[24:25], v[22:23], 0, v[2:3]
	v_lshlrev_b32_e32 v2, 2, v145
	v_or_b32_e32 v147, s1, v59
	global_load_dword v145, v2, s[20:21] nt
	v_lshlrev_b32_e32 v2, 13, v147
	global_load_dword v146, v[24:25], off nt
	v_lshl_add_u64 v[24:25], v[22:23], 0, v[2:3]
	v_lshlrev_b32_e32 v2, 2, v147
	v_or_b32_e32 v150, s1, v60
	global_load_dword v147, v2, s[20:21] nt
	v_lshlrev_b32_e32 v2, 13, v150
	global_load_dword v149, v[24:25], off nt
	v_lshl_add_u64 v[24:25], v[22:23], 0, v[2:3]
	v_lshlrev_b32_e32 v2, 2, v150
	v_or_b32_e32 v152, s1, v61
	global_load_dword v150, v2, s[20:21] nt
	v_lshlrev_b32_e32 v2, 13, v152
	global_load_dword v151, v[24:25], off nt
	v_lshl_add_u64 v[24:25], v[22:23], 0, v[2:3]
	v_lshlrev_b32_e32 v2, 2, v152
	v_or_b32_e32 v152, s1, v62
	global_load_dword v24, v[24:25], off nt
	s_lshl_b32 s4, s0, 5
	global_load_dword v25, v2, s[20:21] nt
	v_lshlrev_b32_e32 v2, 13, v152
	v_lshl_add_u64 v[22:23], v[22:23], 0, v[2:3]
	global_load_dword v2, v[22:23], off nt
	v_lshlrev_b32_e32 v22, 2, v152
	global_load_dword v22, v22, s[20:21] nt
	s_waitcnt vmcnt(62)
	v_mul_f32_e32 v23, v91, v90
	v_add_u32_e32 v90, v26, v27
	s_waitcnt vmcnt(60)
	v_mul_f32_e32 v91, v93, v92
	ds_write2_b32 v90, v23, v91 offset1:66
	s_waitcnt vmcnt(58)
	v_mul_f32_e32 v23, v95, v94
	s_waitcnt vmcnt(56)
	v_mul_f32_e32 v91, v97, v96
	ds_write2_b32 v90, v23, v91 offset0:132 offset1:198
	s_waitcnt vmcnt(54)
	v_mul_f32_e32 v23, v99, v98
	s_waitcnt vmcnt(52)
	v_mul_f32_e32 v91, v101, v100
	v_add_u32_e32 v90, 0x400, v90
	ds_write2_b32 v90, v23, v91 offset0:8 offset1:74
	s_waitcnt vmcnt(50)
	v_mul_f32_e32 v23, v103, v102
	v_add_u32_e32 v90, v26, v34
	s_waitcnt vmcnt(48)
	v_mul_f32_e32 v91, v105, v104
	ds_write2_b32 v90, v23, v91 offset1:66
	s_waitcnt vmcnt(46)
	v_mul_f32_e32 v23, v107, v106
	s_waitcnt vmcnt(44)
	v_mul_f32_e32 v91, v109, v108
	ds_write2_b32 v90, v23, v91 offset0:132 offset1:198
	s_waitcnt vmcnt(42)
	v_mul_f32_e32 v23, v111, v110
	s_waitcnt vmcnt(40)
	v_mul_f32_e32 v91, v113, v112
	v_add_u32_e32 v90, 0x400, v90
	ds_write2_b32 v90, v23, v91 offset0:8 offset1:74
	s_waitcnt vmcnt(38)
	v_mul_f32_e32 v23, v115, v114
	v_add_u32_e32 v90, v26, v41
	s_waitcnt vmcnt(36)
	v_mul_f32_e32 v91, v117, v116
	ds_write2_b32 v90, v23, v91 offset1:66
	s_waitcnt vmcnt(34)
	v_mul_f32_e32 v23, v119, v118
	s_waitcnt vmcnt(32)
	v_mul_f32_e32 v91, v121, v120
	ds_write2_b32 v90, v23, v91 offset0:132 offset1:198
	s_waitcnt vmcnt(30)
	v_mul_f32_e32 v23, v123, v122
	s_waitcnt vmcnt(28)
	v_mul_f32_e32 v91, v125, v124
	v_add_u32_e32 v90, 0x400, v90
	ds_write2_b32 v90, v23, v91 offset0:8 offset1:74
	s_waitcnt vmcnt(26)
	v_mul_f32_e32 v23, v127, v126
	v_add_u32_e32 v90, v26, v48
	s_waitcnt vmcnt(24)
	v_mul_f32_e32 v91, v130, v129
	ds_write2_b32 v90, v23, v91 offset1:66
	s_waitcnt vmcnt(22)
	v_mul_f32_e32 v23, v132, v131
	s_waitcnt vmcnt(20)
	v_mul_f32_e32 v91, v134, v133
	ds_write2_b32 v90, v23, v91 offset0:132 offset1:198
	s_waitcnt vmcnt(18)
	v_mul_f32_e32 v23, v136, v135
	s_waitcnt vmcnt(16)
	v_mul_f32_e32 v91, v138, v137
	v_add_u32_e32 v90, 0x400, v90
	ds_write2_b32 v90, v23, v91 offset0:8 offset1:74
	s_waitcnt vmcnt(14)
	v_mul_f32_e32 v23, v140, v139
	v_add_u32_e32 v90, v26, v55
	s_waitcnt vmcnt(12)
	v_mul_f32_e32 v91, v142, v141
	ds_write2_b32 v90, v23, v91 offset1:66
	s_and_b32 s5, s4, 0x7c0
	s_lshl_b32 s12, s1, 1
	s_waitcnt vmcnt(10)
	v_mul_f32_e32 v23, v144, v143
	s_cmp_lt_u32 s0, 32
	s_cselect_b64 s[0:1], -1, 0
	v_or_b32_e32 v96, s5, v68
	s_and_b64 vcc, s[0:1], s[24:25]
	v_lshl_add_u64 v[92:93], v[18:19], 0, s[12:13]
	s_waitcnt vmcnt(8)
	v_mul_f32_e32 v91, v146, v145
	ds_write2_b32 v90, v23, v91 offset0:132 offset1:198
	v_add_u32_e32 v90, 0x400, v90
	s_waitcnt vmcnt(6)
	v_mul_f32_e32 v23, v149, v147
	s_waitcnt vmcnt(4)
	v_mul_f32_e32 v91, v151, v150
	ds_write2_b32 v90, v23, v91 offset0:8 offset1:74
	s_waitcnt vmcnt(2)
	v_mul_f32_e32 v23, v24, v25
	s_waitcnt vmcnt(0)
	v_mul_f32_e32 v2, v2, v22
	ds_write2_b32 v90, v23, v2 offset0:140 offset1:206
	s_waitcnt lgkmcnt(0)
	ds_read2_b32 v[22:23], v64 offset1:33
	s_waitcnt lgkmcnt(0)
	v_cvt_pk_bf16_f32 v22, v22, v23
	ds_read2_b32 v[24:25], v64 offset0:66 offset1:99
	v_or_b32_e32 v2, s4, v63
	s_waitcnt lgkmcnt(0)
	v_cvt_pk_bf16_f32 v23, v24, v25
	ds_read2_b32 v[24:25], v64 offset0:132 offset1:165
	v_cndmask_b32_e32 v2, v2, v96, vcc
	s_waitcnt lgkmcnt(0)
	v_cvt_pk_bf16_f32 v24, v24, v25
	ds_read2_b32 v[90:91], v64 offset0:198 offset1:231
	v_lshlrev_b32_e32 v2, 11, v2
	s_waitcnt lgkmcnt(0)
	v_cvt_pk_bf16_f32 v25, v90, v91
	v_lshl_add_u64 v[90:91], v[92:93], 0, v[2:3]
	v_add_co_u32_e64 v90, s[0:1], s28, v90
	ds_read2_b32 v[94:95], v64 offset0:8 offset1:41
	s_nop 0
	v_addc_co_u32_e64 v91, s[0:1], 0, v91, s[0:1]
	global_store_dwordx4 v[90:91], v[22:25], off
	v_or_b32_e32 v2, s4, v65
	s_waitcnt lgkmcnt(0)
	v_cvt_pk_bf16_f32 v22, v94, v95
	v_or_b32_e32 v94, 1, v96
	ds_read2_b32 v[24:25], v64 offset0:74 offset1:107
	v_cndmask_b32_e32 v2, v2, v94, vcc
	s_waitcnt lgkmcnt(0)
	v_cvt_pk_bf16_f32 v23, v24, v25
	ds_read2_b32 v[24:25], v64 offset0:140 offset1:173
	v_lshl_or_b32 v2, v2, 11, v89
	s_waitcnt lgkmcnt(0)
	v_cvt_pk_bf16_f32 v24, v24, v25
	ds_read2_b32 v[90:91], v64 offset0:206 offset1:239
	s_waitcnt lgkmcnt(0)
	v_cvt_pk_bf16_f32 v25, v90, v91
	v_lshl_add_u64 v[94:95], v[92:93], 0, v[2:3]
	ds_read2_b32 v[90:91], v64 offset0:16 offset1:49
	global_store_dwordx4 v[94:95], v[22:25], off
	v_or_b32_e32 v2, s4, v66
	v_lshlrev_b32_e32 v2, 11, v2
	s_waitcnt lgkmcnt(0)
	v_cvt_pk_bf16_f32 v22, v90, v91
	ds_read2_b32 v[24:25], v64 offset0:82 offset1:115
	s_waitcnt lgkmcnt(0)
	v_cvt_pk_bf16_f32 v23, v24, v25
	ds_read2_b32 v[24:25], v64 offset0:148 offset1:181
	s_waitcnt lgkmcnt(0)
	v_cvt_pk_bf16_f32 v24, v24, v25
	ds_read2_b32 v[90:91], v64 offset0:214 offset1:247
	s_waitcnt lgkmcnt(0)
	v_cvt_pk_bf16_f32 v25, v90, v91
	v_lshl_add_u64 v[90:91], v[92:93], 0, v[2:3]
	v_add_co_u32_e32 v90, vcc, s28, v90
	ds_read2_b32 v[94:95], v64 offset0:24 offset1:57
	s_nop 0
	v_addc_co_u32_e32 v91, vcc, 0, v91, vcc
	global_store_dwordx4 v[90:91], v[22:25], off
	v_or_b32_e32 v2, s4, v67
	v_lshlrev_b32_e32 v2, 11, v2
	s_waitcnt lgkmcnt(0)
	v_cvt_pk_bf16_f32 v22, v94, v95
	ds_read2_b32 v[24:25], v64 offset0:90 offset1:123
	s_waitcnt lgkmcnt(0)
	v_cvt_pk_bf16_f32 v23, v24, v25
	ds_read2_b32 v[24:25], v64 offset0:156 offset1:189
	s_waitcnt lgkmcnt(0)
	v_cvt_pk_bf16_f32 v24, v24, v25
	ds_read2_b32 v[90:91], v64 offset0:222 offset1:255
	s_waitcnt lgkmcnt(0)
	v_cvt_pk_bf16_f32 v25, v90, v91
	v_lshl_add_u64 v[90:91], v[92:93], 0, v[2:3]
	v_add_co_u32_e32 v90, vcc, 0x400000, v90
	s_nop 1
	v_addc_co_u32_e32 v91, vcc, 0, v91, vcc
	global_store_dwordx4 v[90:91], v[22:25], off
	s_waitcnt lgkmcnt(0)

.LBB0_558:
	s_andn2_b64 vcc, exec, s[0:1]
	s_cbranch_vccnz .LBB0_543
	s_ashr_i32 s0, s30, 31
	s_lshr_b32 s0, s0, 26
	s_add_i32 s0, s30, s0
	s_ashr_i32 s1, s0, 6
	s_andn2_b32 s0, s0, 63
	s_lshl_b32 s12, s1, 11
	s_sub_i32 s26, s9, s12
	v_or_b32_e32 v24, s0, v0
	s_ashr_i32 s27, s26, 31
	v_ashrrev_i32_e32 v25, 31, v24
	v_lshl_add_u64 v[22:23], s[26:27], 2, v[20:21]
	v_lshlrev_b64 v[90:91], 13, v[24:25]
	v_lshl_add_u64 v[90:91], v[22:23], 0, v[90:91]
	global_load_dword v90, v[90:91], off nt
	v_cndmask_b32_e64 v2, 0, 1, s[22:23]
	v_cmp_ne_u32_e64 s[6:7], 1, v2
	s_andn2_b64 vcc, exec, s[22:23]
	s_cbranch_vccnz .LBB0_561
	v_readlane_b32 s36, v254, 30
	v_readlane_b32 s40, v254, 34
	v_readlane_b32 s41, v254, 35
	v_readlane_b32 s37, v254, 31
	v_readlane_b32 s38, v254, 32
	v_lshl_add_u64 v[24:25], v[24:25], 2, s[40:41]
	global_load_dword v2, v[24:25], off nt
	v_readlane_b32 s39, v254, 33
	v_readlane_b32 s42, v254, 36
	v_readlane_b32 s43, v254, 37
	v_readlane_b32 s44, v254, 38
	v_readlane_b32 s45, v254, 39
	v_readlane_b32 s46, v254, 40
	v_readlane_b32 s47, v254, 41
	v_readlane_b32 s48, v254, 42
	v_readlane_b32 s49, v254, 43
	v_readlane_b32 s50, v254, 44
	v_readlane_b32 s51, v254, 45
	s_waitcnt vmcnt(0)
	v_mul_f32_e32 v90, v90, v2
.LBB0_561:
	v_or_b32_e32 v24, s0, v28
	v_ashrrev_i32_e32 v25, 31, v24
	v_lshlrev_b64 v[24:25], 13, v[24:25]
	v_lshl_add_u64 v[24:25], v[22:23], 0, v[24:25]
	global_load_dword v2, v[24:25], off nt
	v_add_u32_e32 v24, v26, v27
	s_and_b64 vcc, exec, s[6:7]
	s_waitcnt vmcnt(1)
	ds_write_b32 v24, v90
	s_cbranch_vccnz .LBB0_563
	s_ashr_i32 s1, s0, 31
	v_readlane_b32 s36, v254, 30
	v_lshl_add_u64 v[24:25], s[0:1], 0, v[0:1]
	v_readlane_b32 s40, v254, 34
	v_readlane_b32 s41, v254, 35
	v_readlane_b32 s37, v254, 31
	v_readlane_b32 s38, v254, 32
	v_lshl_add_u64 v[24:25], v[24:25], 2, s[40:41]
	global_load_dword v24, v[24:25], off offset:8 nt
	v_readlane_b32 s39, v254, 33
	v_readlane_b32 s42, v254, 36
	v_readlane_b32 s43, v254, 37
	v_readlane_b32 s44, v254, 38
	v_readlane_b32 s45, v254, 39
	v_readlane_b32 s46, v254, 40
	v_readlane_b32 s47, v254, 41
	v_readlane_b32 s48, v254, 42
	v_readlane_b32 s49, v254, 43
	v_readlane_b32 s50, v254, 44
	v_readlane_b32 s51, v254, 45
	s_waitcnt vmcnt(0)
	v_mul_f32_e32 v2, v2, v24
.LBB0_563:
	v_or_b32_e32 v24, s0, v29
	v_ashrrev_i32_e32 v25, 31, v24
	v_lshlrev_b64 v[24:25], 13, v[24:25]
	v_lshl_add_u64 v[24:25], v[22:23], 0, v[24:25]
	global_load_dword v24, v[24:25], off nt
	s_and_b64 vcc, exec, s[6:7]
	s_waitcnt vmcnt(1)
	ds_write_b32 v69, v2
	s_cbranch_vccnz .LBB0_565
	s_ashr_i32 s1, s0, 31
	v_readlane_b32 s36, v254, 30
	v_lshl_add_u64 v[90:91], s[0:1], 0, v[0:1]
	v_readlane_b32 s40, v254, 34
	v_readlane_b32 s41, v254, 35
	v_readlane_b32 s37, v254, 31
	v_readlane_b32 s38, v254, 32
	v_lshl_add_u64 v[90:91], v[90:91], 2, s[40:41]
	global_load_dword v2, v[90:91], off offset:16 nt
	v_readlane_b32 s39, v254, 33
	v_readlane_b32 s42, v254, 36
	v_readlane_b32 s43, v254, 37
	v_readlane_b32 s44, v254, 38
	v_readlane_b32 s45, v254, 39
	v_readlane_b32 s46, v254, 40
	v_readlane_b32 s47, v254, 41
	v_readlane_b32 s48, v254, 42
	v_readlane_b32 s49, v254, 43
	v_readlane_b32 s50, v254, 44
	v_readlane_b32 s51, v254, 45
	s_waitcnt vmcnt(0)
	v_mul_f32_e32 v24, v24, v2
.LBB0_565:
	v_or_b32_e32 v90, s0, v30
	v_ashrrev_i32_e32 v91, 31, v90
	v_lshlrev_b64 v[90:91], 13, v[90:91]
	v_lshl_add_u64 v[90:91], v[22:23], 0, v[90:91]
	global_load_dword v2, v[90:91], off nt
	s_and_b64 vcc, exec, s[6:7]
	s_waitcnt vmcnt(1)
	ds_write_b32 v70, v24
	s_cbranch_vccnz .LBB0_567
	s_ashr_i32 s1, s0, 31
	v_readlane_b32 s36, v254, 30
	v_lshl_add_u64 v[24:25], s[0:1], 0, v[0:1]
	v_readlane_b32 s40, v254, 34
	v_readlane_b32 s41, v254, 35
	v_readlane_b32 s37, v254, 31
	v_readlane_b32 s38, v254, 32
	v_lshl_add_u64 v[24:25], v[24:25], 2, s[40:41]
	global_load_dword v24, v[24:25], off offset:24 nt
	v_readlane_b32 s39, v254, 33
	v_readlane_b32 s42, v254, 36
	v_readlane_b32 s43, v254, 37
	v_readlane_b32 s44, v254, 38
	v_readlane_b32 s45, v254, 39
	v_readlane_b32 s46, v254, 40
	v_readlane_b32 s47, v254, 41
	v_readlane_b32 s48, v254, 42
	v_readlane_b32 s49, v254, 43
	v_readlane_b32 s50, v254, 44
	v_readlane_b32 s51, v254, 45
	s_waitcnt vmcnt(0)
	v_mul_f32_e32 v2, v2, v24
.LBB0_567:
	v_or_b32_e32 v24, s0, v31
	v_ashrrev_i32_e32 v25, 31, v24
	v_lshlrev_b64 v[24:25], 13, v[24:25]
	v_lshl_add_u64 v[24:25], v[22:23], 0, v[24:25]
	global_load_dword v24, v[24:25], off nt
	s_and_b64 vcc, exec, s[6:7]
	s_waitcnt vmcnt(1)
	ds_write_b32 v71, v2
	s_cbranch_vccnz .LBB0_569
	s_ashr_i32 s1, s0, 31
	v_readlane_b32 s36, v254, 30
	v_lshl_add_u64 v[90:91], s[0:1], 0, v[0:1]
	v_readlane_b32 s40, v254, 34
	v_readlane_b32 s41, v254, 35
	v_readlane_b32 s37, v254, 31
	v_readlane_b32 s38, v254, 32
	v_lshl_add_u64 v[90:91], v[90:91], 2, s[40:41]
	global_load_dword v2, v[90:91], off offset:32 nt
	v_readlane_b32 s39, v254, 33
	v_readlane_b32 s42, v254, 36
	v_readlane_b32 s43, v254, 37
	v_readlane_b32 s44, v254, 38
	v_readlane_b32 s45, v254, 39
	v_readlane_b32 s46, v254, 40
	v_readlane_b32 s47, v254, 41
	v_readlane_b32 s48, v254, 42
	v_readlane_b32 s49, v254, 43
	v_readlane_b32 s50, v254, 44
	v_readlane_b32 s51, v254, 45
	s_waitcnt vmcnt(0)
	v_mul_f32_e32 v24, v24, v2
.LBB0_569:
	v_or_b32_e32 v90, s0, v32
	v_ashrrev_i32_e32 v91, 31, v90
	v_lshlrev_b64 v[90:91], 13, v[90:91]
	v_lshl_add_u64 v[90:91], v[22:23], 0, v[90:91]
	global_load_dword v25, v[90:91], off nt
	s_and_b64 vcc, exec, s[6:7]
	s_waitcnt vmcnt(1)
	ds_write_b32 v72, v24
	s_cbranch_vccnz .LBB0_571
	s_ashr_i32 s1, s0, 31
	v_readlane_b32 s36, v254, 30
	v_lshl_add_u64 v[90:91], s[0:1], 0, v[0:1]
	v_readlane_b32 s40, v254, 34
	v_readlane_b32 s41, v254, 35
	v_readlane_b32 s37, v254, 31
	v_readlane_b32 s38, v254, 32
	v_lshl_add_u64 v[90:91], v[90:91], 2, s[40:41]
	global_load_dword v2, v[90:91], off offset:40 nt
	v_readlane_b32 s39, v254, 33
	v_readlane_b32 s42, v254, 36
	v_readlane_b32 s43, v254, 37
	v_readlane_b32 s44, v254, 38
	v_readlane_b32 s45, v254, 39
	v_readlane_b32 s46, v254, 40
	v_readlane_b32 s47, v254, 41
	v_readlane_b32 s48, v254, 42
	v_readlane_b32 s49, v254, 43
	v_readlane_b32 s50, v254, 44
	v_readlane_b32 s51, v254, 45
	s_waitcnt vmcnt(0)
	v_mul_f32_e32 v25, v25, v2
.LBB0_571:
	v_or_b32_e32 v90, s0, v33
	v_ashrrev_i32_e32 v91, 31, v90
	v_lshlrev_b64 v[90:91], 13, v[90:91]
	v_lshl_add_u64 v[90:91], v[22:23], 0, v[90:91]
	global_load_dword v2, v[90:91], off nt
	s_and_b64 vcc, exec, s[6:7]
	s_waitcnt vmcnt(1)
	ds_write_b32 v73, v25
	s_cbranch_vccnz .LBB0_573
	s_ashr_i32 s1, s0, 31
	v_readlane_b32 s36, v254, 30
	v_lshl_add_u64 v[24:25], s[0:1], 0, v[0:1]
	v_readlane_b32 s40, v254, 34
	v_readlane_b32 s41, v254, 35
	v_readlane_b32 s37, v254, 31
	v_readlane_b32 s38, v254, 32
	v_lshl_add_u64 v[24:25], v[24:25], 2, s[40:41]
	global_load_dword v24, v[24:25], off offset:48 nt
	v_readlane_b32 s39, v254, 33
	v_readlane_b32 s42, v254, 36
	v_readlane_b32 s43, v254, 37
	v_readlane_b32 s44, v254, 38
	v_readlane_b32 s45, v254, 39
	v_readlane_b32 s46, v254, 40
	v_readlane_b32 s47, v254, 41
	v_readlane_b32 s48, v254, 42
	v_readlane_b32 s49, v254, 43
	v_readlane_b32 s50, v254, 44
	v_readlane_b32 s51, v254, 45
	s_waitcnt vmcnt(0)
	v_mul_f32_e32 v2, v2, v24
.LBB0_573:
	v_or_b32_e32 v24, s0, v35
	v_ashrrev_i32_e32 v25, 31, v24
	v_lshlrev_b64 v[24:25], 13, v[24:25]
	v_lshl_add_u64 v[24:25], v[22:23], 0, v[24:25]
	global_load_dword v24, v[24:25], off nt
	v_add_u32_e32 v25, v26, v34
	s_and_b64 vcc, exec, s[6:7]
	s_waitcnt vmcnt(1)
	ds_write_b32 v25, v2
	s_cbranch_vccnz .LBB0_575
	s_ashr_i32 s1, s0, 31
	v_readlane_b32 s36, v254, 30
	v_lshl_add_u64 v[90:91], s[0:1], 0, v[0:1]
	v_readlane_b32 s40, v254, 34
	v_readlane_b32 s41, v254, 35
	v_readlane_b32 s37, v254, 31
	v_readlane_b32 s38, v254, 32
	v_lshl_add_u64 v[90:91], v[90:91], 2, s[40:41]
	global_load_dword v2, v[90:91], off offset:56 nt
	v_readlane_b32 s39, v254, 33
	v_readlane_b32 s42, v254, 36
	v_readlane_b32 s43, v254, 37
	v_readlane_b32 s44, v254, 38
	v_readlane_b32 s45, v254, 39
	v_readlane_b32 s46, v254, 40
	v_readlane_b32 s47, v254, 41
	v_readlane_b32 s48, v254, 42
	v_readlane_b32 s49, v254, 43
	v_readlane_b32 s50, v254, 44
	v_readlane_b32 s51, v254, 45
	s_waitcnt vmcnt(0)
	v_mul_f32_e32 v24, v24, v2
.LBB0_575:
	v_or_b32_e32 v90, s0, v36
	v_ashrrev_i32_e32 v91, 31, v90
	v_lshlrev_b64 v[90:91], 13, v[90:91]
	v_lshl_add_u64 v[90:91], v[22:23], 0, v[90:91]
	global_load_dword v2, v[90:91], off nt
	s_and_b64 vcc, exec, s[6:7]
	s_waitcnt vmcnt(1)
	ds_write_b32 v74, v24
	s_cbranch_vccnz .LBB0_577
	s_ashr_i32 s1, s0, 31
	v_readlane_b32 s36, v254, 30
	v_lshl_add_u64 v[24:25], s[0:1], 0, v[0:1]
	v_readlane_b32 s40, v254, 34
	v_readlane_b32 s41, v254, 35
	v_readlane_b32 s37, v254, 31
	v_readlane_b32 s38, v254, 32
	v_lshl_add_u64 v[24:25], v[24:25], 2, s[40:41]
	global_load_dword v24, v[24:25], off offset:64 nt
	v_readlane_b32 s39, v254, 33
	v_readlane_b32 s42, v254, 36
	v_readlane_b32 s43, v254, 37
	v_readlane_b32 s44, v254, 38
	v_readlane_b32 s45, v254, 39
	v_readlane_b32 s46, v254, 40
	v_readlane_b32 s47, v254, 41
	v_readlane_b32 s48, v254, 42
	v_readlane_b32 s49, v254, 43
	v_readlane_b32 s50, v254, 44
	v_readlane_b32 s51, v254, 45
	s_waitcnt vmcnt(0)
	v_mul_f32_e32 v2, v2, v24
.LBB0_577:
	v_or_b32_e32 v24, s0, v37
	v_ashrrev_i32_e32 v25, 31, v24
	v_lshlrev_b64 v[24:25], 13, v[24:25]
	v_lshl_add_u64 v[24:25], v[22:23], 0, v[24:25]
	global_load_dword v24, v[24:25], off nt
	s_and_b64 vcc, exec, s[6:7]
	s_waitcnt vmcnt(1)
	ds_write_b32 v75, v2
	s_cbranch_vccnz .LBB0_579
	s_ashr_i32 s1, s0, 31
	v_readlane_b32 s36, v254, 30
	v_lshl_add_u64 v[90:91], s[0:1], 0, v[0:1]
	v_readlane_b32 s40, v254, 34
	v_readlane_b32 s41, v254, 35
	v_readlane_b32 s37, v254, 31
	v_readlane_b32 s38, v254, 32
	v_lshl_add_u64 v[90:91], v[90:91], 2, s[40:41]
	global_load_dword v2, v[90:91], off offset:72 nt
	v_readlane_b32 s39, v254, 33
	v_readlane_b32 s42, v254, 36
	v_readlane_b32 s43, v254, 37
	v_readlane_b32 s44, v254, 38
	v_readlane_b32 s45, v254, 39
	v_readlane_b32 s46, v254, 40
	v_readlane_b32 s47, v254, 41
	v_readlane_b32 s48, v254, 42
	v_readlane_b32 s49, v254, 43
	v_readlane_b32 s50, v254, 44
	v_readlane_b32 s51, v254, 45
	s_waitcnt vmcnt(0)
	v_mul_f32_e32 v24, v24, v2
.LBB0_579:
	v_or_b32_e32 v90, s0, v38
	v_ashrrev_i32_e32 v91, 31, v90
	v_lshlrev_b64 v[90:91], 13, v[90:91]
	v_lshl_add_u64 v[90:91], v[22:23], 0, v[90:91]
	global_load_dword v2, v[90:91], off nt
	s_and_b64 vcc, exec, s[6:7]
	s_waitcnt vmcnt(1)
	ds_write_b32 v76, v24
	s_cbranch_vccnz .LBB0_581
	s_ashr_i32 s1, s0, 31
	v_readlane_b32 s36, v254, 30
	v_lshl_add_u64 v[24:25], s[0:1], 0, v[0:1]
	v_readlane_b32 s40, v254, 34
	v_readlane_b32 s41, v254, 35
	v_readlane_b32 s37, v254, 31
	v_readlane_b32 s38, v254, 32
	v_lshl_add_u64 v[24:25], v[24:25], 2, s[40:41]
	global_load_dword v24, v[24:25], off offset:80 nt
	v_readlane_b32 s39, v254, 33
	v_readlane_b32 s42, v254, 36
	v_readlane_b32 s43, v254, 37
	v_readlane_b32 s44, v254, 38
	v_readlane_b32 s45, v254, 39
	v_readlane_b32 s46, v254, 40
	v_readlane_b32 s47, v254, 41
	v_readlane_b32 s48, v254, 42
	v_readlane_b32 s49, v254, 43
	v_readlane_b32 s50, v254, 44
	v_readlane_b32 s51, v254, 45
	s_waitcnt vmcnt(0)
	v_mul_f32_e32 v2, v2, v24
.LBB0_581:
	v_or_b32_e32 v24, s0, v39
	v_ashrrev_i32_e32 v25, 31, v24
	v_lshlrev_b64 v[24:25], 13, v[24:25]
	v_lshl_add_u64 v[24:25], v[22:23], 0, v[24:25]
	global_load_dword v24, v[24:25], off nt
	s_and_b64 vcc, exec, s[6:7]
	s_waitcnt vmcnt(1)
	ds_write_b32 v77, v2
	s_cbranch_vccnz .LBB0_583
	s_ashr_i32 s1, s0, 31
	v_readlane_b32 s36, v254, 30
	v_lshl_add_u64 v[90:91], s[0:1], 0, v[0:1]
	v_readlane_b32 s40, v254, 34
	v_readlane_b32 s41, v254, 35
	v_readlane_b32 s37, v254, 31
	v_readlane_b32 s38, v254, 32
	v_lshl_add_u64 v[90:91], v[90:91], 2, s[40:41]
	global_load_dword v2, v[90:91], off offset:88 nt
	v_readlane_b32 s39, v254, 33
	v_readlane_b32 s42, v254, 36
	v_readlane_b32 s43, v254, 37
	v_readlane_b32 s44, v254, 38
	v_readlane_b32 s45, v254, 39
	v_readlane_b32 s46, v254, 40
	v_readlane_b32 s47, v254, 41
	v_readlane_b32 s48, v254, 42
	v_readlane_b32 s49, v254, 43
	v_readlane_b32 s50, v254, 44
	v_readlane_b32 s51, v254, 45
	s_waitcnt vmcnt(0)
	v_mul_f32_e32 v24, v24, v2
.LBB0_583:
	v_or_b32_e32 v90, s0, v40
	v_ashrrev_i32_e32 v91, 31, v90
	v_lshlrev_b64 v[90:91], 13, v[90:91]
	v_lshl_add_u64 v[90:91], v[22:23], 0, v[90:91]
	global_load_dword v2, v[90:91], off nt
	s_and_b64 vcc, exec, s[6:7]
	s_waitcnt vmcnt(1)
	ds_write_b32 v78, v24
	s_cbranch_vccnz .LBB0_585
	s_ashr_i32 s1, s0, 31
	v_readlane_b32 s36, v254, 30
	v_lshl_add_u64 v[24:25], s[0:1], 0, v[0:1]
	v_readlane_b32 s40, v254, 34
	v_readlane_b32 s41, v254, 35
	v_readlane_b32 s37, v254, 31
	v_readlane_b32 s38, v254, 32
	v_lshl_add_u64 v[24:25], v[24:25], 2, s[40:41]
	global_load_dword v24, v[24:25], off offset:96 nt
	v_readlane_b32 s39, v254, 33
	v_readlane_b32 s42, v254, 36
	v_readlane_b32 s43, v254, 37
	v_readlane_b32 s44, v254, 38
	v_readlane_b32 s45, v254, 39
	v_readlane_b32 s46, v254, 40
	v_readlane_b32 s47, v254, 41
	v_readlane_b32 s48, v254, 42
	v_readlane_b32 s49, v254, 43
	v_readlane_b32 s50, v254, 44
	v_readlane_b32 s51, v254, 45
	s_waitcnt vmcnt(0)
	v_mul_f32_e32 v2, v2, v24
.LBB0_585:
	v_or_b32_e32 v24, s0, v42
	v_ashrrev_i32_e32 v25, 31, v24
	v_lshlrev_b64 v[24:25], 13, v[24:25]
	v_lshl_add_u64 v[24:25], v[22:23], 0, v[24:25]
	global_load_dword v24, v[24:25], off nt
	v_add_u32_e32 v25, v26, v41
	s_and_b64 vcc, exec, s[6:7]
	s_waitcnt vmcnt(1)
	ds_write_b32 v25, v2
	s_cbranch_vccnz .LBB0_587
	s_ashr_i32 s1, s0, 31
	v_readlane_b32 s36, v254, 30
	v_lshl_add_u64 v[90:91], s[0:1], 0, v[0:1]
	v_readlane_b32 s40, v254, 34
	v_readlane_b32 s41, v254, 35
	v_readlane_b32 s37, v254, 31
	v_readlane_b32 s38, v254, 32
	v_lshl_add_u64 v[90:91], v[90:91], 2, s[40:41]
	global_load_dword v2, v[90:91], off offset:104 nt
	v_readlane_b32 s39, v254, 33
	v_readlane_b32 s42, v254, 36
	v_readlane_b32 s43, v254, 37
	v_readlane_b32 s44, v254, 38
	v_readlane_b32 s45, v254, 39
	v_readlane_b32 s46, v254, 40
	v_readlane_b32 s47, v254, 41
	v_readlane_b32 s48, v254, 42
	v_readlane_b32 s49, v254, 43
	v_readlane_b32 s50, v254, 44
	v_readlane_b32 s51, v254, 45
	s_waitcnt vmcnt(0)
	v_mul_f32_e32 v24, v24, v2
.LBB0_587:
	v_or_b32_e32 v90, s0, v43
	v_ashrrev_i32_e32 v91, 31, v90
	v_lshlrev_b64 v[90:91], 13, v[90:91]
	v_lshl_add_u64 v[90:91], v[22:23], 0, v[90:91]
	global_load_dword v2, v[90:91], off nt
	s_and_b64 vcc, exec, s[6:7]
	s_waitcnt vmcnt(1)
	ds_write_b32 v79, v24
	s_cbranch_vccnz .LBB0_589
	s_ashr_i32 s1, s0, 31
	v_readlane_b32 s36, v254, 30
	v_lshl_add_u64 v[24:25], s[0:1], 0, v[0:1]
	v_readlane_b32 s40, v254, 34
	v_readlane_b32 s41, v254, 35
	v_readlane_b32 s37, v254, 31
	v_readlane_b32 s38, v254, 32
	v_lshl_add_u64 v[24:25], v[24:25], 2, s[40:41]
	global_load_dword v24, v[24:25], off offset:112 nt
	v_readlane_b32 s39, v254, 33
	v_readlane_b32 s42, v254, 36
	v_readlane_b32 s43, v254, 37
	v_readlane_b32 s44, v254, 38
	v_readlane_b32 s45, v254, 39
	v_readlane_b32 s46, v254, 40
	v_readlane_b32 s47, v254, 41
	v_readlane_b32 s48, v254, 42
	v_readlane_b32 s49, v254, 43
	v_readlane_b32 s50, v254, 44
	v_readlane_b32 s51, v254, 45
	s_waitcnt vmcnt(0)
	v_mul_f32_e32 v2, v2, v24
.LBB0_589:
	v_or_b32_e32 v24, s0, v44
	v_ashrrev_i32_e32 v25, 31, v24
	v_lshlrev_b64 v[24:25], 13, v[24:25]
	v_lshl_add_u64 v[24:25], v[22:23], 0, v[24:25]
	global_load_dword v24, v[24:25], off nt
	s_and_b64 vcc, exec, s[6:7]
	s_waitcnt vmcnt(1)
	ds_write_b32 v80, v2
	s_cbranch_vccnz .LBB0_591
	s_ashr_i32 s1, s0, 31
	v_readlane_b32 s36, v254, 30
	v_lshl_add_u64 v[90:91], s[0:1], 0, v[0:1]
	v_readlane_b32 s40, v254, 34
	v_readlane_b32 s41, v254, 35
	v_readlane_b32 s37, v254, 31
	v_readlane_b32 s38, v254, 32
	v_lshl_add_u64 v[90:91], v[90:91], 2, s[40:41]
	global_load_dword v2, v[90:91], off offset:120 nt
	v_readlane_b32 s39, v254, 33
	v_readlane_b32 s42, v254, 36
	v_readlane_b32 s43, v254, 37
	v_readlane_b32 s44, v254, 38
	v_readlane_b32 s45, v254, 39
	v_readlane_b32 s46, v254, 40
	v_readlane_b32 s47, v254, 41
	v_readlane_b32 s48, v254, 42
	v_readlane_b32 s49, v254, 43
	v_readlane_b32 s50, v254, 44
	v_readlane_b32 s51, v254, 45
	s_waitcnt vmcnt(0)
	v_mul_f32_e32 v24, v24, v2
.LBB0_591:
	v_or_b32_e32 v90, s0, v45
	v_ashrrev_i32_e32 v91, 31, v90
	v_lshlrev_b64 v[90:91], 13, v[90:91]
	v_lshl_add_u64 v[90:91], v[22:23], 0, v[90:91]
	global_load_dword v2, v[90:91], off nt
	s_and_b64 vcc, exec, s[6:7]
	s_waitcnt vmcnt(1)
	ds_write_b32 v81, v24
	s_cbranch_vccnz .LBB0_593
	s_ashr_i32 s1, s0, 31
	v_readlane_b32 s36, v254, 30
	v_lshl_add_u64 v[24:25], s[0:1], 0, v[0:1]
	v_readlane_b32 s40, v254, 34
	v_readlane_b32 s41, v254, 35
	v_readlane_b32 s37, v254, 31
	v_readlane_b32 s38, v254, 32
	v_lshl_add_u64 v[24:25], v[24:25], 2, s[40:41]
	global_load_dword v24, v[24:25], off offset:128 nt
	v_readlane_b32 s39, v254, 33
	v_readlane_b32 s42, v254, 36
	v_readlane_b32 s43, v254, 37
	v_readlane_b32 s44, v254, 38
	v_readlane_b32 s45, v254, 39
	v_readlane_b32 s46, v254, 40
	v_readlane_b32 s47, v254, 41
	v_readlane_b32 s48, v254, 42
	v_readlane_b32 s49, v254, 43
	v_readlane_b32 s50, v254, 44
	v_readlane_b32 s51, v254, 45
	s_waitcnt vmcnt(0)
	v_mul_f32_e32 v2, v2, v24
.LBB0_593:
	v_or_b32_e32 v24, s0, v46
	v_ashrrev_i32_e32 v25, 31, v24
	v_lshlrev_b64 v[24:25], 13, v[24:25]
	v_lshl_add_u64 v[24:25], v[22:23], 0, v[24:25]
	global_load_dword v24, v[24:25], off nt
	s_and_b64 vcc, exec, s[6:7]
	s_waitcnt vmcnt(1)
	ds_write_b32 v82, v2
	s_cbranch_vccnz .LBB0_595
	s_ashr_i32 s1, s0, 31
	v_readlane_b32 s36, v254, 30
	v_lshl_add_u64 v[90:91], s[0:1], 0, v[0:1]
	v_readlane_b32 s40, v254, 34
	v_readlane_b32 s41, v254, 35
	v_readlane_b32 s37, v254, 31
	v_readlane_b32 s38, v254, 32
	v_lshl_add_u64 v[90:91], v[90:91], 2, s[40:41]
	global_load_dword v2, v[90:91], off offset:136 nt
	v_readlane_b32 s39, v254, 33
	v_readlane_b32 s42, v254, 36
	v_readlane_b32 s43, v254, 37
	v_readlane_b32 s44, v254, 38
	v_readlane_b32 s45, v254, 39
	v_readlane_b32 s46, v254, 40
	v_readlane_b32 s47, v254, 41
	v_readlane_b32 s48, v254, 42
	v_readlane_b32 s49, v254, 43
	v_readlane_b32 s50, v254, 44
	v_readlane_b32 s51, v254, 45
	s_waitcnt vmcnt(0)
	v_mul_f32_e32 v24, v24, v2
.LBB0_595:
	v_or_b32_e32 v90, s0, v47
	v_ashrrev_i32_e32 v91, 31, v90
	v_lshlrev_b64 v[90:91], 13, v[90:91]
	v_lshl_add_u64 v[90:91], v[22:23], 0, v[90:91]
	global_load_dword v2, v[90:91], off nt
	s_and_b64 vcc, exec, s[6:7]
	s_waitcnt vmcnt(1)
	ds_write_b32 v83, v24
	s_cbranch_vccnz .LBB0_597
	s_ashr_i32 s1, s0, 31
	v_readlane_b32 s36, v254, 30
	v_lshl_add_u64 v[24:25], s[0:1], 0, v[0:1]
	v_readlane_b32 s40, v254, 34
	v_readlane_b32 s41, v254, 35
	v_readlane_b32 s37, v254, 31
	v_readlane_b32 s38, v254, 32
	v_lshl_add_u64 v[24:25], v[24:25], 2, s[40:41]
	global_load_dword v24, v[24:25], off offset:144 nt
	v_readlane_b32 s39, v254, 33
	v_readlane_b32 s42, v254, 36
	v_readlane_b32 s43, v254, 37
	v_readlane_b32 s44, v254, 38
	v_readlane_b32 s45, v254, 39
	v_readlane_b32 s46, v254, 40
	v_readlane_b32 s47, v254, 41
	v_readlane_b32 s48, v254, 42
	v_readlane_b32 s49, v254, 43
	v_readlane_b32 s50, v254, 44
	v_readlane_b32 s51, v254, 45
	s_waitcnt vmcnt(0)
	v_mul_f32_e32 v2, v2, v24
.LBB0_597:
	v_or_b32_e32 v24, s0, v49
	v_ashrrev_i32_e32 v25, 31, v24
	v_lshlrev_b64 v[24:25], 13, v[24:25]
	v_lshl_add_u64 v[24:25], v[22:23], 0, v[24:25]
	global_load_dword v24, v[24:25], off nt
	v_add_u32_e32 v25, v26, v48
	s_and_b64 vcc, exec, s[6:7]
	s_waitcnt vmcnt(1)
	ds_write_b32 v25, v2
	s_cbranch_vccnz .LBB0_599
	s_ashr_i32 s1, s0, 31
	v_readlane_b32 s36, v254, 30
	v_lshl_add_u64 v[90:91], s[0:1], 0, v[0:1]
	v_readlane_b32 s40, v254, 34
	v_readlane_b32 s41, v254, 35
	v_readlane_b32 s37, v254, 31
	v_readlane_b32 s38, v254, 32
	v_lshl_add_u64 v[90:91], v[90:91], 2, s[40:41]
	global_load_dword v2, v[90:91], off offset:152 nt
	v_readlane_b32 s39, v254, 33
	v_readlane_b32 s42, v254, 36
	v_readlane_b32 s43, v254, 37
	v_readlane_b32 s44, v254, 38
	v_readlane_b32 s45, v254, 39
	v_readlane_b32 s46, v254, 40
	v_readlane_b32 s47, v254, 41
	v_readlane_b32 s48, v254, 42
	v_readlane_b32 s49, v254, 43
	v_readlane_b32 s50, v254, 44
	v_readlane_b32 s51, v254, 45
	s_waitcnt vmcnt(0)
	v_mul_f32_e32 v24, v24, v2
.LBB0_599:
	v_or_b32_e32 v90, s0, v50
	v_ashrrev_i32_e32 v91, 31, v90
	v_lshlrev_b64 v[90:91], 13, v[90:91]
	v_lshl_add_u64 v[90:91], v[22:23], 0, v[90:91]
	global_load_dword v2, v[90:91], off nt
	s_and_b64 vcc, exec, s[6:7]
	s_waitcnt vmcnt(1)
	ds_write_b32 v84, v24
	s_cbranch_vccnz .LBB0_601
	s_ashr_i32 s1, s0, 31
	v_readlane_b32 s36, v254, 30
	v_lshl_add_u64 v[24:25], s[0:1], 0, v[0:1]
	v_readlane_b32 s40, v254, 34
	v_readlane_b32 s41, v254, 35
	v_readlane_b32 s37, v254, 31
	v_readlane_b32 s38, v254, 32
	v_lshl_add_u64 v[24:25], v[24:25], 2, s[40:41]
	global_load_dword v24, v[24:25], off offset:160 nt
	v_readlane_b32 s39, v254, 33
	v_readlane_b32 s42, v254, 36
	v_readlane_b32 s43, v254, 37
	v_readlane_b32 s44, v254, 38
	v_readlane_b32 s45, v254, 39
	v_readlane_b32 s46, v254, 40
	v_readlane_b32 s47, v254, 41
	v_readlane_b32 s48, v254, 42
	v_readlane_b32 s49, v254, 43
	v_readlane_b32 s50, v254, 44
	v_readlane_b32 s51, v254, 45
	s_waitcnt vmcnt(0)
	v_mul_f32_e32 v2, v2, v24
.LBB0_601:
	v_or_b32_e32 v24, s0, v51
	v_ashrrev_i32_e32 v25, 31, v24
	v_lshlrev_b64 v[24:25], 13, v[24:25]
	v_lshl_add_u64 v[24:25], v[22:23], 0, v[24:25]
	global_load_dword v24, v[24:25], off nt
	s_and_b64 vcc, exec, s[6:7]
	s_waitcnt vmcnt(1)
	ds_write_b32 v85, v2
	s_cbranch_vccnz .LBB0_603
	s_ashr_i32 s1, s0, 31
	v_readlane_b32 s36, v254, 30
	v_lshl_add_u64 v[90:91], s[0:1], 0, v[0:1]
	v_readlane_b32 s40, v254, 34
	v_readlane_b32 s41, v254, 35
	v_readlane_b32 s37, v254, 31
	v_readlane_b32 s38, v254, 32
	v_lshl_add_u64 v[90:91], v[90:91], 2, s[40:41]
	global_load_dword v2, v[90:91], off offset:168 nt
	v_readlane_b32 s39, v254, 33
	v_readlane_b32 s42, v254, 36
	v_readlane_b32 s43, v254, 37
	v_readlane_b32 s44, v254, 38
	v_readlane_b32 s45, v254, 39
	v_readlane_b32 s46, v254, 40
	v_readlane_b32 s47, v254, 41
	v_readlane_b32 s48, v254, 42
	v_readlane_b32 s49, v254, 43
	v_readlane_b32 s50, v254, 44
	v_readlane_b32 s51, v254, 45
	s_waitcnt vmcnt(0)
	v_mul_f32_e32 v24, v24, v2
.LBB0_603:
	v_or_b32_e32 v90, s0, v52
	v_ashrrev_i32_e32 v91, 31, v90
	v_lshlrev_b64 v[90:91], 13, v[90:91]
	v_lshl_add_u64 v[90:91], v[22:23], 0, v[90:91]
	global_load_dword v2, v[90:91], off nt
	s_and_b64 vcc, exec, s[6:7]
	s_waitcnt vmcnt(1)
	ds_write_b32 v86, v24
	s_cbranch_vccnz .LBB0_605
	s_ashr_i32 s1, s0, 31
	v_readlane_b32 s36, v254, 30
	v_lshl_add_u64 v[24:25], s[0:1], 0, v[0:1]
	v_readlane_b32 s40, v254, 34
	v_readlane_b32 s41, v254, 35
	v_readlane_b32 s37, v254, 31
	v_readlane_b32 s38, v254, 32
	v_lshl_add_u64 v[24:25], v[24:25], 2, s[40:41]
	global_load_dword v24, v[24:25], off offset:176 nt
	v_readlane_b32 s39, v254, 33
	v_readlane_b32 s42, v254, 36
	v_readlane_b32 s43, v254, 37
	v_readlane_b32 s44, v254, 38
	v_readlane_b32 s45, v254, 39
	v_readlane_b32 s46, v254, 40
	v_readlane_b32 s47, v254, 41
	v_readlane_b32 s48, v254, 42
	v_readlane_b32 s49, v254, 43
	v_readlane_b32 s50, v254, 44
	v_readlane_b32 s51, v254, 45
	s_waitcnt vmcnt(0)
	v_mul_f32_e32 v2, v2, v24
.LBB0_605:
	v_or_b32_e32 v24, s0, v53
	v_ashrrev_i32_e32 v25, 31, v24
	v_lshlrev_b64 v[24:25], 13, v[24:25]
	v_lshl_add_u64 v[24:25], v[22:23], 0, v[24:25]
	global_load_dword v25, v[24:25], off nt
	s_and_b64 vcc, exec, s[6:7]
	s_waitcnt vmcnt(1)
	ds_write_b32 v87, v2
	s_cbranch_vccnz .LBB0_607
	s_ashr_i32 s1, s0, 31
	v_readlane_b32 s36, v254, 30
	v_lshl_add_u64 v[90:91], s[0:1], 0, v[0:1]
	v_readlane_b32 s40, v254, 34
	v_readlane_b32 s41, v254, 35
	v_readlane_b32 s37, v254, 31
	v_readlane_b32 s38, v254, 32
	v_lshl_add_u64 v[90:91], v[90:91], 2, s[40:41]
	global_load_dword v2, v[90:91], off offset:184 nt
	v_readlane_b32 s39, v254, 33
	v_readlane_b32 s42, v254, 36
	v_readlane_b32 s43, v254, 37
	v_readlane_b32 s44, v254, 38
	v_readlane_b32 s45, v254, 39
	v_readlane_b32 s46, v254, 40
	v_readlane_b32 s47, v254, 41
	v_readlane_b32 s48, v254, 42
	v_readlane_b32 s49, v254, 43
	v_readlane_b32 s50, v254, 44
	v_readlane_b32 s51, v254, 45
	s_waitcnt vmcnt(0)
	v_mul_f32_e32 v25, v25, v2
.LBB0_607:
	v_or_b32_e32 v90, s0, v54
	v_ashrrev_i32_e32 v91, 31, v90
	v_lshlrev_b64 v[90:91], 13, v[90:91]
	v_lshl_add_u64 v[90:91], v[22:23], 0, v[90:91]
	global_load_dword v24, v[90:91], off nt
	s_and_b64 vcc, exec, s[6:7]
	s_waitcnt vmcnt(1)
	ds_write_b32 v88, v25
	s_cbranch_vccnz .LBB0_609
	s_ashr_i32 s1, s0, 31
	v_readlane_b32 s36, v254, 30
	v_lshl_add_u64 v[90:91], s[0:1], 0, v[0:1]
	v_readlane_b32 s40, v254, 34
	v_readlane_b32 s41, v254, 35
	v_readlane_b32 s37, v254, 31
	v_readlane_b32 s38, v254, 32
	v_lshl_add_u64 v[90:91], v[90:91], 2, s[40:41]
	global_load_dword v2, v[90:91], off offset:192 nt
	v_readlane_b32 s39, v254, 33
	v_readlane_b32 s42, v254, 36
	v_readlane_b32 s43, v254, 37
	v_readlane_b32 s44, v254, 38
	v_readlane_b32 s45, v254, 39
	v_readlane_b32 s46, v254, 40
	v_readlane_b32 s47, v254, 41
	v_readlane_b32 s48, v254, 42
	v_readlane_b32 s49, v254, 43
	v_readlane_b32 s50, v254, 44
	v_readlane_b32 s51, v254, 45
	s_waitcnt vmcnt(0)
	v_mul_f32_e32 v24, v24, v2
.LBB0_609:
	v_or_b32_e32 v90, s0, v56
	v_ashrrev_i32_e32 v91, 31, v90
	v_lshlrev_b64 v[90:91], 13, v[90:91]
	v_lshl_add_u64 v[90:91], v[22:23], 0, v[90:91]
	global_load_dword v25, v[90:91], off nt
	v_add_u32_e32 v2, v26, v55
	s_and_b64 vcc, exec, s[6:7]
	s_waitcnt vmcnt(1)
	ds_write_b32 v2, v24
	s_cbranch_vccnz .LBB0_611
	s_ashr_i32 s1, s0, 31
	v_readlane_b32 s36, v254, 30
	v_lshl_add_u64 v[90:91], s[0:1], 0, v[0:1]
	v_readlane_b32 s40, v254, 34
	v_readlane_b32 s41, v254, 35
	v_readlane_b32 s37, v254, 31
	v_readlane_b32 s38, v254, 32
	v_lshl_add_u64 v[90:91], v[90:91], 2, s[40:41]
	global_load_dword v24, v[90:91], off offset:200 nt
	v_readlane_b32 s39, v254, 33
	v_readlane_b32 s42, v254, 36
	v_readlane_b32 s43, v254, 37
	v_readlane_b32 s44, v254, 38
	v_readlane_b32 s45, v254, 39
	v_readlane_b32 s46, v254, 40
	v_readlane_b32 s47, v254, 41
	v_readlane_b32 s48, v254, 42
	v_readlane_b32 s49, v254, 43
	v_readlane_b32 s50, v254, 44
	v_readlane_b32 s51, v254, 45
	s_waitcnt vmcnt(0)
	v_mul_f32_e32 v25, v25, v24
.LBB0_611:
	v_or_b32_e32 v90, s0, v57
	v_ashrrev_i32_e32 v91, 31, v90
	v_lshlrev_b64 v[90:91], 13, v[90:91]
	v_lshl_add_u64 v[90:91], v[22:23], 0, v[90:91]
	global_load_dword v24, v[90:91], off nt
	s_and_b64 vcc, exec, s[6:7]
	s_waitcnt vmcnt(1)
	ds_write_b32 v2, v25 offset:264
	s_cbranch_vccnz .LBB0_613
	s_ashr_i32 s1, s0, 31
	v_readlane_b32 s36, v254, 30
	v_lshl_add_u64 v[90:91], s[0:1], 0, v[0:1]
	v_readlane_b32 s40, v254, 34
	v_readlane_b32 s41, v254, 35
	v_readlane_b32 s37, v254, 31
	v_readlane_b32 s38, v254, 32
	v_lshl_add_u64 v[90:91], v[90:91], 2, s[40:41]
	global_load_dword v25, v[90:91], off offset:208 nt
	v_readlane_b32 s39, v254, 33
	v_readlane_b32 s42, v254, 36
	v_readlane_b32 s43, v254, 37
	v_readlane_b32 s44, v254, 38
	v_readlane_b32 s45, v254, 39
	v_readlane_b32 s46, v254, 40
	v_readlane_b32 s47, v254, 41
	v_readlane_b32 s48, v254, 42
	v_readlane_b32 s49, v254, 43
	v_readlane_b32 s50, v254, 44
	v_readlane_b32 s51, v254, 45
	s_waitcnt vmcnt(0)
	v_mul_f32_e32 v24, v24, v25
.LBB0_613:
	v_or_b32_e32 v90, s0, v58
	v_ashrrev_i32_e32 v91, 31, v90
	v_lshlrev_b64 v[90:91], 13, v[90:91]
	v_lshl_add_u64 v[90:91], v[22:23], 0, v[90:91]
	global_load_dword v25, v[90:91], off nt
	s_and_b64 vcc, exec, s[6:7]
	s_waitcnt vmcnt(1)
	ds_write_b32 v2, v24 offset:528
	s_cbranch_vccnz .LBB0_615
	s_ashr_i32 s1, s0, 31
	v_readlane_b32 s36, v254, 30
	v_lshl_add_u64 v[90:91], s[0:1], 0, v[0:1]
	v_readlane_b32 s40, v254, 34
	v_readlane_b32 s41, v254, 35
	v_readlane_b32 s37, v254, 31
	v_readlane_b32 s38, v254, 32
	v_lshl_add_u64 v[90:91], v[90:91], 2, s[40:41]
	global_load_dword v24, v[90:91], off offset:216 nt
	v_readlane_b32 s39, v254, 33
	v_readlane_b32 s42, v254, 36
	v_readlane_b32 s43, v254, 37
	v_readlane_b32 s44, v254, 38
	v_readlane_b32 s45, v254, 39
	v_readlane_b32 s46, v254, 40
	v_readlane_b32 s47, v254, 41
	v_readlane_b32 s48, v254, 42
	v_readlane_b32 s49, v254, 43
	v_readlane_b32 s50, v254, 44
	v_readlane_b32 s51, v254, 45
	s_waitcnt vmcnt(0)
	v_mul_f32_e32 v25, v25, v24
.LBB0_615:
	v_or_b32_e32 v90, s0, v59
	v_ashrrev_i32_e32 v91, 31, v90
	v_lshlrev_b64 v[90:91], 13, v[90:91]
	v_lshl_add_u64 v[90:91], v[22:23], 0, v[90:91]
	global_load_dword v24, v[90:91], off nt
	s_and_b64 vcc, exec, s[6:7]
	s_waitcnt vmcnt(1)
	ds_write_b32 v2, v25 offset:792
	s_cbranch_vccnz .LBB0_617
	s_ashr_i32 s1, s0, 31
	v_readlane_b32 s36, v254, 30
	v_lshl_add_u64 v[90:91], s[0:1], 0, v[0:1]
	v_readlane_b32 s40, v254, 34
	v_readlane_b32 s41, v254, 35
	v_readlane_b32 s37, v254, 31
	v_readlane_b32 s38, v254, 32
	v_lshl_add_u64 v[90:91], v[90:91], 2, s[40:41]
	global_load_dword v25, v[90:91], off offset:224 nt
	v_readlane_b32 s39, v254, 33
	v_readlane_b32 s42, v254, 36
	v_readlane_b32 s43, v254, 37
	v_readlane_b32 s44, v254, 38
	v_readlane_b32 s45, v254, 39
	v_readlane_b32 s46, v254, 40
	v_readlane_b32 s47, v254, 41
	v_readlane_b32 s48, v254, 42
	v_readlane_b32 s49, v254, 43
	v_readlane_b32 s50, v254, 44
	v_readlane_b32 s51, v254, 45
	s_waitcnt vmcnt(0)
	v_mul_f32_e32 v24, v24, v25
.LBB0_617:
	v_or_b32_e32 v90, s0, v60
	v_ashrrev_i32_e32 v91, 31, v90
	v_lshlrev_b64 v[90:91], 13, v[90:91]
	v_lshl_add_u64 v[90:91], v[22:23], 0, v[90:91]
	global_load_dword v25, v[90:91], off nt
	s_and_b64 vcc, exec, s[6:7]
	s_waitcnt vmcnt(1)
	ds_write_b32 v2, v24 offset:1056
	s_cbranch_vccnz .LBB0_619
	s_ashr_i32 s1, s0, 31
	v_readlane_b32 s36, v254, 30
	v_lshl_add_u64 v[90:91], s[0:1], 0, v[0:1]
	v_readlane_b32 s40, v254, 34
	v_readlane_b32 s41, v254, 35
	v_readlane_b32 s37, v254, 31
	v_readlane_b32 s38, v254, 32
	v_lshl_add_u64 v[90:91], v[90:91], 2, s[40:41]
	global_load_dword v24, v[90:91], off offset:232 nt
	v_readlane_b32 s39, v254, 33
	v_readlane_b32 s42, v254, 36
	v_readlane_b32 s43, v254, 37
	v_readlane_b32 s44, v254, 38
	v_readlane_b32 s45, v254, 39
	v_readlane_b32 s46, v254, 40
	v_readlane_b32 s47, v254, 41
	v_readlane_b32 s48, v254, 42
	v_readlane_b32 s49, v254, 43
	v_readlane_b32 s50, v254, 44
	v_readlane_b32 s51, v254, 45
	s_waitcnt vmcnt(0)
	v_mul_f32_e32 v25, v25, v24
.LBB0_619:
	v_or_b32_e32 v90, s0, v61
	v_ashrrev_i32_e32 v91, 31, v90
	v_lshlrev_b64 v[90:91], 13, v[90:91]
	v_lshl_add_u64 v[90:91], v[22:23], 0, v[90:91]
	global_load_dword v24, v[90:91], off nt
	s_and_b64 vcc, exec, s[6:7]
	s_waitcnt vmcnt(1)
	ds_write_b32 v2, v25 offset:1320
	s_cbranch_vccnz .LBB0_621
	s_ashr_i32 s1, s0, 31
	v_readlane_b32 s36, v254, 30
	v_lshl_add_u64 v[90:91], s[0:1], 0, v[0:1]
	v_readlane_b32 s40, v254, 34
	v_readlane_b32 s41, v254, 35
	v_readlane_b32 s37, v254, 31
	v_readlane_b32 s38, v254, 32
	v_lshl_add_u64 v[90:91], v[90:91], 2, s[40:41]
	global_load_dword v25, v[90:91], off offset:240 nt
	v_readlane_b32 s39, v254, 33
	v_readlane_b32 s42, v254, 36
	v_readlane_b32 s43, v254, 37
	v_readlane_b32 s44, v254, 38
	v_readlane_b32 s45, v254, 39
	v_readlane_b32 s46, v254, 40
	v_readlane_b32 s47, v254, 41
	v_readlane_b32 s48, v254, 42
	v_readlane_b32 s49, v254, 43
	v_readlane_b32 s50, v254, 44
	v_readlane_b32 s51, v254, 45
	s_waitcnt vmcnt(0)
	v_mul_f32_e32 v24, v24, v25
.LBB0_621:
	v_or_b32_e32 v90, s0, v62
	v_ashrrev_i32_e32 v91, 31, v90
	v_lshlrev_b64 v[90:91], 13, v[90:91]
	v_lshl_add_u64 v[22:23], v[22:23], 0, v[90:91]
	global_load_dword v22, v[22:23], off nt
	s_and_b64 vcc, exec, s[22:23]
	s_waitcnt vmcnt(1)
	ds_write_b32 v2, v24 offset:1584
	s_cbranch_vccz .LBB0_623
	s_ashr_i32 s1, s0, 31
	v_readlane_b32 s36, v254, 30
	v_lshl_add_u64 v[24:25], s[0:1], 0, v[0:1]
	v_readlane_b32 s40, v254, 34
	v_readlane_b32 s41, v254, 35
	v_readlane_b32 s37, v254, 31
	v_readlane_b32 s38, v254, 32
	v_lshl_add_u64 v[24:25], v[24:25], 2, s[40:41]
	global_load_dword v23, v[24:25], off offset:248 nt
	v_readlane_b32 s39, v254, 33
	v_readlane_b32 s42, v254, 36
	v_readlane_b32 s43, v254, 37
	v_readlane_b32 s44, v254, 38
	v_readlane_b32 s45, v254, 39
	v_readlane_b32 s46, v254, 40
	v_readlane_b32 s47, v254, 41
	v_readlane_b32 s48, v254, 42
	v_readlane_b32 s49, v254, 43
	v_readlane_b32 s50, v254, 44
	v_readlane_b32 s51, v254, 45
	s_waitcnt vmcnt(0)
	v_mul_f32_e32 v23, v22, v23
	s_cbranch_execnz .LBB0_542
	s_branch .LBB0_624

.LBB0_627:
	global_load_dwordx4 v[6:9], v[2:3], off nt
	global_load_dwordx4 v[10:13], v[2:3], off offset:16 nt
	v_lshl_add_u64 v[0:1], v[0:1], 0, s[12:13]
	v_cmp_lt_u64_e32 vcc, s[22:23], v[0:1]
	v_lshl_add_u64 v[2:3], v[2:3], 0, s[0:1]
	s_or_b64 s[6:7], vcc, s[6:7]
	s_waitcnt vmcnt(1)
	v_cvt_pk_bf16_f32 v6, v6, v7
	v_cvt_pk_bf16_f32 v7, v8, v9
	s_waitcnt vmcnt(0)
	v_cvt_pk_bf16_f32 v8, v10, v11
	v_cvt_pk_bf16_f32 v9, v12, v13
	global_store_dwordx4 v[4:5], v[6:9], off
	v_lshl_add_u64 v[4:5], v[4:5], 0, s[20:21]
	s_andn2_b64 exec, exec, s[6:7]
	s_cbranch_execnz .LBB0_627

.LBB0_631:
	v_lshl_add_u64 v[32:33], s[92:93], 0, v[90:91]
	v_add_co_u32_e32 v34, vcc, 0x37f00000, v32
	v_readlane_b32 s24, v254, 0
	s_nop 0
	v_addc_co_u32_e32 v35, vcc, 0, v33, vcc
	v_lshl_add_u64 v[94:95], s[92:93], 0, v[92:93]
	global_load_dwordx4 v[110:113], v[34:35], off nt
	global_load_dwordx4 v[80:83], v[34:35], off offset:1024 nt
	v_readlane_b32 s30, v254, 6
	v_readlane_b32 s31, v254, 7
	v_add_co_u32_e32 v34, vcc, 0x17b00000, v94
	s_nop 0
	v_lshl_add_u64 v[36:37], s[30:31], 0, v[90:91]
	v_addc_co_u32_e32 v35, vcc, 0, v95, vcc
	global_load_dwordx4 v[114:117], v[36:37], off nt
	global_load_dwordx4 v[84:87], v[36:37], off offset:1024 nt
	global_load_dwordx2 v[118:119], v[34:35], off nt
	global_load_dwordx2 v[108:109], v[34:35], off offset:512 nt
	v_add_co_u32_e32 v34, vcc, 0x38100000, v32
	v_readlane_b32 s25, v254, 1
	s_nop 0
	v_addc_co_u32_e32 v35, vcc, 0, v33, vcc
	global_load_dwordx4 v[72:75], v[34:35], off nt
	global_load_dwordx4 v[64:67], v[34:35], off offset:1024 nt
	v_add_co_u32_e32 v34, vcc, 0x200000, v36
	v_readlane_b32 s26, v254, 2
	s_nop 0
	v_addc_co_u32_e32 v35, vcc, 0, v37, vcc
	global_load_dwordx4 v[76:79], v[34:35], off nt
	global_load_dwordx4 v[68:71], v[34:35], off offset:1024 nt
	v_add_co_u32_e32 v34, vcc, 0x17c00000, v94
	v_readlane_b32 s27, v254, 3
	s_nop 0
	v_addc_co_u32_e32 v35, vcc, 0, v95, vcc
	global_load_dwordx2 v[106:107], v[34:35], off nt
	global_load_dwordx2 v[104:105], v[34:35], off offset:512 nt
	v_add_co_u32_e32 v34, vcc, 0x38300000, v32
	v_readlane_b32 s28, v254, 4
	s_nop 0
	v_addc_co_u32_e32 v35, vcc, 0, v33, vcc
	global_load_dwordx4 v[56:59], v[34:35], off nt
	global_load_dwordx4 v[48:51], v[34:35], off offset:1024 nt
	v_add_co_u32_e32 v34, vcc, 0x400000, v36
	v_readlane_b32 s29, v254, 5
	s_nop 0
	v_addc_co_u32_e32 v35, vcc, 0, v37, vcc
	global_load_dwordx4 v[60:63], v[34:35], off nt
	global_load_dwordx4 v[52:55], v[34:35], off offset:1024 nt
	v_add_co_u32_e32 v34, vcc, 0x17d00000, v94
	s_waitcnt vmcnt(15)
	v_lshlrev_b32_e32 v120, 16, v110
	v_addc_co_u32_e32 v35, vcc, 0, v95, vcc
	v_add_co_u32_e32 v32, vcc, 0x38500000, v32
	global_load_dwordx2 v[102:103], v[34:35], off nt
	global_load_dwordx2 v[100:101], v[34:35], off offset:512 nt
	v_addc_co_u32_e32 v33, vcc, 0, v33, vcc
	v_add_co_u32_e32 v36, vcc, 0x600000, v36
	global_load_dwordx4 v[40:43], v[32:33], off nt
	s_nop 0
	global_load_dwordx4 v[32:35], v[32:33], off offset:1024 nt
	v_addc_co_u32_e32 v37, vcc, 0, v37, vcc
	v_add_co_u32_e32 v94, vcc, 0x17e00000, v94
	global_load_dwordx4 v[44:47], v[36:37], off nt
	s_nop 0
	global_load_dwordx4 v[36:39], v[36:37], off offset:1024 nt
	v_addc_co_u32_e32 v95, vcc, 0, v95, vcc
	global_load_dwordx2 v[98:99], v[94:95], off nt
	global_load_dwordx2 v[96:97], v[94:95], off offset:512 nt
	s_waitcnt vmcnt(19)
	v_cvt_f32_ubyte1_e32 v125, v118
	v_cvt_f32_ubyte0_e32 v124, v118
	v_cvt_f32_ubyte3_e32 v127, v118
	v_cvt_f32_ubyte2_e32 v126, v118
	v_pk_fma_f32 v[126:127], v[126:127], s[0:1], -1.0 op_sel_hi:[1,0,0]
	v_pk_fma_f32 v[124:125], v[124:125], s[0:1], -1.0 op_sel_hi:[1,0,0]
	v_lshlrev_b32_e32 v122, 16, v114
	v_and_b32_e32 v123, 0xffff0000, v114
	v_lshlrev_b32_e32 v114, 16, v115
	v_and_b32_e32 v115, 0xffff0000, v115
	v_pk_fma_f32 v[124:125], v[8:9], v[124:125], 1.0 op_sel_hi:[1,1,0]
	v_pk_fma_f32 v[126:127], v[10:11], v[126:127], 1.0 op_sel_hi:[1,1,0]
	v_and_b32_e32 v121, 0xffff0000, v110
	v_lshlrev_b32_e32 v110, 16, v111
	v_and_b32_e32 v111, 0xffff0000, v111
	v_pk_mul_f32 v[114:115], v[126:127], v[114:115]
	v_pk_mul_f32 v[122:123], v[124:125], v[122:123]
	v_pk_mul_f32 v[110:111], v[114:115], v[110:111]
	v_pk_mul_f32 v[120:121], v[122:123], v[120:121]
	v_pk_mul_f32 v[110:111], v[14:15], v[110:111]
	v_pk_mul_f32 v[114:115], v[12:13], v[120:121]
	v_cvt_f32_ubyte1_e32 v121, v119
	v_cvt_f32_ubyte0_e32 v120, v119
	v_cvt_f32_ubyte3_e32 v123, v119
	v_cvt_f32_ubyte2_e32 v122, v119
	v_add_f32_e32 v114, v114, v115
	v_add_f32_e32 v110, v110, v111
	v_pk_fma_f32 v[118:119], v[122:123], s[0:1], -1.0 op_sel_hi:[1,0,0]
	v_pk_fma_f32 v[120:121], v[120:121], s[0:1], -1.0 op_sel_hi:[1,0,0]
	v_add_f32_e32 v110, v114, v110
	v_lshlrev_b32_e32 v114, 16, v116
	v_and_b32_e32 v115, 0xffff0000, v116
	v_lshlrev_b32_e32 v116, 16, v117
	v_and_b32_e32 v117, 0xffff0000, v117
	v_pk_fma_f32 v[120:121], v[0:1], v[120:121], 1.0 op_sel_hi:[1,1,0]
	v_pk_fma_f32 v[118:119], v[2:3], v[118:119], 1.0 op_sel_hi:[1,1,0]
	v_add_f32_e32 v124, 0, v110
	v_lshlrev_b32_e32 v110, 16, v112
	v_and_b32_e32 v111, 0xffff0000, v112
	v_lshlrev_b32_e32 v112, 16, v113
	v_and_b32_e32 v113, 0xffff0000, v113
	v_pk_mul_f32 v[116:117], v[118:119], v[116:117]
	v_pk_mul_f32 v[114:115], v[120:121], v[114:115]
	v_pk_mul_f32 v[112:113], v[116:117], v[112:113]
	v_pk_mul_f32 v[110:111], v[114:115], v[110:111]
	v_pk_mul_f32 v[112:113], v[6:7], v[112:113]
	v_pk_mul_f32 v[110:111], v[4:5], v[110:111]
	v_lshl_add_u64 v[94:95], s[92:93], 0, v[88:89]
	v_add_f32_e32 v110, v110, v111
	v_add_f32_e32 v111, v112, v113
	v_add_f32_e32 v110, v110, v111
	v_add_f32_e32 v110, v124, v110
	s_nop 1
	v_add_f32_dpp v110, v110, v110 quad_perm:[1,0,3,2] row_mask:0xf bank_mask:0xf bound_ctrl:1
	s_nop 1
	v_add_f32_dpp v110, v110, v110 quad_perm:[2,3,0,1] row_mask:0xf bank_mask:0xf bound_ctrl:1
	s_nop 1
	v_mov_b32_dpp v111, v110 row_half_mirror row_mask:0xf bank_mask:0xf bound_ctrl:1
	s_and_saveexec_b64 s[4:5], s[6:7]
	s_cbranch_execz .LBB0_633
	v_add_f32_e32 v112, v110, v111
	v_add_co_u32_e32 v110, vcc, 0x1e00000, v94
	s_nop 1
	v_addc_co_u32_e32 v111, vcc, 0, v95, vcc
	global_store_dword v[110:111], v112, off

.LBB0_700:
	s_or_b64 exec, exec, s[0:1]
	s_lshl_b32 s43, s2, 4
	s_and_b32 s0, s43, 0x70
	s_add_i32 s0, s0, s71
	s_ashr_i32 s0, s0, 4
	s_ashr_i32 s1, s0, 31
	s_cmp_eq_u32 s70, 2
	s_waitcnt vmcnt(0) lgkmcnt(0)
	s_barrier
	s_cbranch_scc0 .LBB0_718
	v_lshlrev_b32_e32 v14, 4, v148
	v_mov_b32_e32 v1, 0
	v_and_b32_e32 v0, 0x70, v14
	v_readlane_b32 s16, v254, 0
	s_lshl_b64 s[10:11], s[0:1], 13
	s_mov_b32 s9, 0
	s_lshl_b32 s4, s42, 6
	v_lshl_add_u64 v[2:3], s[82:83], 0, v[0:1]
	s_lshl_b32 s8, s42, 7
	v_readlane_b32 s22, v254, 6
	v_readlane_b32 s23, v254, 7
	v_lshl_add_u64 v[10:11], v[2:3], 0, s[8:9]
	s_add_u32 s4, s80, s4
	v_lshl_add_u64 v[2:3], s[22:23], 0, v[0:1]
	v_lshrrev_b32_e32 v7, 3, v148
	v_lshl_add_u64 v[12:13], v[2:3], 0, s[8:9]
	v_lshl_add_u64 v[2:3], s[14:15], 0, v[0:1]
	s_addc_u32 s5, s81, 0
	v_lshl_add_u64 v[8:9], v[2:3], 0, s[8:9]
	v_lshl_add_u64 v[2:3], s[62:63], 0, v[0:1]
	v_and_b32_e32 v0, 48, v14
	v_or_b32_e32 v14, s10, v7
	v_mov_b32_e32 v15, s11
	s_cmp_lg_u32 0, -1
	v_lshlrev_b64 v[14:15], 11, v[14:15]
	s_cselect_b32 s6, 0, 0
	v_lshl_add_u64 v[0:1], s[4:5], 0, v[0:1]
	v_lshl_add_u64 v[16:17], v[10:11], 0, v[14:15]
	s_add_i32 s4, s6, 0x19c00
	s_mov_b32 m0, s4
	s_nop 0
	global_load_lds_dwordx4 v[16:17], off nt
	s_mov_b64 s[4:5], 0x4000
	v_lshl_add_u64 v[2:3], v[2:3], 0, s[8:9]
	v_lshl_add_u64 v[16:17], v[16:17], 0, s[4:5]
	s_add_i32 s7, s6, 0x1a000
	s_mov_b32 m0, s7
	s_nop 0
	global_load_lds_dwordx4 v[16:17], off nt
	v_lshl_add_u64 v[16:17], v[12:13], 0, v[14:15]
	s_add_i32 s7, s6, 0x1a400
	s_mov_b32 m0, s7
	s_nop 0
	global_load_lds_dwordx4 v[16:17], off nt
	v_lshl_add_u64 v[16:17], v[16:17], 0, s[4:5]
	s_add_i32 s7, s6, 0x1a800
	s_mov_b32 m0, s7
	s_nop 0
	global_load_lds_dwordx4 v[16:17], off nt
	v_lshl_add_u64 v[16:17], v[8:9], 0, v[14:15]
	s_add_i32 s7, s6, 0x1ac00
	s_mov_b32 m0, s7
	s_nop 0
	global_load_lds_dwordx4 v[16:17], off nt
	v_lshl_add_u64 v[16:17], v[16:17], 0, s[4:5]
	s_add_i32 s7, s6, 0x1b000
	s_mov_b32 m0, s7
	s_nop 0
	global_load_lds_dwordx4 v[16:17], off nt
	v_lshl_add_u64 v[14:15], v[2:3], 0, v[14:15]
	s_add_i32 s7, s6, 0x1b400
	s_mov_b32 m0, s7
	s_nop 0
	global_load_lds_dwordx4 v[14:15], off nt
	v_lshl_add_u64 v[14:15], v[14:15], 0, s[4:5]
	s_add_i32 s6, s6, 0x1b800
	s_mov_b32 m0, s6
	s_nop 0
	global_load_lds_dwordx4 v[14:15], off nt
	v_cmp_gt_u32_e32 vcc, 32, v148
	v_lshrrev_b32_e32 v5, 2, v148
	v_readlane_b32 s17, v254, 1
	v_readlane_b32 s18, v254, 2
	v_readlane_b32 s19, v254, 3
	v_readlane_b32 s20, v254, 4
	v_readlane_b32 s21, v254, 5
	s_and_saveexec_b64 s[4:5], vcc
	s_cbranch_execz .LBB0_703
	v_mov_b32_e32 v15, s11
	v_or_b32_e32 v14, s10, v5
	s_cmp_lg_u32 0, -1
	v_lshlrev_b64 v[14:15], 10, v[14:15]
	s_cselect_b32 s8, 0, 0
	v_lshl_add_u64 v[14:15], v[0:1], 0, v[14:15]
	s_add_i32 s6, s8, 0x1bc00
	s_mov_b32 m0, s6
	s_nop 0
	global_load_lds_dwordx4 v[14:15], off nt
	s_mov_b64 s[6:7], 0x2000
	v_lshl_add_u64 v[14:15], v[14:15], 0, s[6:7]
	s_add_i32 s8, s8, 0x1be00
	s_mov_b32 m0, s8
	s_nop 0
	global_load_lds_dwordx4 v[14:15], off nt
.LBB0_703:
	s_or_b64 exec, exec, s[4:5]
	v_cmp_gt_u32_e64 s[6:7], 16, v148
	s_lshl_b32 s8, s42, 4
	s_and_saveexec_b64 s[4:5], s[6:7]
	s_cbranch_execz .LBB0_705
	v_mov_b32_e32 v15, s11
	v_or_b32_e32 v14, s10, v148
	v_lshlrev_b64 v[14:15], 8, v[14:15]
	s_cmp_lg_u32 0, -1
	v_lshl_add_u64 v[14:15], s[52:53], 0, v[14:15]
	s_cselect_b32 s12, 0, 0
	v_lshl_add_u64 v[14:15], v[14:15], 0, s[8:9]
	s_add_i32 s12, s12, 0x1c400
	s_mov_b32 m0, s12
	s_nop 0
	global_load_lds_dwordx4 v[14:15], off nt
.LBB0_705:
	s_or_b64 exec, exec, s[4:5]
	s_or_b32 s12, s10, 16
	v_mov_b32_e32 v15, s11
	v_or_b32_e32 v14, s12, v7
	s_cmp_lg_u32 0, -1
	v_lshlrev_b64 v[14:15], 11, v[14:15]
	s_cselect_b32 s14, 0, 0
	v_lshl_add_u64 v[16:17], v[10:11], 0, v[14:15]
	s_add_i32 s4, s14, 0x1c500
	s_mov_b32 m0, s4
	s_nop 0
	global_load_lds_dwordx4 v[16:17], off nt
	s_mov_b64 s[4:5], 0x4000
	v_lshl_add_u64 v[16:17], v[16:17], 0, s[4:5]
	s_add_i32 s15, s14, 0x1c900
	s_mov_b32 s16, m0
	s_mov_b32 m0, s15
	s_nop 0
	global_load_lds_dwordx4 v[16:17], off nt
	s_mov_b32 m0, s16
	v_lshl_add_u64 v[16:17], v[12:13], 0, v[14:15]
	s_add_i32 s15, s14, 0x1cd00
	s_mov_b32 s16, m0
	s_mov_b32 m0, s15
	s_nop 0
	global_load_lds_dwordx4 v[16:17], off nt
	s_mov_b32 m0, s16
	v_lshl_add_u64 v[16:17], v[16:17], 0, s[4:5]
	s_add_i32 s15, s14, 0x1d100
	s_mov_b32 s16, m0
	s_mov_b32 m0, s15
	s_nop 0
	global_load_lds_dwordx4 v[16:17], off nt
	s_mov_b32 m0, s16
	v_lshl_add_u64 v[16:17], v[8:9], 0, v[14:15]
	s_add_i32 s15, s14, 0x1d500
	s_mov_b32 s16, m0
	s_mov_b32 m0, s15
	s_nop 0
	global_load_lds_dwordx4 v[16:17], off nt
	s_mov_b32 m0, s16
	v_lshl_add_u64 v[16:17], v[16:17], 0, s[4:5]
	s_add_i32 s15, s14, 0x1d900
	s_mov_b32 s16, m0
	s_mov_b32 m0, s15
	s_nop 0
	global_load_lds_dwordx4 v[16:17], off nt
	s_mov_b32 m0, s16
	v_lshl_add_u64 v[14:15], v[2:3], 0, v[14:15]
	s_add_i32 s15, s14, 0x1dd00
	s_mov_b32 s16, m0
	s_mov_b32 m0, s15
	s_nop 0
	global_load_lds_dwordx4 v[14:15], off nt
	s_mov_b32 m0, s16
	v_lshl_add_u64 v[14:15], v[14:15], 0, s[4:5]
	s_add_i32 s14, s14, 0x1e100
	s_mov_b32 m0, s14
	s_nop 0
	global_load_lds_dwordx4 v[14:15], off nt
	s_mov_b32 s13, s11
	s_and_saveexec_b64 s[4:5], vcc
	s_cbranch_execz .LBB0_707
	v_mov_b32_e32 v15, s13
	v_or_b32_e32 v14, s12, v5
	s_cmp_lg_u32 0, -1
	v_lshlrev_b64 v[14:15], 10, v[14:15]
	s_cselect_b32 s16, 0, 0
	v_lshl_add_u64 v[14:15], v[0:1], 0, v[14:15]
	s_add_i32 s14, s16, 0x1e500
	s_mov_b32 m0, s14
	s_nop 0
	global_load_lds_dwordx4 v[14:15], off nt
	s_mov_b64 s[14:15], 0x2000
	v_lshl_add_u64 v[14:15], v[14:15], 0, s[14:15]
	s_add_i32 s16, s16, 0x1e700
	s_mov_b32 m0, s16
	s_nop 0
	global_load_lds_dwordx4 v[14:15], off nt
.LBB0_707:
	s_or_b64 exec, exec, s[4:5]
	s_and_saveexec_b64 s[4:5], s[6:7]
	s_cbranch_execz .LBB0_709
	v_mov_b32_e32 v15, s13
	v_or_b32_e32 v14, s12, v148
	v_lshlrev_b64 v[14:15], 8, v[14:15]
	s_cmp_lg_u32 0, -1
	v_lshl_add_u64 v[14:15], s[52:53], 0, v[14:15]
	s_cselect_b32 s12, 0, 0
	v_lshl_add_u64 v[14:15], v[14:15], 0, s[8:9]
	s_add_i32 s12, s12, 0x1ed00
	s_mov_b32 m0, s12
	s_nop 0
	global_load_lds_dwordx4 v[14:15], off nt
.LBB0_709:
	s_or_b64 exec, exec, s[4:5]
	s_or_b32 s12, s10, 32
	v_mov_b32_e32 v15, s11
	v_or_b32_e32 v14, s12, v7
	s_cmp_lg_u32 0, -1
	v_lshlrev_b64 v[14:15], 11, v[14:15]
	s_cselect_b32 s14, 0, 0
	v_lshl_add_u64 v[16:17], v[10:11], 0, v[14:15]
	s_add_i32 s4, s14, 0x1ee00
	s_mov_b32 m0, s4
	s_nop 0
	global_load_lds_dwordx4 v[16:17], off nt
	s_mov_b64 s[4:5], 0x4000
	v_lshl_add_u64 v[16:17], v[16:17], 0, s[4:5]
	s_add_i32 s15, s14, 0x1f200
	s_mov_b32 s16, m0
	s_mov_b32 m0, s15
	s_nop 0
	global_load_lds_dwordx4 v[16:17], off nt
	s_mov_b32 m0, s16
	v_lshl_add_u64 v[16:17], v[12:13], 0, v[14:15]
	s_add_i32 s15, s14, 0x1f600
	s_mov_b32 s16, m0
	s_mov_b32 m0, s15
	s_nop 0
	global_load_lds_dwordx4 v[16:17], off nt
	s_mov_b32 m0, s16
	v_lshl_add_u64 v[16:17], v[16:17], 0, s[4:5]
	s_add_i32 s15, s14, 0x1fa00
	s_mov_b32 s16, m0
	s_mov_b32 m0, s15
	s_nop 0
	global_load_lds_dwordx4 v[16:17], off nt
	s_mov_b32 m0, s16
	v_lshl_add_u64 v[16:17], v[8:9], 0, v[14:15]
	s_add_i32 s15, s14, 0x1fe00
	s_mov_b32 s16, m0
	s_mov_b32 m0, s15
	s_nop 0
	global_load_lds_dwordx4 v[16:17], off nt
	s_mov_b32 m0, s16
	v_lshl_add_u64 v[16:17], v[16:17], 0, s[4:5]
	s_add_i32 s15, s14, 0x20200
	s_mov_b32 s16, m0
	s_mov_b32 m0, s15
	s_nop 0
	global_load_lds_dwordx4 v[16:17], off nt
	s_mov_b32 m0, s16
	v_lshl_add_u64 v[14:15], v[2:3], 0, v[14:15]
	s_add_i32 s15, s14, 0x20600
	s_mov_b32 s16, m0
	s_mov_b32 m0, s15
	s_nop 0
	global_load_lds_dwordx4 v[14:15], off nt
	s_mov_b32 m0, s16
	v_lshl_add_u64 v[14:15], v[14:15], 0, s[4:5]
	s_add_i32 s14, s14, 0x20a00
	s_mov_b32 m0, s14
	s_nop 0
	global_load_lds_dwordx4 v[14:15], off nt
	s_mov_b32 s13, s11
	s_and_saveexec_b64 s[4:5], vcc
	s_cbranch_execz .LBB0_711
	v_mov_b32_e32 v15, s13
	v_or_b32_e32 v14, s12, v5
	s_cmp_lg_u32 0, -1
	v_lshlrev_b64 v[14:15], 10, v[14:15]
	s_cselect_b32 s16, 0, 0
	v_lshl_add_u64 v[14:15], v[0:1], 0, v[14:15]
	s_add_i32 s14, s16, 0x20e00
	s_mov_b32 m0, s14
	s_nop 0
	global_load_lds_dwordx4 v[14:15], off nt
	s_mov_b64 s[14:15], 0x2000
	v_lshl_add_u64 v[14:15], v[14:15], 0, s[14:15]
	s_add_i32 s16, s16, 0x21000
	s_mov_b32 s14, m0
	s_mov_b32 m0, s16
	s_nop 0
	global_load_lds_dwordx4 v[14:15], off nt
	s_mov_b32 m0, s14
.LBB0_711:
	s_or_b64 exec, exec, s[4:5]
	s_and_saveexec_b64 s[4:5], s[6:7]
	s_cbranch_execz .LBB0_713
	v_mov_b32_e32 v15, s13
	v_or_b32_e32 v14, s12, v148
	v_lshlrev_b64 v[14:15], 8, v[14:15]
	s_cmp_lg_u32 0, -1
	v_lshl_add_u64 v[14:15], s[52:53], 0, v[14:15]
	s_cselect_b32 s12, 0, 0
	v_lshl_add_u64 v[14:15], v[14:15], 0, s[8:9]
	s_add_i32 s12, s12, 0x21600
	s_mov_b32 m0, s12
	s_nop 0
	global_load_lds_dwordx4 v[14:15], off nt
.LBB0_713:
	s_or_b64 exec, exec, s[4:5]
	s_or_b32 s10, s10, 48
	v_mov_b32_e32 v15, s11
	v_or_b32_e32 v14, s10, v7
	s_cmp_lg_u32 0, -1
	v_lshlrev_b64 v[14:15], 11, v[14:15]
	s_cselect_b32 s12, 0, 0
	v_lshl_add_u64 v[10:11], v[10:11], 0, v[14:15]
	s_add_i32 s4, s12, 0x21700
	s_mov_b32 m0, s4
	s_nop 0
	global_load_lds_dwordx4 v[10:11], off nt
	s_mov_b64 s[4:5], 0x4000
	v_lshl_add_u64 v[10:11], v[10:11], 0, s[4:5]
	s_add_i32 s13, s12, 0x21b00
	s_mov_b32 s14, m0
	s_mov_b32 m0, s13
	s_nop 0
	global_load_lds_dwordx4 v[10:11], off nt
	s_mov_b32 m0, s14
	v_lshl_add_u64 v[10:11], v[12:13], 0, v[14:15]
	s_add_i32 s13, s12, 0x21f00
	s_mov_b32 s14, m0
	s_mov_b32 m0, s13
	s_nop 0
	global_load_lds_dwordx4 v[10:11], off nt
	s_mov_b32 m0, s14
	v_lshl_add_u64 v[10:11], v[10:11], 0, s[4:5]
	s_add_i32 s13, s12, 0x22300
	s_mov_b32 s14, m0
	s_mov_b32 m0, s13
	s_nop 0
	global_load_lds_dwordx4 v[10:11], off nt
	s_mov_b32 m0, s14
	v_lshl_add_u64 v[8:9], v[8:9], 0, v[14:15]
	s_add_i32 s13, s12, 0x22700
	s_mov_b32 s14, m0
	s_mov_b32 m0, s13
	s_nop 0
	global_load_lds_dwordx4 v[8:9], off nt
	s_mov_b32 m0, s14
	v_lshl_add_u64 v[8:9], v[8:9], 0, s[4:5]
	s_add_i32 s13, s12, 0x22b00
	s_mov_b32 s14, m0
	s_mov_b32 m0, s13
	s_nop 0
	global_load_lds_dwordx4 v[8:9], off nt
	s_mov_b32 m0, s14
	v_lshl_add_u64 v[2:3], v[2:3], 0, v[14:15]
	s_add_i32 s13, s12, 0x22f00
	s_mov_b32 s14, m0
	s_mov_b32 m0, s13
	s_nop 0
	global_load_lds_dwordx4 v[2:3], off nt
	s_mov_b32 m0, s14
	v_lshl_add_u64 v[2:3], v[2:3], 0, s[4:5]
	s_add_i32 s12, s12, 0x23300
	s_mov_b32 m0, s12
	s_nop 0
	global_load_lds_dwordx4 v[2:3], off nt
	s_and_saveexec_b64 s[4:5], vcc
	s_cbranch_execz .LBB0_715
	v_mov_b32_e32 v3, s11
	v_or_b32_e32 v2, s10, v5
	s_cmp_lg_u32 0, -1
	v_lshlrev_b64 v[2:3], 10, v[2:3]
	s_cselect_b32 s14, 0, 0
	v_lshl_add_u64 v[0:1], v[0:1], 0, v[2:3]
	s_add_i32 s12, s14, 0x23700
	s_mov_b32 m0, s12
	s_nop 0
	global_load_lds_dwordx4 v[0:1], off nt
	s_mov_b64 s[12:13], 0x2000
	v_lshl_add_u64 v[0:1], v[0:1], 0, s[12:13]
	s_add_i32 s14, s14, 0x23900
	s_mov_b32 m0, s14
	s_nop 0
	global_load_lds_dwordx4 v[0:1], off nt
.LBB0_715:
	s_or_b64 exec, exec, s[4:5]
	s_and_saveexec_b64 s[4:5], s[6:7]
	s_cbranch_execz .LBB0_717
	v_mov_b32_e32 v1, s11
	v_or_b32_e32 v0, s10, v148
	v_lshlrev_b64 v[0:1], 8, v[0:1]
	s_cmp_lg_u32 0, -1
	v_lshl_add_u64 v[0:1], s[52:53], 0, v[0:1]
	s_cselect_b32 s6, 0, 0
	v_lshl_add_u64 v[0:1], v[0:1], 0, s[8:9]
	s_add_i32 s6, s6, 0x23f00
	s_mov_b32 m0, s6
	s_nop 0
	global_load_lds_dwordx4 v[0:1], off nt

.LBB0_826:
	s_add_i32 s36, s78, 0x19c00
	s_add_u32 s72, s64, s12
	s_addc_u32 s73, s65, s13
	s_add_u32 s76, s66, s12
	s_addc_u32 s77, s67, s13
	s_mov_b32 m0, s36
	s_add_u32 s74, s72, s14
	s_addc_u32 s75, s73, s15
	global_load_lds_dwordx4 v102, s[74:75] nt
	s_add_i32 m0, s36, 0x400
	s_add_u32 s74, s72, s16
	s_addc_u32 s75, s73, s17
	global_load_lds_dwordx4 v102, s[74:75] nt
	s_add_i32 m0, s36, 0x800
	s_add_u32 s74, s76, s18
	s_addc_u32 s75, s77, s19
	global_load_lds_dwordx4 v103, s[74:75] nt
	s_add_i32 m0, s36, 0xc00
	s_add_u32 s74, s76, s20
	s_addc_u32 s75, s77, s21
	global_load_lds_dwordx4 v103, s[74:75] nt
	s_add_i32 m0, s36, 0x1000
	s_add_u32 s74, s76, s22
	s_addc_u32 s75, s77, s23
	global_load_lds_dwordx4 v103, s[74:75] nt
	s_add_i32 m0, s36, 0x1400
	s_add_u32 s74, s76, s24
	s_addc_u32 s75, s77, s25
	global_load_lds_dwordx4 v103, s[74:75] nt
	s_add_i32 m0, s36, 0x1800
	s_add_u32 s74, s72, s26
	s_addc_u32 s75, s73, s27
	global_load_lds_dwordx4 v102, s[74:75] nt
	s_add_i32 m0, s36, 0x1c00
	s_add_u32 s74, s72, s28
	s_addc_u32 s75, s73, s29
	global_load_lds_dwordx4 v102, s[74:75] nt
	s_add_i32 s78, s78, 0x2900
	s_cmp_eq_u32 s78, 0xcd00
	s_cselect_b32 s78, 0, s78
	s_and_saveexec_b64 s[4:5], s[6:7]
	s_cbranch_execz .LBB0_828
	s_add_i32 m0, s36, 0x2000
	s_add_u32 s74, s68, s30
	s_addc_u32 s75, s69, s31
	global_load_lds_dwordx4 v104, s[68:69] nt
	s_add_i32 m0, s36, 0x2200
	s_nop 0
	global_load_lds_dwordx4 v104, s[74:75] nt
.LBB0_828:
	s_or_b64 exec, exec, s[4:5]
	s_and_saveexec_b64 s[4:5], s[8:9]
	s_cbranch_execz .LBB0_815
	s_add_i32 m0, s36, 0x2800
	s_add_u32 s74, s70, s0
	s_addc_u32 s75, s71, s1
	s_add_u32 s74, s74, s10
	s_addc_u32 s75, s75, s11
	global_load_lds_dwordx4 v105, s[74:75] nt
	s_branch .LBB0_815

.LBB0_1761:
	v_lshl_add_u64 v[8:9], s[92:93], 0, v[60:61]
	v_add_co_u32_e32 v2, vcc, 0xfa00000, v8
	v_lshl_add_u64 v[10:11], s[92:93], 0, v[66:67]
	v_lshl_add_u64 v[0:1], s[92:93], 0, v[62:63]
	v_addc_co_u32_e32 v3, vcc, 0, v9, vcc
	global_load_dwordx4 v[86:89], v[52:53], off
	global_load_dwordx4 v[80:83], v[0:1], off nt
	global_load_dwordx4 v[90:93], v[0:1], off offset:1024 nt
	v_add_co_u32_e32 v0, vcc, 0x1fc00000, v10
	global_load_dwordx4 v[94:97], v[2:3], off nt
	global_load_dwordx4 v[48:51], v[2:3], off offset:1024 nt
	v_addc_co_u32_e32 v1, vcc, 0, v11, vcc
	global_load_dwordx2 v[98:99], v[0:1], off nt
	global_load_dwordx2 v[100:101], v[0:1], off offset:512 nt
	v_add_co_u32_e32 v2, vcc, 0xfa80000, v8
	s_addk_i32 s0, 0xfc00
	s_nop 0
	v_addc_co_u32_e32 v3, vcc, 0, v9, vcc
	v_add_co_u32_e32 v0, vcc, 0x1fc40000, v10
	global_load_dwordx4 v[36:39], v[2:3], off nt
	global_load_dwordx4 v[32:35], v[2:3], off offset:1024 nt
	v_addc_co_u32_e32 v1, vcc, 0, v11, vcc
	v_add_co_u32_e32 v2, vcc, 0x17b80000, v8
	global_load_dwordx2 v[78:79], v[0:1], off nt
	global_load_dwordx2 v[76:77], v[0:1], off offset:512 nt
	v_addc_co_u32_e32 v3, vcc, 0, v9, vcc
	v_add_co_u32_e32 v0, vcc, 0xfb00000, v8
	global_load_dwordx4 v[44:47], v[2:3], off nt
	global_load_dwordx4 v[40:43], v[2:3], off offset:1024 nt
	v_addc_co_u32_e32 v1, vcc, 0, v9, vcc
	v_add_co_u32_e32 v2, vcc, 0x1fc80000, v10
	global_load_dwordx4 v[20:23], v[0:1], off nt
	global_load_dwordx4 v[16:19], v[0:1], off offset:1024 nt
	v_addc_co_u32_e32 v3, vcc, 0, v11, vcc
	v_add_co_u32_e32 v0, vcc, 0x17c00000, v8
	global_load_dwordx2 v[74:75], v[2:3], off nt
	global_load_dwordx2 v[72:73], v[2:3], off offset:512 nt
	v_addc_co_u32_e32 v1, vcc, 0, v9, vcc
	v_add_co_u32_e32 v12, vcc, 0xfb80000, v8
	global_load_dwordx4 v[28:31], v[0:1], off nt
	global_load_dwordx4 v[24:27], v[0:1], off offset:1024 nt
	v_addc_co_u32_e32 v13, vcc, 0, v9, vcc
	v_add_co_u32_e32 v10, vcc, 0x1fcc0000, v10
	global_load_dwordx4 v[4:7], v[12:13], off nt
	global_load_dwordx4 v[0:3], v[12:13], off offset:1024 nt
	v_addc_co_u32_e32 v11, vcc, 0, v11, vcc
	v_add_co_u32_e32 v102, vcc, 0x17c80000, v8
	global_load_dwordx2 v[70:71], v[10:11], off nt
	global_load_dwordx2 v[68:69], v[10:11], off offset:512 nt
	v_addc_co_u32_e32 v103, vcc, 0, v9, vcc
	global_load_dwordx4 v[12:15], v[102:103], off nt
	global_load_dwordx4 v[8:11], v[102:103], off offset:1024 nt
	v_lshl_add_u64 v[62:63], v[62:63], 0, s[4:5]
	v_lshl_add_u64 v[60:61], v[60:61], 0, s[4:5]
	v_lshl_add_u64 v[66:67], v[66:67], 0, s[8:9]
	s_cmp_lt_i32 s0, s73
	s_waitcnt vmcnt(23)
	v_lshlrev_b32_e32 v102, 16, v80
	v_and_b32_e32 v103, 0xffff0000, v80
	v_lshlrev_b32_e32 v80, 16, v81
	v_and_b32_e32 v81, 0xffff0000, v81
	v_lshlrev_b32_e32 v104, 16, v82
	v_and_b32_e32 v105, 0xffff0000, v82
	s_waitcnt vmcnt(19)
	v_cvt_f32_ubyte1_e32 v113, v98
	v_cvt_f32_ubyte0_e32 v112, v98
	v_cvt_f32_ubyte3_e32 v115, v98
	v_cvt_f32_ubyte2_e32 v114, v98
	v_cvt_f32_ubyte1_e32 v117, v99
	v_cvt_f32_ubyte0_e32 v116, v99
	v_cvt_f32_ubyte3_e32 v119, v99
	v_cvt_f32_ubyte2_e32 v118, v99
	v_lshlrev_b32_e32 v82, 16, v83
	v_and_b32_e32 v83, 0xffff0000, v83
	s_waitcnt vmcnt(18)
	v_cvt_f32_ubyte3_e32 v99, v100
	v_cvt_f32_ubyte2_e32 v98, v100
	v_cvt_f32_ubyte1_e32 v121, v100
	v_cvt_f32_ubyte0_e32 v120, v100
	v_cvt_f32_ubyte3_e32 v123, v101
	v_cvt_f32_ubyte2_e32 v122, v101
	v_cvt_f32_ubyte1_e32 v125, v101
	v_cvt_f32_ubyte0_e32 v124, v101
	v_pk_mul_f32 v[100:101], v[114:115], s[2:3] op_sel_hi:[1,0]
	v_pk_mul_f32 v[112:113], v[112:113], s[2:3] op_sel_hi:[1,0]
	v_pk_mul_f32 v[114:115], v[118:119], s[2:3] op_sel_hi:[1,0]
	v_pk_mul_f32 v[116:117], v[116:117], s[2:3] op_sel_hi:[1,0]
	v_lshlrev_b32_e32 v106, 16, v90
	v_and_b32_e32 v107, 0xffff0000, v90
	v_lshlrev_b32_e32 v90, 16, v91
	v_and_b32_e32 v91, 0xffff0000, v91
	v_lshlrev_b32_e32 v108, 16, v92
	v_and_b32_e32 v109, 0xffff0000, v92
	v_lshlrev_b32_e32 v92, 16, v93
	v_and_b32_e32 v93, 0xffff0000, v93
	v_pk_mul_f32 v[118:119], v[120:121], s[2:3] op_sel_hi:[1,0]
	v_pk_mul_f32 v[98:99], v[98:99], s[2:3] op_sel_hi:[1,0]
	v_pk_mul_f32 v[120:121], v[124:125], s[2:3] op_sel_hi:[1,0]
	v_pk_mul_f32 v[122:123], v[122:123], s[2:3] op_sel_hi:[1,0]
	v_pk_mul_f32 v[102:103], v[112:113], v[102:103]
	v_pk_mul_f32 v[100:101], v[100:101], v[80:81]
	v_pk_mul_f32 v[104:105], v[116:117], v[104:105]
	v_pk_mul_f32 v[112:113], v[114:115], v[82:83]
	v_pk_mul_f32 v[90:91], v[98:99], v[90:91]
	v_pk_mul_f32 v[98:99], v[118:119], v[106:107]
	v_pk_mul_f32 v[80:81], v[122:123], v[92:93]
	v_pk_mul_f32 v[82:83], v[120:121], v[108:109]
	v_pk_mul_f32 v[92:93], v[100:101], v[100:101]
	v_pk_mul_f32 v[106:107], v[102:103], v[102:103]
	v_pk_mul_f32 v[108:109], v[112:113], v[112:113]
	v_pk_mul_f32 v[114:115], v[104:105], v[104:105]
	v_pk_mov_b32 v[118:119], v[106:107], v[92:93] op_sel:[1,0]
	v_mov_b32_e32 v107, v93
	v_pk_mov_b32 v[92:93], v[114:115], v[108:109] op_sel:[1,0]
	v_mov_b32_e32 v115, v109
	v_mul_f32_e32 v84, v99, v99
	v_mul_f32_e32 v116, v91, v91
	v_pk_add_f32 v[106:107], v[118:119], v[106:107]
	v_pk_add_f32 v[92:93], v[92:93], v[114:115]
	v_mul_f32_e32 v120, v82, v82
	v_mul_f32_e32 v121, v83, v83
	v_mul_f32_e32 v122, v80, v80
	v_mul_f32_e32 v123, v81, v81
	v_pk_fma_f32 v[108:109], v[98:99], v[98:99], v[84:85] op_sel_hi:[1,1,0]
	v_pk_fma_f32 v[116:117], v[90:91], v[90:91], v[116:117] op_sel_hi:[1,1,0]
	v_pk_add_f32 v[106:107], v[106:107], v[106:107] op_sel:[0,1] op_sel_hi:[1,0]
	v_pk_add_f32 v[92:93], v[92:93], v[92:93] op_sel:[0,1] op_sel_hi:[1,0]
	v_mov_b32_e32 v109, v122
	v_mov_b32_e32 v117, v123
	v_mov_b32_e32 v107, v120
	v_mov_b32_e32 v93, v121
	v_pk_add_f32 v[108:109], v[108:109], v[116:117]
	v_pk_add_f32 v[92:93], v[106:107], v[92:93]
	v_lshlrev_b32_e32 v110, 16, v94
	v_pk_add_f32 v[92:93], v[92:93], v[108:109]
	v_and_b32_e32 v111, 0xffff0000, v94
	v_add_f32_e32 v84, v92, v93
	v_lshlrev_b32_e32 v94, 16, v95
	v_and_b32_e32 v95, 0xffff0000, v95
	v_add_f32_dpp v84, v84, v84 quad_perm:[1,0,3,2] row_mask:0xf bank_mask:0xf bound_ctrl:1
	s_waitcnt vmcnt(14)
	v_cvt_f32_ubyte1_e32 v107, v77
	v_cvt_f32_ubyte0_e32 v106, v77
	v_add_f32_dpp v84, v84, v84 quad_perm:[2,3,0,1] row_mask:0xf bank_mask:0xf bound_ctrl:1
	s_waitcnt vmcnt(13)
	v_lshlrev_b32_e32 v108, 16, v45
	v_and_b32_e32 v109, 0xffff0000, v45
	v_add_f32_dpp v84, v84, v84 row_half_mirror row_mask:0xf bank_mask:0xf bound_ctrl:1
	s_nop 1
	v_add_f32_dpp v84, v84, v84 row_mirror row_mask:0xf bank_mask:0xf bound_ctrl:1
	s_nop 0
	v_readlane_b32 s11, v84, 16
	v_readlane_b32 s14, v84, 48
	v_readlane_b32 s12, v84, 0
	v_readlane_b32 s13, v84, 32
	v_mov_b32_e32 v92, s11
	v_mov_b32_e32 v93, s14
	v_pk_add_f32 v[92:93], s[12:13], v[92:93]
	s_nop 0
	v_add_f32_e32 v84, v92, v93
	v_fmamk_f32 v84, v84, 0x3a800000, v85
	v_rsq_f32_e32 v84, v84
	s_nop 0
	v_pk_mul_f32 v[92:93], v[84:85], v[102:103] op_sel_hi:[0,1]
	v_pk_mul_f32 v[100:101], v[84:85], v[100:101] op_sel_hi:[0,1]
	v_pk_fma_f32 v[88:89], v[100:101], v[88:89], v[94:95]
	v_pk_fma_f32 v[86:87], v[92:93], v[86:87], v[110:111]
	global_store_dwordx4 v[64:65], v[86:89], off nt
	global_load_dwordx4 v[86:89], v[54:55], off
	v_lshlrev_b32_e32 v92, 16, v96
	v_and_b32_e32 v93, 0xffff0000, v96
	v_lshlrev_b32_e32 v94, 16, v97
	v_and_b32_e32 v95, 0xffff0000, v97
	v_pk_mul_f32 v[96:97], v[84:85], v[112:113] op_sel_hi:[0,1]
	v_pk_mul_f32 v[100:101], v[84:85], v[104:105] op_sel_hi:[0,1]
	v_pk_mul_f32 v[90:91], v[84:85], v[90:91] op_sel_hi:[0,1]
	v_cvt_f32_ubyte1_e32 v103, v76
	v_cvt_f32_ubyte0_e32 v102, v76
	v_cvt_f32_ubyte3_e32 v105, v77
	v_cvt_f32_ubyte2_e32 v104, v77
	v_lshlrev_b32_e32 v110, 16, v46
	v_and_b32_e32 v111, 0xffff0000, v46
	v_lshlrev_b32_e32 v112, 16, v47
	v_and_b32_e32 v113, 0xffff0000, v47
	v_pk_mul_f32 v[46:47], v[84:85], v[80:81] op_sel_hi:[0,1]
	s_waitcnt vmcnt(14)
	v_lshlrev_b32_e32 v80, 16, v40
	v_and_b32_e32 v81, 0xffff0000, v40
	v_lshlrev_b32_e32 v40, 16, v41
	v_and_b32_e32 v41, 0xffff0000, v41
	s_waitcnt vmcnt(0)
	v_pk_fma_f32 v[86:87], v[100:101], v[86:87], v[92:93]
	v_pk_fma_f32 v[88:89], v[96:97], v[88:89], v[94:95]
	global_store_dwordx4 v[64:65], v[86:89], off offset:16 nt
	global_load_dwordx4 v[86:89], v[56:57], off
	v_lshlrev_b32_e32 v92, 16, v48
	v_and_b32_e32 v93, 0xffff0000, v48
	v_lshlrev_b32_e32 v48, 16, v49
	v_and_b32_e32 v49, 0xffff0000, v49
	v_pk_mul_f32 v[94:95], v[84:85], v[98:99] op_sel_hi:[0,1]
	v_cvt_f32_ubyte3_e32 v97, v78
	v_cvt_f32_ubyte2_e32 v96, v78
	v_cvt_f32_ubyte1_e32 v99, v79
	v_cvt_f32_ubyte0_e32 v98, v79
	v_cvt_f32_ubyte3_e32 v101, v79
	v_cvt_f32_ubyte2_e32 v100, v79
	v_cvt_f32_ubyte3_e32 v79, v76
	v_pk_mul_f32 v[100:101], v[100:101], s[2:3] op_sel_hi:[1,0]
	v_pk_mul_f32 v[98:99], v[98:99], s[2:3] op_sel_hi:[1,0]
	s_waitcnt vmcnt(0)
	v_pk_fma_f32 v[86:87], v[94:95], v[86:87], v[92:93]
	v_pk_fma_f32 v[88:89], v[90:91], v[88:89], v[48:49]
	global_store_dwordx4 v[64:65], v[86:89], off offset:2048 nt
	global_load_dwordx4 v[86:89], v[58:59], off
	v_lshlrev_b32_e32 v90, 16, v50
	v_and_b32_e32 v91, 0xffff0000, v50
	v_lshlrev_b32_e32 v50, 16, v51
	v_and_b32_e32 v51, 0xffff0000, v51
	v_lshlrev_b32_e32 v92, 16, v36
	v_and_b32_e32 v93, 0xffff0000, v36
	v_lshlrev_b32_e32 v94, 16, v37
	v_and_b32_e32 v95, 0xffff0000, v37
	v_cvt_f32_ubyte1_e32 v37, v78
	v_cvt_f32_ubyte0_e32 v36, v78
	v_cvt_f32_ubyte2_e32 v78, v76
	v_pk_mul_f32 v[76:77], v[96:97], s[2:3] op_sel_hi:[1,0]
	v_lshlrev_b32_e32 v96, 16, v44
	v_and_b32_e32 v97, 0xffff0000, v44
	v_pk_mul_f32 v[44:45], v[84:85], v[82:83] op_sel_hi:[0,1]
	v_pk_mul_f32 v[36:37], v[36:37], s[2:3] op_sel_hi:[1,0]
	v_pk_mul_f32 v[78:79], v[78:79], s[2:3] op_sel_hi:[1,0]
	v_pk_mul_f32 v[82:83], v[106:107], s[2:3] op_sel_hi:[1,0]
	v_pk_mul_f32 v[76:77], v[76:77], v[108:109]
	v_pk_mul_f32 v[78:79], v[78:79], v[40:41]
	v_add_co_u32_e32 v48, vcc, s1, v64
	s_waitcnt vmcnt(0)
	v_pk_fma_f32 v[44:45], v[44:45], v[86:87], v[90:91]
	v_pk_fma_f32 v[46:47], v[46:47], v[88:89], v[50:51]
	global_store_dwordx4 v[64:65], v[44:47], off offset:2064 nt
	global_load_dwordx4 v[44:47], v[52:53], off
	v_pk_mul_f32 v[50:51], v[102:103], s[2:3] op_sel_hi:[1,0]
	v_pk_mul_f32 v[86:87], v[104:105], s[2:3] op_sel_hi:[1,0]
	v_lshlrev_b32_e32 v88, 16, v42
	v_and_b32_e32 v89, 0xffff0000, v42
	v_lshlrev_b32_e32 v42, 16, v43
	v_and_b32_e32 v43, 0xffff0000, v43
	v_pk_mul_f32 v[90:91], v[36:37], v[96:97]
	v_pk_mul_f32 v[96:97], v[98:99], v[110:111]
	v_pk_mul_f32 v[98:99], v[100:101], v[112:113]
	v_pk_mul_f32 v[50:51], v[50:51], v[80:81]
	v_pk_mul_f32 v[36:37], v[86:87], v[42:43]
	v_pk_mul_f32 v[40:41], v[82:83], v[88:89]
	v_pk_mul_f32 v[42:43], v[76:77], v[76:77]
	v_pk_mul_f32 v[80:81], v[90:91], v[90:91]
	v_pk_mul_f32 v[82:83], v[98:99], v[98:99]
	v_pk_mul_f32 v[86:87], v[96:97], v[96:97]
	v_pk_mov_b32 v[100:101], v[80:81], v[42:43] op_sel:[1,0]
	v_mov_b32_e32 v81, v43
	v_pk_mov_b32 v[42:43], v[86:87], v[82:83] op_sel:[1,0]
	v_mov_b32_e32 v87, v83
	v_mul_f32_e32 v84, v51, v51
	v_mul_f32_e32 v88, v79, v79
	v_pk_add_f32 v[80:81], v[100:101], v[80:81]
	v_pk_add_f32 v[42:43], v[42:43], v[86:87]
	v_mul_f32_e32 v102, v40, v40
	v_mul_f32_e32 v103, v41, v41
	v_mul_f32_e32 v104, v36, v36
	v_mul_f32_e32 v105, v37, v37
	v_pk_fma_f32 v[82:83], v[50:51], v[50:51], v[84:85] op_sel_hi:[1,1,0]
	v_pk_fma_f32 v[88:89], v[78:79], v[78:79], v[88:89] op_sel_hi:[1,1,0]
	v_pk_add_f32 v[80:81], v[80:81], v[80:81] op_sel:[0,1] op_sel_hi:[1,0]
	v_pk_add_f32 v[42:43], v[42:43], v[42:43] op_sel:[0,1] op_sel_hi:[1,0]
	v_mov_b32_e32 v83, v104
	v_mov_b32_e32 v89, v105
	v_mov_b32_e32 v81, v102
	v_mov_b32_e32 v43, v103
	v_pk_add_f32 v[82:83], v[82:83], v[88:89]
	v_pk_add_f32 v[42:43], v[80:81], v[42:43]
	v_addc_co_u32_e32 v49, vcc, 0, v65, vcc
	v_pk_add_f32 v[42:43], v[42:43], v[82:83]
	v_cvt_f32_ubyte1_e32 v87, v72
	v_add_f32_e32 v42, v42, v43
	v_cvt_f32_ubyte0_e32 v86, v72
	v_cvt_f32_ubyte3_e32 v89, v73
	v_add_f32_dpp v42, v42, v42 quad_perm:[1,0,3,2] row_mask:0xf bank_mask:0xf bound_ctrl:1
	v_cvt_f32_ubyte2_e32 v88, v73
	s_nop 0
	v_add_f32_dpp v42, v42, v42 quad_perm:[2,3,0,1] row_mask:0xf bank_mask:0xf bound_ctrl:1
	s_nop 1
	v_add_f32_dpp v42, v42, v42 row_half_mirror row_mask:0xf bank_mask:0xf bound_ctrl:1
	s_nop 1
	v_add_f32_dpp v42, v42, v42 row_mirror row_mask:0xf bank_mask:0xf bound_ctrl:1
	s_nop 0
	v_readlane_b32 s11, v42, 16
	v_readlane_b32 s14, v42, 48
	v_readlane_b32 s12, v42, 0
	v_readlane_b32 s13, v42, 32
	v_mov_b32_e32 v42, s11
	v_mov_b32_e32 v43, s14
	v_pk_add_f32 v[42:43], s[12:13], v[42:43]
	s_nop 0
	v_add_f32_e32 v42, v42, v43
	v_fmamk_f32 v42, v42, 0x3a800000, v85
	v_rsq_f32_e32 v42, v42
	s_nop 0
	v_pk_mul_f32 v[76:77], v[42:43], v[76:77] op_sel_hi:[0,1]
	v_pk_mul_f32 v[80:81], v[42:43], v[90:91] op_sel_hi:[0,1]
	v_pk_mul_f32 v[82:83], v[42:43], v[96:97] op_sel_hi:[0,1]
	v_pk_mul_f32 v[50:51], v[42:43], v[50:51] op_sel_hi:[0,1]
	v_cvt_f32_ubyte1_e32 v91, v73
	v_cvt_f32_ubyte0_e32 v90, v73
	v_pk_mul_f32 v[36:37], v[42:43], v[36:37] op_sel_hi:[0,1]
	s_waitcnt vmcnt(0)
	v_pk_fma_f32 v[44:45], v[80:81], v[44:45], v[92:93]
	v_pk_fma_f32 v[46:47], v[76:77], v[46:47], v[94:95]
	global_store_dwordx4 v[48:49], v[44:47], off nt
	global_load_dwordx4 v[44:47], v[54:55], off
	v_lshlrev_b32_e32 v76, 16, v38
	v_and_b32_e32 v77, 0xffff0000, v38
	v_lshlrev_b32_e32 v38, 16, v39
	v_and_b32_e32 v39, 0xffff0000, v39
	v_pk_mul_f32 v[80:81], v[42:43], v[98:99] op_sel_hi:[0,1]
	v_lshlrev_b32_e32 v92, 16, v28
	v_and_b32_e32 v93, 0xffff0000, v28
	v_lshlrev_b32_e32 v28, 16, v29
	v_and_b32_e32 v29, 0xffff0000, v29
	s_waitcnt vmcnt(0)
	v_pk_fma_f32 v[44:45], v[82:83], v[44:45], v[76:77]
	v_pk_fma_f32 v[46:47], v[80:81], v[46:47], v[38:39]
	global_store_dwordx4 v[48:49], v[44:47], off offset:16 nt
	global_load_dwordx4 v[44:47], v[56:57], off
	v_lshlrev_b32_e32 v38, 16, v32
	v_and_b32_e32 v39, 0xffff0000, v32
	v_lshlrev_b32_e32 v32, 16, v33
	v_and_b32_e32 v33, 0xffff0000, v33
	v_pk_mul_f32 v[76:77], v[42:43], v[78:79] op_sel_hi:[0,1]
	v_lshlrev_b32_e32 v78, 16, v21
	v_and_b32_e32 v79, 0xffff0000, v21
	v_cvt_f32_ubyte1_e32 v21, v74
	v_cvt_f32_ubyte1_e32 v81, v75
	v_cvt_f32_ubyte0_e32 v80, v75
	v_cvt_f32_ubyte3_e32 v83, v75
	v_cvt_f32_ubyte2_e32 v82, v75
	v_cvt_f32_ubyte3_e32 v75, v72
	v_pk_mul_f32 v[82:83], v[82:83], s[2:3] op_sel_hi:[1,0]
	v_pk_mul_f32 v[80:81], v[80:81], s[2:3] op_sel_hi:[1,0]
	s_waitcnt vmcnt(0)
	v_pk_fma_f32 v[44:45], v[50:51], v[44:45], v[38:39]
	v_pk_fma_f32 v[46:47], v[76:77], v[46:47], v[32:33]
	global_store_dwordx4 v[48:49], v[44:47], off offset:2048 nt
	global_load_dwordx4 v[44:47], v[58:59], off
	v_lshlrev_b32_e32 v38, 16, v34
	v_and_b32_e32 v39, 0xffff0000, v34
	v_lshlrev_b32_e32 v50, 16, v35
	v_and_b32_e32 v51, 0xffff0000, v35
	v_cvt_f32_ubyte3_e32 v35, v74
	v_cvt_f32_ubyte2_e32 v34, v74
	v_lshlrev_b32_e32 v76, 16, v20
	v_and_b32_e32 v77, 0xffff0000, v20
	v_cvt_f32_ubyte0_e32 v20, v74
	v_cvt_f32_ubyte2_e32 v74, v72
	v_pk_mul_f32 v[72:73], v[34:35], s[2:3] op_sel_hi:[1,0]
	v_pk_mul_f32 v[34:35], v[42:43], v[40:41] op_sel_hi:[0,1]
	v_pk_mul_f32 v[20:21], v[20:21], s[2:3] op_sel_hi:[1,0]
	v_pk_mul_f32 v[40:41], v[86:87], s[2:3] op_sel_hi:[1,0]
	v_pk_mul_f32 v[42:43], v[74:75], s[2:3] op_sel_hi:[1,0]
	v_pk_mul_f32 v[74:75], v[20:21], v[92:93]
	v_pk_mul_f32 v[28:29], v[72:73], v[28:29]
	v_add_co_u32_e32 v32, vcc, s3, v64
	s_waitcnt vmcnt(0)
	v_pk_fma_f32 v[34:35], v[34:35], v[44:45], v[38:39]
	v_pk_fma_f32 v[36:37], v[36:37], v[46:47], v[50:51]
	global_store_dwordx4 v[48:49], v[34:37], off offset:2064 nt
	global_load_dwordx4 v[34:37], v[52:53], off
	v_lshlrev_b32_e32 v38, 16, v30
	v_and_b32_e32 v39, 0xffff0000, v30
	v_lshlrev_b32_e32 v30, 16, v31
	v_and_b32_e32 v31, 0xffff0000, v31
	v_lshlrev_b32_e32 v44, 16, v24
	v_and_b32_e32 v45, 0xffff0000, v24
	v_lshlrev_b32_e32 v24, 16, v25
	v_and_b32_e32 v25, 0xffff0000, v25
	v_pk_mul_f32 v[46:47], v[90:91], s[2:3] op_sel_hi:[1,0]
	v_pk_mul_f32 v[48:49], v[88:89], s[2:3] op_sel_hi:[1,0]
	v_lshlrev_b32_e32 v50, 16, v26
	v_and_b32_e32 v51, 0xffff0000, v26
	v_lshlrev_b32_e32 v26, 16, v27
	v_and_b32_e32 v27, 0xffff0000, v27
	v_pk_mul_f32 v[38:39], v[80:81], v[38:39]
	v_pk_mul_f32 v[72:73], v[82:83], v[30:31]
	v_pk_mul_f32 v[42:43], v[42:43], v[24:25]
	v_pk_mul_f32 v[40:41], v[40:41], v[44:45]
	v_pk_mul_f32 v[20:21], v[48:49], v[26:27]
	v_pk_mul_f32 v[24:25], v[46:47], v[50:51]
	v_pk_mul_f32 v[26:27], v[28:29], v[28:29]
	v_pk_mul_f32 v[30:31], v[74:75], v[74:75]
	v_pk_mul_f32 v[44:45], v[72:73], v[72:73]
	v_pk_mul_f32 v[46:47], v[38:39], v[38:39]
	v_pk_mov_b32 v[80:81], v[30:31], v[26:27] op_sel:[1,0]
	v_mov_b32_e32 v31, v27
	v_pk_mov_b32 v[26:27], v[46:47], v[44:45] op_sel:[1,0]
	v_mov_b32_e32 v47, v45
	v_mul_f32_e32 v51, v24, v24
	v_mul_f32_e32 v48, v41, v41
	v_mul_f32_e32 v50, v43, v43
	v_pk_add_f32 v[30:31], v[80:81], v[30:31]
	v_pk_add_f32 v[26:27], v[26:27], v[46:47]
	v_mul_f32_e32 v82, v25, v25
	v_mul_f32_e32 v83, v20, v20
	v_mul_f32_e32 v84, v21, v21
	v_pk_fma_f32 v[44:45], v[40:41], v[40:41], v[48:49] op_sel_hi:[1,1,0]
	v_pk_fma_f32 v[48:49], v[42:43], v[42:43], v[50:51] op_sel_hi:[1,1,0]
	v_pk_add_f32 v[30:31], v[30:31], v[30:31] op_sel:[0,1] op_sel_hi:[1,0]
	v_pk_add_f32 v[26:27], v[26:27], v[26:27] op_sel:[0,1] op_sel_hi:[1,0]
	v_mov_b32_e32 v45, v83
	v_mov_b32_e32 v49, v84
	v_mov_b32_e32 v31, v51
	v_mov_b32_e32 v27, v82
	v_pk_add_f32 v[44:45], v[44:45], v[48:49]
	v_pk_add_f32 v[26:27], v[30:31], v[26:27]
	v_addc_co_u32_e32 v33, vcc, 0, v65, vcc
	v_pk_add_f32 v[26:27], v[26:27], v[44:45]
	v_cvt_f32_ubyte3_e32 v45, v68
	v_add_f32_e32 v26, v26, v27
	v_cvt_f32_ubyte2_e32 v44, v68
	v_cvt_f32_ubyte1_e32 v47, v68
	v_add_f32_dpp v26, v26, v26 quad_perm:[1,0,3,2] row_mask:0xf bank_mask:0xf bound_ctrl:1
	v_cvt_f32_ubyte0_e32 v46, v68
	v_cvt_f32_ubyte3_e32 v49, v69
	v_add_f32_dpp v26, v26, v26 quad_perm:[2,3,0,1] row_mask:0xf bank_mask:0xf bound_ctrl:1
	v_cvt_f32_ubyte2_e32 v48, v69
	v_cvt_f32_ubyte1_e32 v51, v69
	v_add_f32_dpp v26, v26, v26 row_half_mirror row_mask:0xf bank_mask:0xf bound_ctrl:1
	v_cvt_f32_ubyte0_e32 v50, v69
	v_lshlrev_b32_e32 v68, 16, v12
	v_add_f32_dpp v26, v26, v26 row_mirror row_mask:0xf bank_mask:0xf bound_ctrl:1
	v_and_b32_e32 v69, 0xffff0000, v12
	v_readlane_b32 s11, v26, 16
	v_readlane_b32 s14, v26, 48
	v_readlane_b32 s12, v26, 0
	v_readlane_b32 s13, v26, 32
	v_mov_b32_e32 v26, s11
	v_mov_b32_e32 v27, s14
	v_pk_add_f32 v[26:27], s[12:13], v[26:27]
	v_lshlrev_b32_e32 v12, 16, v13
	v_add_f32_e32 v26, v26, v27
	v_fmamk_f32 v26, v26, 0x3a800000, v85
	v_rsq_f32_e32 v26, v26
	v_and_b32_e32 v13, 0xffff0000, v13
	v_pk_mul_f32 v[30:31], v[26:27], v[28:29] op_sel_hi:[0,1]
	v_pk_mul_f32 v[28:29], v[26:27], v[74:75] op_sel_hi:[0,1]
	s_waitcnt vmcnt(0)
	v_pk_fma_f32 v[28:29], v[28:29], v[34:35], v[76:77]
	v_pk_fma_f32 v[30:31], v[30:31], v[36:37], v[78:79]
	global_store_dwordx4 v[32:33], v[28:31], off nt
	global_load_dwordx4 v[28:31], v[54:55], off
	v_lshlrev_b32_e32 v34, 16, v22
	v_and_b32_e32 v35, 0xffff0000, v22
	v_lshlrev_b32_e32 v22, 16, v23
	v_and_b32_e32 v23, 0xffff0000, v23
	v_pk_mul_f32 v[36:37], v[26:27], v[72:73] op_sel_hi:[0,1]
	v_pk_mul_f32 v[38:39], v[26:27], v[38:39] op_sel_hi:[0,1]
	v_pk_mul_f32 v[20:21], v[26:27], v[20:21] op_sel_hi:[0,1]
	v_pk_mul_f32 v[24:25], v[26:27], v[24:25] op_sel_hi:[0,1]
	s_waitcnt vmcnt(0)
	v_pk_fma_f32 v[28:29], v[38:39], v[28:29], v[34:35]
	v_pk_fma_f32 v[30:31], v[36:37], v[30:31], v[22:23]
	global_store_dwordx4 v[32:33], v[28:31], off offset:16 nt
	global_load_dwordx4 v[28:31], v[56:57], off
	v_lshlrev_b32_e32 v22, 16, v16
	v_and_b32_e32 v23, 0xffff0000, v16
	v_lshlrev_b32_e32 v16, 16, v17
	v_and_b32_e32 v17, 0xffff0000, v17
	v_pk_mul_f32 v[34:35], v[26:27], v[42:43] op_sel_hi:[0,1]
	v_pk_mul_f32 v[36:37], v[26:27], v[40:41] op_sel_hi:[0,1]
	v_cvt_f32_ubyte3_e32 v39, v70
	v_cvt_f32_ubyte2_e32 v38, v70
	v_cvt_f32_ubyte1_e32 v41, v71
	v_cvt_f32_ubyte0_e32 v40, v71
	v_cvt_f32_ubyte3_e32 v43, v71
	v_cvt_f32_ubyte2_e32 v42, v71
	v_pk_mul_f32 v[38:39], v[38:39], s[2:3] op_sel_hi:[1,0]
	v_lshlrev_b32_e32 v26, 16, v14
	v_and_b32_e32 v27, 0xffff0000, v14
	v_lshlrev_b32_e32 v14, 16, v15
	v_and_b32_e32 v15, 0xffff0000, v15
	v_pk_mul_f32 v[12:13], v[38:39], v[12:13]
	s_waitcnt vmcnt(0)
	v_pk_fma_f32 v[28:29], v[36:37], v[28:29], v[22:23]
	v_pk_fma_f32 v[30:31], v[34:35], v[30:31], v[16:17]
	global_store_dwordx4 v[32:33], v[28:31], off offset:2048 nt
	global_load_dwordx4 v[28:31], v[58:59], off
	v_lshlrev_b32_e32 v16, 16, v18
	v_and_b32_e32 v17, 0xffff0000, v18
	v_lshlrev_b32_e32 v18, 16, v19
	v_and_b32_e32 v19, 0xffff0000, v19
	v_cvt_f32_ubyte1_e32 v37, v70
	v_cvt_f32_ubyte0_e32 v36, v70
	v_pk_mul_f32 v[36:37], v[36:37], s[2:3] op_sel_hi:[1,0]
	v_add_co_u32_e32 v22, vcc, s10, v64
	v_pk_mul_f32 v[36:37], v[36:37], v[68:69]
	v_lshlrev_b32_e32 v34, 16, v4
	v_and_b32_e32 v35, 0xffff0000, v4
	v_lshlrev_b32_e32 v4, 16, v5
	v_and_b32_e32 v5, 0xffff0000, v5
	v_addc_co_u32_e32 v23, vcc, 0, v65, vcc
	v_lshl_add_u64 v[64:65], v[64:65], 0, s[6:7]
	s_waitcnt vmcnt(0)
	v_pk_fma_f32 v[16:17], v[24:25], v[28:29], v[16:17]
	v_pk_fma_f32 v[18:19], v[20:21], v[30:31], v[18:19]
	global_store_dwordx4 v[32:33], v[16:19], off offset:2064 nt
	global_load_dwordx4 v[16:19], v[52:53], off
	v_pk_mul_f32 v[20:21], v[42:43], s[2:3] op_sel_hi:[1,0]
	v_pk_mul_f32 v[24:25], v[40:41], s[2:3] op_sel_hi:[1,0]
	v_pk_mul_f32 v[28:29], v[46:47], s[2:3] op_sel_hi:[1,0]
	v_pk_mul_f32 v[30:31], v[44:45], s[2:3] op_sel_hi:[1,0]
	v_lshlrev_b32_e32 v32, 16, v8
	v_and_b32_e32 v33, 0xffff0000, v8
	v_lshlrev_b32_e32 v8, 16, v9
	v_and_b32_e32 v9, 0xffff0000, v9
	v_pk_mul_f32 v[42:43], v[48:49], s[2:3] op_sel_hi:[1,0]
	v_lshlrev_b32_e32 v44, 16, v10
	v_and_b32_e32 v45, 0xffff0000, v10
	v_lshlrev_b32_e32 v10, 16, v11
	v_and_b32_e32 v11, 0xffff0000, v11
	v_pk_mul_f32 v[24:25], v[24:25], v[26:27]
	v_pk_mul_f32 v[14:15], v[20:21], v[14:15]
	v_pk_mul_f32 v[40:41], v[50:51], s[2:3] op_sel_hi:[1,0]
	v_pk_mul_f32 v[20:21], v[30:31], v[8:9]
	v_pk_mul_f32 v[26:27], v[28:29], v[32:33]
	v_pk_mul_f32 v[28:29], v[42:43], v[10:11]
	v_pk_mul_f32 v[8:9], v[12:13], v[12:13]
	v_pk_mul_f32 v[10:11], v[36:37], v[36:37]
	v_pk_mul_f32 v[32:33], v[14:15], v[14:15]
	v_pk_mul_f32 v[38:39], v[24:25], v[24:25]
	v_pk_mul_f32 v[30:31], v[40:41], v[44:45]
	v_pk_mov_b32 v[44:45], v[10:11], v[8:9] op_sel:[1,0]
	v_mov_b32_e32 v11, v9
	v_pk_mov_b32 v[8:9], v[38:39], v[32:33] op_sel:[1,0]
	v_mov_b32_e32 v39, v33
	v_mul_f32_e32 v43, v30, v30
	v_mul_f32_e32 v40, v27, v27
	v_mul_f32_e32 v42, v21, v21
	v_pk_add_f32 v[10:11], v[44:45], v[10:11]
	v_pk_add_f32 v[8:9], v[8:9], v[38:39]
	v_mul_f32_e32 v46, v31, v31
	v_mul_f32_e32 v47, v28, v28
	v_mul_f32_e32 v48, v29, v29
	v_pk_fma_f32 v[32:33], v[26:27], v[26:27], v[40:41] op_sel_hi:[1,1,0]
	v_pk_fma_f32 v[40:41], v[20:21], v[20:21], v[42:43] op_sel_hi:[1,1,0]
	v_pk_add_f32 v[10:11], v[10:11], v[10:11] op_sel:[0,1] op_sel_hi:[1,0]
	v_pk_add_f32 v[8:9], v[8:9], v[8:9] op_sel:[0,1] op_sel_hi:[1,0]
	v_mov_b32_e32 v33, v47
	v_mov_b32_e32 v41, v48
	v_mov_b32_e32 v11, v43
	v_mov_b32_e32 v9, v46
	v_pk_add_f32 v[32:33], v[32:33], v[40:41]
	v_pk_add_f32 v[8:9], v[10:11], v[8:9]
	s_nop 0
	v_pk_add_f32 v[8:9], v[8:9], v[32:33]
	s_nop 0
	v_add_f32_e32 v8, v8, v9
	s_nop 1
	v_add_f32_dpp v8, v8, v8 quad_perm:[1,0,3,2] row_mask:0xf bank_mask:0xf bound_ctrl:1
	s_nop 1
	v_add_f32_dpp v8, v8, v8 quad_perm:[2,3,0,1] row_mask:0xf bank_mask:0xf bound_ctrl:1
	s_nop 1
	v_add_f32_dpp v8, v8, v8 row_half_mirror row_mask:0xf bank_mask:0xf bound_ctrl:1
	s_nop 1
	v_add_f32_dpp v8, v8, v8 row_mirror row_mask:0xf bank_mask:0xf bound_ctrl:1
	s_nop 0
	v_readlane_b32 s11, v8, 16
	v_readlane_b32 s14, v8, 48
	v_readlane_b32 s12, v8, 0
	v_readlane_b32 s13, v8, 32
	v_mov_b32_e32 v8, s11
	v_mov_b32_e32 v9, s14
	v_pk_add_f32 v[8:9], s[12:13], v[8:9]
	s_nop 0
	v_add_f32_e32 v8, v8, v9
	v_fmamk_f32 v8, v8, 0x3a800000, v85
	v_rsq_f32_e32 v32, v8
	s_nop 0
	v_pk_mul_f32 v[10:11], v[32:33], v[12:13] op_sel_hi:[0,1]
	v_pk_mul_f32 v[8:9], v[32:33], v[36:37] op_sel_hi:[0,1]
	s_waitcnt vmcnt(0)
	v_pk_fma_f32 v[8:9], v[8:9], v[16:17], v[34:35]
	v_pk_fma_f32 v[10:11], v[10:11], v[18:19], v[4:5]
	global_store_dwordx4 v[22:23], v[8:11], off nt
	global_load_dwordx4 v[8:11], v[54:55], off
	v_lshlrev_b32_e32 v4, 16, v6
	v_and_b32_e32 v5, 0xffff0000, v6
	v_lshlrev_b32_e32 v6, 16, v7
	v_and_b32_e32 v7, 0xffff0000, v7
	v_pk_mul_f32 v[12:13], v[32:33], v[14:15] op_sel_hi:[0,1]
	v_pk_mul_f32 v[14:15], v[32:33], v[24:25] op_sel_hi:[0,1]
	s_waitcnt vmcnt(0)
	v_pk_fma_f32 v[4:5], v[14:15], v[8:9], v[4:5]
	v_pk_fma_f32 v[6:7], v[12:13], v[10:11], v[6:7]
	global_store_dwordx4 v[22:23], v[4:7], off offset:16 nt
	global_load_dwordx4 v[4:7], v[56:57], off
	v_lshlrev_b32_e32 v8, 16, v0
	v_and_b32_e32 v9, 0xffff0000, v0
	v_lshlrev_b32_e32 v0, 16, v1
	v_and_b32_e32 v1, 0xffff0000, v1
	v_pk_mul_f32 v[10:11], v[32:33], v[20:21] op_sel_hi:[0,1]
	v_pk_mul_f32 v[12:13], v[32:33], v[26:27] op_sel_hi:[0,1]
	s_waitcnt vmcnt(0)
	v_pk_fma_f32 v[4:5], v[12:13], v[4:5], v[8:9]
	v_pk_fma_f32 v[6:7], v[10:11], v[6:7], v[0:1]
	global_store_dwordx4 v[22:23], v[4:7], off offset:2048 nt
	global_load_dwordx4 v[4:7], v[58:59], off
	v_lshlrev_b32_e32 v0, 16, v2
	v_and_b32_e32 v1, 0xffff0000, v2
	v_lshlrev_b32_e32 v2, 16, v3
	v_and_b32_e32 v3, 0xffff0000, v3
	v_pk_mul_f32 v[8:9], v[32:33], v[28:29] op_sel_hi:[0,1]
	v_pk_mul_f32 v[10:11], v[32:33], v[30:31] op_sel_hi:[0,1]
	s_waitcnt vmcnt(0)
	v_pk_fma_f32 v[0:1], v[10:11], v[4:5], v[0:1]
	v_pk_fma_f32 v[2:3], v[8:9], v[6:7], v[2:3]
	global_store_dwordx4 v[22:23], v[0:3], off offset:2064 nt
	s_cbranch_scc0 .LBB0_1761
